# GEMM K loops: lgkmcnt(8) wait before the ping-pong barrier in phases 1/5 dropped (reads are waited after the barrier)
# speedup vs baseline: 1.0093x; 1.0093x over previous
; #define PG8_STAGE(bufoff, gbase, voff) do { _Pragma("unroll") for (int _i = 0; _i < 2; ++_i) \
;     __builtin_amdgcn_global_load_lds((const unsigned*)((const char*)(gbase) + (voff)[_i]), (LAS unsigned*)(lds + (bufoff) + ldsw + _i * 8192), 16, 0, 0); } while (0)
; #define PG8_LDA(dst, b, h) do { _Pragma("unroll") for (int m = 0; m < 4; ++m) _Pragma("unroll") for (int k = 0; k < 2; ++k) dst[m][k] = *(const LAS bf16x8*)(lds + PG8_SA(b, h) + aoff + m * 2048 + k * 1024); } while (0)
; #define PG8_LDB(dst, b, h) do { _Pragma("unroll") for (int n = 0; n < 2; ++n) _Pragma("unroll") for (int k = 0; k < 2; ++k) dst[n][k] = *(const LAS bf16x8*)(lds + PG8_SB(b, h) + boff + n * 2048 + k * 1024); } while (0)
; #define PG8_MMA(ai, bj, At, Bt) do { __builtin_amdgcn_s_setprio(1); _Pragma("unroll") for (int m = 0; m < 4; ++m) _Pragma("unroll") for (int n = 0; n < 2; ++n) _Pragma("unroll") for (int k = 0; k < 2; ++k) \
;     acc[ai][bj][m][n] = __builtin_amdgcn_mfma_f32_16x16x32_bf16(Bt[n][k], At[m][k], acc[ai][bj][m][n], 0, 0, 0); __builtin_amdgcn_s_setprio(0); } while (0)
; #define PG8_WAIT_L(n) asm volatile("s_waitcnt lgkmcnt(" #n ")" ::: "memory")
; #define PG8_BAR __builtin_amdgcn_s_barrier()
; #define PG8_SCHED __builtin_amdgcn_sched_barrier(0)
; template <class Epi, class Sched>
; DI void gemm_phase(LAS unsigned char* lds, const Gemm g, const Sched& S, const Epi& E) {
;     ...
;       const bool last = (t == nt - 2);
;       const char* a1 = cA + (size_t)(t + 1) * kstep;
;       const char* a2 = last ? nA : cA + (size_t)(t + 2) * kstep; const char* b2 = last ? nB : cB + (size_t)(t + 2) * kstep;
;       const char* a3 = a2 + kstep; const char* b3 = b2 + kstep;
;       PG8_LDB(B0, 0, 0); PG8_SCHED; PG8_LDA(At, 0, 0); PG8_STAGE(PG8_SA(1, 1), a1 + hstep, voffA);
;       PG8_WAIT_L(8); PG8_BAR; PG8_WAIT_L(0); PG8_MMA(0, 0, At, B0); PG8_BAR; PG8_SCHED;
;       PG8_LDB(B1, 0, 1); PG8_STAGE(PG8_SB(0, 0), b2, voffB);
;       PG8_BAR; PG8_WAIT_L(0); PG8_MMA(0, 1, At, B1); PG8_BAR;
;       PG8_LDA(At, 0, 1); PG8_STAGE(PG8_SA(0, 0), a2, voffA);
;       PG8_BAR; PG8_WAIT_L(0); PG8_MMA(1, 0, At, B0); PG8_BAR; PG8_SCHED;
.LBB0_137:
	s_add_i32 s41, s1, 2
	s_add_u32 s18, s16, 0x80
	s_addc_u32 s19, s17, 0
	s_cmp_lg_u32 s40, s1
	s_cselect_b32 s20, s18, 0
	s_cselect_b32 s1, s19, 0
	s_add_u32 s18, s14, s20
	s_addc_u32 s19, s15, s1
	s_add_i32 s42, 16, 0x10000
	v_add_u32_e32 v139, s42, v137
	ds_read_b128 v[140:143], v139
	ds_read_b128 v[144:147], v139 offset:1024
	ds_read_b128 v[150:153], v139 offset:2048
	ds_read_b128 v[154:157], v139 offset:3072
	s_add_u32 s20, s12, s20
	s_addc_u32 s21, s13, s1
	v_lshl_add_u64 v[180:181], v[132:133], 0, s[16:17]
	s_add_i32 m0, s31, 0xc000
	ds_read_b128 v[158:161], v138
	ds_read_b128 v[162:165], v138 offset:1024
	ds_read_b128 v[166:169], v138 offset:2048
	ds_read_b128 v[170:173], v138 offset:3072
	ds_read_b128 v[174:177], v138 offset:4096
	ds_read_b128 v[186:189], v138 offset:5120
	ds_read_b128 v[190:193], v138 offset:6144
	ds_read_b128 v[198:201], v138 offset:7168
	global_load_lds_dwordx4 v[180:181], off
	v_lshl_add_u64 v[180:181], v[134:135], 0, s[16:17]
	s_add_i32 m0, s31, 0xe000
	s_nop 0
	global_load_lds_dwordx4 v[180:181], off
	s_barrier
	s_waitcnt lgkmcnt(0)
	s_waitcnt lgkmcnt(0)
	v_mfma_f32_16x16x32_bf16 v[126:129], v[140:143], v[158:161], v[126:129]
	v_mfma_f32_16x16x32_bf16 v[122:125], v[150:153], v[158:161], v[122:125]
	v_mfma_f32_16x16x32_bf16 v[110:113], v[140:143], v[166:169], v[110:113]
	v_mfma_f32_16x16x32_bf16 v[106:109], v[150:153], v[166:169], v[106:109]
	v_mfma_f32_16x16x32_bf16 v[94:97], v[140:143], v[174:177], v[94:97]
	v_mfma_f32_16x16x32_bf16 v[90:93], v[150:153], v[174:177], v[90:93]
	v_mfma_f32_16x16x32_bf16 v[78:81], v[140:143], v[190:193], v[78:81]
	v_mfma_f32_16x16x32_bf16 v[74:77], v[150:153], v[190:193], v[74:77]
	v_mfma_f32_16x16x32_bf16 v[126:129], v[144:147], v[162:165], v[126:129]
	v_mfma_f32_16x16x32_bf16 v[122:125], v[154:157], v[162:165], v[122:125]
	v_mfma_f32_16x16x32_bf16 v[110:113], v[144:147], v[170:173], v[110:113]
	v_mfma_f32_16x16x32_bf16 v[106:109], v[154:157], v[170:173], v[106:109]
	v_mfma_f32_16x16x32_bf16 v[94:97], v[144:147], v[186:189], v[94:97]
	v_mfma_f32_16x16x32_bf16 v[90:93], v[154:157], v[186:189], v[90:93]
	v_mfma_f32_16x16x32_bf16 v[78:81], v[144:147], v[198:201], v[78:81]
	v_mfma_f32_16x16x32_bf16 v[74:77], v[154:157], v[198:201], v[74:77]
	s_barrier
	s_add_i32 s1, 16, 0x14000
	s_add_i32 s42, s42, s30
	v_add_u32_e32 v139, s1, v137
	v_lshl_add_u64 v[180:181], s[20:21], 0, v[0:1]
	s_mov_b32 m0, s42
	ds_read_b128 v[202:205], v139
	ds_read_b128 v[206:209], v139 offset:1024
	ds_read_b128 v[214:217], v139 offset:2048
	ds_read_b128 v[218:221], v139 offset:3072
	global_load_lds_dwordx4 v[180:181], off
	v_lshl_add_u64 v[182:183], s[20:21], 0, v[130:131]
	s_add_i32 m0, s42, 0x2000
	s_nop 0
	global_load_lds_dwordx4 v[182:183], off
	s_barrier
	s_waitcnt lgkmcnt(0)
	s_waitcnt lgkmcnt(0)
	v_mfma_f32_16x16x32_bf16 v[118:121], v[202:205], v[158:161], v[118:121]
	v_mfma_f32_16x16x32_bf16 v[114:117], v[214:217], v[158:161], v[114:117]
	v_mfma_f32_16x16x32_bf16 v[102:105], v[202:205], v[166:169], v[102:105]
	v_mfma_f32_16x16x32_bf16 v[98:101], v[214:217], v[166:169], v[98:101]
	v_mfma_f32_16x16x32_bf16 v[86:89], v[202:205], v[174:177], v[86:89]
	v_mfma_f32_16x16x32_bf16 v[82:85], v[214:217], v[174:177], v[82:85]
	v_mfma_f32_16x16x32_bf16 v[70:73], v[202:205], v[190:193], v[70:73]
	v_mfma_f32_16x16x32_bf16 v[66:69], v[214:217], v[190:193], v[66:69]
	v_mfma_f32_16x16x32_bf16 v[118:121], v[206:209], v[162:165], v[118:121]
	v_mfma_f32_16x16x32_bf16 v[114:117], v[218:221], v[162:165], v[114:117]
	v_mfma_f32_16x16x32_bf16 v[102:105], v[206:209], v[170:173], v[102:105]
	v_mfma_f32_16x16x32_bf16 v[98:101], v[218:221], v[170:173], v[98:101]
	v_mfma_f32_16x16x32_bf16 v[86:89], v[206:209], v[186:189], v[86:89]
	v_mfma_f32_16x16x32_bf16 v[82:85], v[218:221], v[186:189], v[82:85]
	v_mfma_f32_16x16x32_bf16 v[70:73], v[206:209], v[198:201], v[70:73]
	v_mfma_f32_16x16x32_bf16 v[66:69], v[218:221], v[198:201], v[66:69]
	s_mov_b32 m0, s31
	v_lshl_add_u64 v[184:185], s[18:19], 0, v[0:1]
	s_barrier
	ds_read_b128 v[158:161], v138 offset:16384
	ds_read_b128 v[162:165], v138 offset:17408
	ds_read_b128 v[166:169], v138 offset:18432
	ds_read_b128 v[170:173], v138 offset:19456
	ds_read_b128 v[174:177], v138 offset:20480
	ds_read_b128 v[186:189], v138 offset:21504
	ds_read_b128 v[190:193], v138 offset:22528
	ds_read_b128 v[198:201], v138 offset:23552
	global_load_lds_dwordx4 v[184:185], off
	v_lshl_add_u64 v[222:223], s[18:19], 0, v[130:131]
	s_mov_b32 m0, s34
	s_nop 0
	global_load_lds_dwordx4 v[222:223], off
	s_barrier
	s_waitcnt lgkmcnt(0)
	s_waitcnt lgkmcnt(0)
	v_mfma_f32_16x16x32_bf16 v[62:65], v[140:143], v[158:161], v[62:65]
	v_mfma_f32_16x16x32_bf16 v[58:61], v[150:153], v[158:161], v[58:61]
	v_mfma_f32_16x16x32_bf16 v[46:49], v[140:143], v[166:169], v[46:49]
	v_mfma_f32_16x16x32_bf16 v[42:45], v[150:153], v[166:169], v[42:45]
	v_mfma_f32_16x16x32_bf16 v[30:33], v[140:143], v[174:177], v[30:33]
	v_mfma_f32_16x16x32_bf16 v[26:29], v[150:153], v[174:177], v[26:29]
	v_mfma_f32_16x16x32_bf16 v[14:17], v[140:143], v[190:193], v[14:17]
	v_mfma_f32_16x16x32_bf16 v[10:13], v[150:153], v[190:193], v[10:13]
	v_mfma_f32_16x16x32_bf16 v[62:65], v[144:147], v[162:165], v[62:65]
	v_mfma_f32_16x16x32_bf16 v[58:61], v[154:157], v[162:165], v[58:61]
	v_mfma_f32_16x16x32_bf16 v[46:49], v[144:147], v[170:173], v[46:49]
	v_mfma_f32_16x16x32_bf16 v[42:45], v[154:157], v[170:173], v[42:45]
	v_mfma_f32_16x16x32_bf16 v[30:33], v[144:147], v[186:189], v[30:33]
	v_mfma_f32_16x16x32_bf16 v[26:29], v[154:157], v[186:189], v[26:29]
	v_mfma_f32_16x16x32_bf16 v[14:17], v[144:147], v[198:201], v[14:17]
	v_mfma_f32_16x16x32_bf16 v[10:13], v[154:157], v[198:201], v[10:13]
	s_barrier
; #define PG8_STAGE(bufoff, gbase, voff) do { _Pragma("unroll") for (int _i = 0; _i < 2; ++_i) \
;     __builtin_amdgcn_global_load_lds((const unsigned*)((const char*)(gbase) + (voff)[_i]), (LAS unsigned*)(lds + (bufoff) + ldsw + _i * 8192), 16, 0, 0); } while (0)
; #define PG8_LDA(dst, b, h) do { _Pragma("unroll") for (int m = 0; m < 4; ++m) _Pragma("unroll") for (int k = 0; k < 2; ++k) dst[m][k] = *(const LAS bf16x8*)(lds + PG8_SA(b, h) + aoff + m * 2048 + k * 1024); } while (0)
; #define PG8_LDB(dst, b, h) do { _Pragma("unroll") for (int n = 0; n < 2; ++n) _Pragma("unroll") for (int k = 0; k < 2; ++k) dst[n][k] = *(const LAS bf16x8*)(lds + PG8_SB(b, h) + boff + n * 2048 + k * 1024); } while (0)
; #define PG8_MMA(ai, bj, At, Bt) do { __builtin_amdgcn_s_setprio(1); _Pragma("unroll") for (int m = 0; m < 4; ++m) _Pragma("unroll") for (int n = 0; n < 2; ++n) _Pragma("unroll") for (int k = 0; k < 2; ++k) \
;     acc[ai][bj][m][n] = __builtin_amdgcn_mfma_f32_16x16x32_bf16(Bt[n][k], At[m][k], acc[ai][bj][m][n], 0, 0, 0); __builtin_amdgcn_s_setprio(0); } while (0)
; #define PG8_WAIT_V(n) asm volatile("s_waitcnt vmcnt(" #n ")" ::: "memory")
; #define PG8_WAIT_L(n) asm volatile("s_waitcnt lgkmcnt(" #n ")" ::: "memory")
; #define PG8_BAR __builtin_amdgcn_s_barrier()
; #define PG8_SCHED __builtin_amdgcn_sched_barrier(0)
; template <class Epi, class Sched>
; DI void gemm_phase(LAS unsigned char* lds, const Gemm g, const Sched& S, const Epi& E) {
;     ...
;       PG8_STAGE(PG8_SB(0, 1), b2 + hstepB, voffB);
;       PG8_WAIT_V(6); PG8_BAR; PG8_MMA(1, 1, At, B1); PG8_BAR;
;       PG8_LDB(B0, 1, 0); PG8_SCHED; PG8_LDA(At, 1, 0); PG8_STAGE(PG8_SA(0, 1), a2 + hstep, voffA);
;       PG8_WAIT_L(8); PG8_BAR; PG8_WAIT_L(0); PG8_MMA(0, 0, At, B0); PG8_BAR; PG8_SCHED;
;       PG8_LDB(B1, 1, 1); PG8_STAGE(PG8_SB(1, 0), b3, voffB);
;       PG8_BAR; PG8_WAIT_L(0); PG8_MMA(0, 1, At, B1); PG8_BAR;
	s_add_u32 s20, s20, s2
	s_addc_u32 s21, s21, s3
	s_add_i32 s1, s1, s30
	v_lshl_add_u64 v[224:225], s[20:21], 0, v[0:1]
	s_mov_b32 m0, s1
	v_lshl_add_u64 v[226:227], s[20:21], 0, v[130:131]
	global_load_lds_dwordx4 v[224:225], off
	s_add_i32 m0, s1, 0x2000
	s_nop 0
	global_load_lds_dwordx4 v[226:227], off
	s_waitcnt vmcnt(6)
	s_barrier
	v_mfma_f32_16x16x32_bf16 v[54:57], v[202:205], v[158:161], v[54:57]
	v_mfma_f32_16x16x32_bf16 v[50:53], v[214:217], v[158:161], v[50:53]
	v_mfma_f32_16x16x32_bf16 v[38:41], v[202:205], v[166:169], v[38:41]
	v_mfma_f32_16x16x32_bf16 v[34:37], v[214:217], v[166:169], v[34:37]
	v_mfma_f32_16x16x32_bf16 v[22:25], v[202:205], v[174:177], v[22:25]
	v_mfma_f32_16x16x32_bf16 v[18:21], v[214:217], v[174:177], v[18:21]
	v_mfma_f32_16x16x32_bf16 v[6:9], v[202:205], v[190:193], v[6:9]
	v_mfma_f32_16x16x32_bf16 v[2:5], v[214:217], v[190:193], v[2:5]
	v_mfma_f32_16x16x32_bf16 v[54:57], v[206:209], v[162:165], v[54:57]
	v_mfma_f32_16x16x32_bf16 v[50:53], v[218:221], v[162:165], v[50:53]
	v_mfma_f32_16x16x32_bf16 v[38:41], v[206:209], v[170:173], v[38:41]
	v_mfma_f32_16x16x32_bf16 v[34:37], v[218:221], v[170:173], v[34:37]
	v_mfma_f32_16x16x32_bf16 v[22:25], v[206:209], v[186:189], v[22:25]
	v_mfma_f32_16x16x32_bf16 v[18:21], v[218:221], v[186:189], v[18:21]
	v_mfma_f32_16x16x32_bf16 v[6:9], v[206:209], v[198:201], v[6:9]
	v_mfma_f32_16x16x32_bf16 v[2:5], v[218:221], v[198:201], v[2:5]
	s_add_i32 s1, 16, 0x18000
	v_add_u32_e32 v139, s1, v137
	s_barrier
	ds_read_b128 v[140:143], v139
	ds_read_b128 v[144:147], v139 offset:1024
	ds_read_b128 v[150:153], v139 offset:2048
	ds_read_b128 v[154:157], v139 offset:3072
	s_add_u32 s18, s18, s2
	s_addc_u32 s19, s19, s3
	s_mov_b32 m0, s35
	v_lshl_add_u64 v[202:203], s[18:19], 0, v[0:1]
	ds_read_b128 v[158:161], v138 offset:32768
	ds_read_b128 v[162:165], v138 offset:33792
	ds_read_b128 v[166:169], v138 offset:34816
	ds_read_b128 v[170:173], v138 offset:35840
	ds_read_b128 v[174:177], v138 offset:36864
	ds_read_b128 v[186:189], v138 offset:37888
	ds_read_b128 v[190:193], v138 offset:38912
	ds_read_b128 v[198:201], v138 offset:39936
	global_load_lds_dwordx4 v[202:203], off
	v_lshl_add_u64 v[202:203], s[18:19], 0, v[130:131]
	s_mov_b32 m0, s36
	s_nop 0
	global_load_lds_dwordx4 v[202:203], off
	s_barrier
	s_waitcnt lgkmcnt(0)
	s_waitcnt lgkmcnt(0)
	v_mfma_f32_16x16x32_bf16 v[126:129], v[140:143], v[158:161], v[126:129]
	v_mfma_f32_16x16x32_bf16 v[122:125], v[150:153], v[158:161], v[122:125]
	v_mfma_f32_16x16x32_bf16 v[110:113], v[140:143], v[166:169], v[110:113]
	v_mfma_f32_16x16x32_bf16 v[106:109], v[150:153], v[166:169], v[106:109]
	v_mfma_f32_16x16x32_bf16 v[94:97], v[140:143], v[174:177], v[94:97]
	v_mfma_f32_16x16x32_bf16 v[90:93], v[150:153], v[174:177], v[90:93]
	v_mfma_f32_16x16x32_bf16 v[78:81], v[140:143], v[190:193], v[78:81]
	v_mfma_f32_16x16x32_bf16 v[74:77], v[150:153], v[190:193], v[74:77]
	v_mfma_f32_16x16x32_bf16 v[126:129], v[144:147], v[162:165], v[126:129]
	v_mfma_f32_16x16x32_bf16 v[122:125], v[154:157], v[162:165], v[122:125]
	v_mfma_f32_16x16x32_bf16 v[110:113], v[144:147], v[170:173], v[110:113]
	v_mfma_f32_16x16x32_bf16 v[106:109], v[154:157], v[170:173], v[106:109]
	v_mfma_f32_16x16x32_bf16 v[94:97], v[144:147], v[186:189], v[94:97]
	v_mfma_f32_16x16x32_bf16 v[90:93], v[154:157], v[186:189], v[90:93]
	v_mfma_f32_16x16x32_bf16 v[78:81], v[144:147], v[198:201], v[78:81]
	v_mfma_f32_16x16x32_bf16 v[74:77], v[154:157], v[198:201], v[74:77]
	s_barrier
	s_add_i32 s18, 16, 0x1c000
	s_add_i32 s1, s1, s30
	v_add_u32_e32 v139, s18, v137
	v_lshl_add_u64 v[180:181], v[180:181], 0, s[70:71]
	s_mov_b32 m0, s1
	ds_read_b128 v[202:205], v139
	ds_read_b128 v[206:209], v139 offset:1024
	ds_read_b128 v[214:217], v139 offset:2048
	ds_read_b128 v[218:221], v139 offset:3072
	global_load_lds_dwordx4 v[180:181], off
	v_lshl_add_u64 v[180:181], v[182:183], 0, s[70:71]
	s_add_i32 m0, s1, 0x2000
	s_nop 0
	global_load_lds_dwordx4 v[180:181], off
	s_barrier
; #define PG8_STAGE(bufoff, gbase, voff) do { _Pragma("unroll") for (int _i = 0; _i < 2; ++_i) \
;     __builtin_amdgcn_global_load_lds((const unsigned*)((const char*)(gbase) + (voff)[_i]), (LAS unsigned*)(lds + (bufoff) + ldsw + _i * 8192), 16, 0, 0); } while (0)
; #define PG8_LDA(dst, b, h) do { _Pragma("unroll") for (int m = 0; m < 4; ++m) _Pragma("unroll") for (int k = 0; k < 2; ++k) dst[m][k] = *(const LAS bf16x8*)(lds + PG8_SA(b, h) + aoff + m * 2048 + k * 1024); } while (0)
; #define PG8_MMA(ai, bj, At, Bt) do { __builtin_amdgcn_s_setprio(1); _Pragma("unroll") for (int m = 0; m < 4; ++m) _Pragma("unroll") for (int n = 0; n < 2; ++n) _Pragma("unroll") for (int k = 0; k < 2; ++k) \
;     acc[ai][bj][m][n] = __builtin_amdgcn_mfma_f32_16x16x32_bf16(Bt[n][k], At[m][k], acc[ai][bj][m][n], 0, 0, 0); __builtin_amdgcn_s_setprio(0); } while (0)
; #define PG8_WAIT_V(n) asm volatile("s_waitcnt vmcnt(" #n ")" ::: "memory")
; #define PG8_WAIT_L(n) asm volatile("s_waitcnt lgkmcnt(" #n ")" ::: "memory")
; #define PG8_BAR __builtin_amdgcn_s_barrier()
; #define PG8_SCHED __builtin_amdgcn_sched_barrier(0)
; template <class Epi, class Sched>
; DI void gemm_phase(LAS unsigned char* lds, const Gemm g, const Sched& S, const Epi& E) {
;     ...
;       PG8_BAR; PG8_WAIT_L(0); PG8_MMA(0, 1, At, B1); PG8_BAR;
;       PG8_LDA(At, 1, 1); PG8_STAGE(PG8_SA(1, 0), a3, voffA);
;       PG8_BAR; PG8_WAIT_L(0); PG8_MMA(1, 0, At, B0); PG8_BAR; PG8_SCHED;
;       PG8_STAGE(PG8_SB(1, 1), b3 + hstepB, voffB);
;       PG8_WAIT_V(6); PG8_BAR; PG8_MMA(1, 1, At, B1); PG8_BAR;
	s_waitcnt lgkmcnt(0)
	s_waitcnt lgkmcnt(0)
	v_mfma_f32_16x16x32_bf16 v[118:121], v[202:205], v[158:161], v[118:121]
	v_mfma_f32_16x16x32_bf16 v[114:117], v[214:217], v[158:161], v[114:117]
	v_mfma_f32_16x16x32_bf16 v[102:105], v[202:205], v[166:169], v[102:105]
	v_mfma_f32_16x16x32_bf16 v[98:101], v[214:217], v[166:169], v[98:101]
	v_mfma_f32_16x16x32_bf16 v[86:89], v[202:205], v[174:177], v[86:89]
	v_mfma_f32_16x16x32_bf16 v[82:85], v[214:217], v[174:177], v[82:85]
	v_mfma_f32_16x16x32_bf16 v[70:73], v[202:205], v[190:193], v[70:73]
	v_mfma_f32_16x16x32_bf16 v[66:69], v[214:217], v[190:193], v[66:69]
	v_mfma_f32_16x16x32_bf16 v[118:121], v[206:209], v[162:165], v[118:121]
	v_mfma_f32_16x16x32_bf16 v[114:117], v[218:221], v[162:165], v[114:117]
	v_mfma_f32_16x16x32_bf16 v[102:105], v[206:209], v[170:173], v[102:105]
	v_mfma_f32_16x16x32_bf16 v[98:101], v[218:221], v[170:173], v[98:101]
	v_mfma_f32_16x16x32_bf16 v[86:89], v[206:209], v[186:189], v[86:89]
	v_mfma_f32_16x16x32_bf16 v[82:85], v[218:221], v[186:189], v[82:85]
	v_mfma_f32_16x16x32_bf16 v[70:73], v[206:209], v[198:201], v[70:73]
	v_mfma_f32_16x16x32_bf16 v[66:69], v[218:221], v[198:201], v[66:69]
	s_mov_b32 m0, s37
	v_lshl_add_u64 v[180:181], v[184:185], 0, s[70:71]
	s_barrier
	ds_read_b128 v[158:161], v138 offset:49152
	ds_read_b128 v[162:165], v138 offset:50176
	ds_read_b128 v[166:169], v138 offset:51200
	ds_read_b128 v[170:173], v138 offset:52224
	ds_read_b128 v[174:177], v138 offset:53248
	ds_read_b128 v[186:189], v138 offset:54272
	ds_read_b128 v[190:193], v138 offset:55296
	ds_read_b128 v[198:201], v138 offset:56320
	global_load_lds_dwordx4 v[180:181], off
	v_lshl_add_u64 v[180:181], v[222:223], 0, s[70:71]
	s_mov_b32 m0, s38
	s_nop 0
	global_load_lds_dwordx4 v[180:181], off
	s_barrier
	s_waitcnt lgkmcnt(0)
	s_waitcnt lgkmcnt(0)
	v_mfma_f32_16x16x32_bf16 v[62:65], v[140:143], v[158:161], v[62:65]
	v_mfma_f32_16x16x32_bf16 v[58:61], v[150:153], v[158:161], v[58:61]
	v_mfma_f32_16x16x32_bf16 v[46:49], v[140:143], v[166:169], v[46:49]
	v_mfma_f32_16x16x32_bf16 v[42:45], v[150:153], v[166:169], v[42:45]
	v_mfma_f32_16x16x32_bf16 v[30:33], v[140:143], v[174:177], v[30:33]
	v_mfma_f32_16x16x32_bf16 v[26:29], v[150:153], v[174:177], v[26:29]
	v_mfma_f32_16x16x32_bf16 v[14:17], v[140:143], v[190:193], v[14:17]
	v_mfma_f32_16x16x32_bf16 v[10:13], v[150:153], v[190:193], v[10:13]
	v_mfma_f32_16x16x32_bf16 v[62:65], v[144:147], v[162:165], v[62:65]
	v_mfma_f32_16x16x32_bf16 v[58:61], v[154:157], v[162:165], v[58:61]
	v_mfma_f32_16x16x32_bf16 v[46:49], v[144:147], v[170:173], v[46:49]
	v_mfma_f32_16x16x32_bf16 v[42:45], v[154:157], v[170:173], v[42:45]
	v_mfma_f32_16x16x32_bf16 v[30:33], v[144:147], v[186:189], v[30:33]
	v_mfma_f32_16x16x32_bf16 v[26:29], v[154:157], v[186:189], v[26:29]
	v_mfma_f32_16x16x32_bf16 v[14:17], v[144:147], v[198:201], v[14:17]
	v_mfma_f32_16x16x32_bf16 v[10:13], v[154:157], v[198:201], v[10:13]
	s_barrier
	s_add_i32 s1, s18, s30
	v_lshl_add_u64 v[140:141], v[224:225], 0, s[70:71]
	s_mov_b32 m0, s1
	s_nop 0
	global_load_lds_dwordx4 v[140:141], off
	v_lshl_add_u64 v[140:141], v[226:227], 0, s[70:71]
	s_add_i32 m0, s1, 0x2000
	s_nop 0
	global_load_lds_dwordx4 v[140:141], off
	s_waitcnt vmcnt(6)
	s_barrier
	v_mfma_f32_16x16x32_bf16 v[54:57], v[202:205], v[158:161], v[54:57]
	v_mfma_f32_16x16x32_bf16 v[50:53], v[214:217], v[158:161], v[50:53]
	v_mfma_f32_16x16x32_bf16 v[38:41], v[202:205], v[166:169], v[38:41]
	v_mfma_f32_16x16x32_bf16 v[34:37], v[214:217], v[166:169], v[34:37]
	v_mfma_f32_16x16x32_bf16 v[22:25], v[202:205], v[174:177], v[22:25]
	v_mfma_f32_16x16x32_bf16 v[18:21], v[214:217], v[174:177], v[18:21]
	v_mfma_f32_16x16x32_bf16 v[6:9], v[202:205], v[190:193], v[6:9]
	v_mfma_f32_16x16x32_bf16 v[2:5], v[214:217], v[190:193], v[2:5]
	v_mfma_f32_16x16x32_bf16 v[54:57], v[206:209], v[162:165], v[54:57]
	v_mfma_f32_16x16x32_bf16 v[50:53], v[218:221], v[162:165], v[50:53]
	v_mfma_f32_16x16x32_bf16 v[38:41], v[206:209], v[170:173], v[38:41]
	v_mfma_f32_16x16x32_bf16 v[34:37], v[218:221], v[170:173], v[34:37]
	v_mfma_f32_16x16x32_bf16 v[22:25], v[206:209], v[186:189], v[22:25]
	v_mfma_f32_16x16x32_bf16 v[18:21], v[218:221], v[186:189], v[18:21]
	v_mfma_f32_16x16x32_bf16 v[6:9], v[206:209], v[198:201], v[6:9]
	v_mfma_f32_16x16x32_bf16 v[2:5], v[218:221], v[198:201], v[2:5]
	s_add_u32 s16, s16, 0x100
	s_addc_u32 s17, s17, 0
	s_cmp_ge_i32 s41, s39
	s_mov_b32 s1, s41
	s_barrier
	s_cbranch_scc0 .LBB0_137

; #define PG8_STAGE(bufoff, gbase, voff) do { _Pragma("unroll") for (int _i = 0; _i < 2; ++_i) \
;     __builtin_amdgcn_global_load_lds((const unsigned*)((const char*)(gbase) + (voff)[_i]), (LAS unsigned*)(lds + (bufoff) + ldsw + _i * 8192), 16, 0, 0); } while (0)
; #define PG8_LDA(dst, b, h) do { _Pragma("unroll") for (int m = 0; m < 4; ++m) _Pragma("unroll") for (int k = 0; k < 2; ++k) dst[m][k] = *(const LAS bf16x8*)(lds + PG8_SA(b, h) + aoff + m * 2048 + k * 1024); } while (0)
; #define PG8_LDB(dst, b, h) do { _Pragma("unroll") for (int n = 0; n < 2; ++n) _Pragma("unroll") for (int k = 0; k < 2; ++k) dst[n][k] = *(const LAS bf16x8*)(lds + PG8_SB(b, h) + boff + n * 2048 + k * 1024); } while (0)
; #define PG8_MMA(ai, bj, At, Bt) do { __builtin_amdgcn_s_setprio(1); _Pragma("unroll") for (int m = 0; m < 4; ++m) _Pragma("unroll") for (int n = 0; n < 2; ++n) _Pragma("unroll") for (int k = 0; k < 2; ++k) \
;     acc[ai][bj][m][n] = __builtin_amdgcn_mfma_f32_16x16x32_bf16(Bt[n][k], At[m][k], acc[ai][bj][m][n], 0, 0, 0); __builtin_amdgcn_s_setprio(0); } while (0)
; #define PG8_WAIT_L(n) asm volatile("s_waitcnt lgkmcnt(" #n ")" ::: "memory")
; #define PG8_BAR __builtin_amdgcn_s_barrier()
; #define PG8_SCHED __builtin_amdgcn_sched_barrier(0)
; template <class Epi, class Sched>
; DI void gemm_phase(LAS unsigned char* lds, const Gemm g, const Sched& S, const Epi& E) {
;     ...
;       const bool last = (t == nt - 2);
;       const char* a1 = cA + (size_t)(t + 1) * kstep;
;       const char* a2 = last ? nA : cA + (size_t)(t + 2) * kstep; const char* b2 = last ? nB : cB + (size_t)(t + 2) * kstep;
;       const char* a3 = a2 + kstep; const char* b3 = b2 + kstep;
;       PG8_LDB(B0, 0, 0); PG8_SCHED; PG8_LDA(At, 0, 0); PG8_STAGE(PG8_SA(1, 1), a1 + hstep, voffA);
;       PG8_WAIT_L(8); PG8_BAR; PG8_WAIT_L(0); PG8_MMA(0, 0, At, B0); PG8_BAR; PG8_SCHED;
;       PG8_LDB(B1, 0, 1); PG8_STAGE(PG8_SB(0, 0), b2, voffB);
;       PG8_BAR; PG8_WAIT_L(0); PG8_MMA(0, 1, At, B1); PG8_BAR;
;       PG8_LDA(At, 0, 1); PG8_STAGE(PG8_SA(0, 0), a2, voffA);
;       PG8_BAR; PG8_WAIT_L(0); PG8_MMA(1, 0, At, B0); PG8_BAR; PG8_SCHED;
.LBB0_153:
	s_add_i32 s36, s16, 2
	s_add_u32 s17, s14, 0xfa800080
	s_addc_u32 s18, s15, -1
	s_cmp_lg_u32 s35, s16
	s_cselect_b32 s19, s18, 0
	s_cselect_b32 s18, s17, 0
	s_add_u32 s16, s12, s18
	s_addc_u32 s17, s13, s19
	s_add_i32 s37, 16, 0x10000
	v_add_u32_e32 v139, s37, v137
	ds_read_b128 v[140:143], v139
	ds_read_b128 v[144:147], v139 offset:1024
	ds_read_b128 v[150:153], v139 offset:2048
	ds_read_b128 v[154:157], v139 offset:3072
	s_add_u32 s18, s2, s18
	s_addc_u32 s19, s3, s19
	v_lshl_add_u64 v[180:181], v[132:133], 0, s[14:15]
	s_add_i32 m0, s24, 0xc000
	ds_read_b128 v[158:161], v138
	ds_read_b128 v[162:165], v138 offset:1024
	ds_read_b128 v[166:169], v138 offset:2048
	ds_read_b128 v[170:173], v138 offset:3072
	ds_read_b128 v[174:177], v138 offset:4096
	ds_read_b128 v[186:189], v138 offset:5120
	ds_read_b128 v[190:193], v138 offset:6144
	ds_read_b128 v[198:201], v138 offset:7168
	global_load_lds_dwordx4 v[180:181], off
	v_lshl_add_u64 v[180:181], v[134:135], 0, s[14:15]
	s_add_i32 m0, s24, 0xe000
	s_nop 0
	global_load_lds_dwordx4 v[180:181], off
	s_barrier
	s_waitcnt lgkmcnt(0)
	s_waitcnt lgkmcnt(0)
	v_mfma_f32_16x16x32_bf16 v[126:129], v[140:143], v[158:161], v[126:129]
	v_mfma_f32_16x16x32_bf16 v[122:125], v[150:153], v[158:161], v[122:125]
	v_mfma_f32_16x16x32_bf16 v[110:113], v[140:143], v[166:169], v[110:113]
	v_mfma_f32_16x16x32_bf16 v[106:109], v[150:153], v[166:169], v[106:109]
	v_mfma_f32_16x16x32_bf16 v[94:97], v[140:143], v[174:177], v[94:97]
	v_mfma_f32_16x16x32_bf16 v[90:93], v[150:153], v[174:177], v[90:93]
	v_mfma_f32_16x16x32_bf16 v[78:81], v[140:143], v[190:193], v[78:81]
	v_mfma_f32_16x16x32_bf16 v[74:77], v[150:153], v[190:193], v[74:77]
	v_mfma_f32_16x16x32_bf16 v[126:129], v[144:147], v[162:165], v[126:129]
	v_mfma_f32_16x16x32_bf16 v[122:125], v[154:157], v[162:165], v[122:125]
	v_mfma_f32_16x16x32_bf16 v[110:113], v[144:147], v[170:173], v[110:113]
	v_mfma_f32_16x16x32_bf16 v[106:109], v[154:157], v[170:173], v[106:109]
	v_mfma_f32_16x16x32_bf16 v[94:97], v[144:147], v[186:189], v[94:97]
	v_mfma_f32_16x16x32_bf16 v[90:93], v[154:157], v[186:189], v[90:93]
	v_mfma_f32_16x16x32_bf16 v[78:81], v[144:147], v[198:201], v[78:81]
	v_mfma_f32_16x16x32_bf16 v[74:77], v[154:157], v[198:201], v[74:77]
	s_barrier
	s_add_i32 s38, 16, 0x14000
	s_add_i32 s37, s37, s23
	v_add_u32_e32 v139, s38, v137
	v_lshl_add_u64 v[180:181], s[18:19], 0, v[0:1]
	s_mov_b32 m0, s37
	ds_read_b128 v[202:205], v139
	ds_read_b128 v[206:209], v139 offset:1024
	ds_read_b128 v[214:217], v139 offset:2048
	ds_read_b128 v[218:221], v139 offset:3072
	global_load_lds_dwordx4 v[180:181], off
	v_lshl_add_u64 v[182:183], s[18:19], 0, v[130:131]
	s_add_i32 m0, s37, 0x2000
	s_nop 0
	global_load_lds_dwordx4 v[182:183], off
	s_barrier
	s_waitcnt lgkmcnt(0)
	s_waitcnt lgkmcnt(0)
	v_mfma_f32_16x16x32_bf16 v[118:121], v[202:205], v[158:161], v[118:121]
	v_mfma_f32_16x16x32_bf16 v[114:117], v[214:217], v[158:161], v[114:117]
	v_mfma_f32_16x16x32_bf16 v[102:105], v[202:205], v[166:169], v[102:105]
	v_mfma_f32_16x16x32_bf16 v[98:101], v[214:217], v[166:169], v[98:101]
	v_mfma_f32_16x16x32_bf16 v[86:89], v[202:205], v[174:177], v[86:89]
	v_mfma_f32_16x16x32_bf16 v[82:85], v[214:217], v[174:177], v[82:85]
	v_mfma_f32_16x16x32_bf16 v[70:73], v[202:205], v[190:193], v[70:73]
	v_mfma_f32_16x16x32_bf16 v[66:69], v[214:217], v[190:193], v[66:69]
	v_mfma_f32_16x16x32_bf16 v[118:121], v[206:209], v[162:165], v[118:121]
	v_mfma_f32_16x16x32_bf16 v[114:117], v[218:221], v[162:165], v[114:117]
	v_mfma_f32_16x16x32_bf16 v[102:105], v[206:209], v[170:173], v[102:105]
	v_mfma_f32_16x16x32_bf16 v[98:101], v[218:221], v[170:173], v[98:101]
	v_mfma_f32_16x16x32_bf16 v[86:89], v[206:209], v[186:189], v[86:89]
	v_mfma_f32_16x16x32_bf16 v[82:85], v[218:221], v[186:189], v[82:85]
	v_mfma_f32_16x16x32_bf16 v[70:73], v[206:209], v[198:201], v[70:73]
	v_mfma_f32_16x16x32_bf16 v[66:69], v[218:221], v[198:201], v[66:69]
	s_mov_b32 m0, s24
	v_lshl_add_u64 v[184:185], s[16:17], 0, v[0:1]
	s_barrier
	ds_read_b128 v[158:161], v138 offset:16384
	ds_read_b128 v[162:165], v138 offset:17408
	ds_read_b128 v[166:169], v138 offset:18432
	ds_read_b128 v[170:173], v138 offset:19456
	ds_read_b128 v[174:177], v138 offset:20480
	ds_read_b128 v[186:189], v138 offset:21504
	ds_read_b128 v[190:193], v138 offset:22528
	ds_read_b128 v[198:201], v138 offset:23552
	global_load_lds_dwordx4 v[184:185], off
	v_lshl_add_u64 v[222:223], s[16:17], 0, v[130:131]
	s_mov_b32 m0, s25
	s_nop 0
	global_load_lds_dwordx4 v[222:223], off
	s_barrier
	s_waitcnt lgkmcnt(0)
	s_waitcnt lgkmcnt(0)
	v_mfma_f32_16x16x32_bf16 v[62:65], v[140:143], v[158:161], v[62:65]
	v_mfma_f32_16x16x32_bf16 v[58:61], v[150:153], v[158:161], v[58:61]
	v_mfma_f32_16x16x32_bf16 v[46:49], v[140:143], v[166:169], v[46:49]
	v_mfma_f32_16x16x32_bf16 v[42:45], v[150:153], v[166:169], v[42:45]
	v_mfma_f32_16x16x32_bf16 v[30:33], v[140:143], v[174:177], v[30:33]
	v_mfma_f32_16x16x32_bf16 v[26:29], v[150:153], v[174:177], v[26:29]
	v_mfma_f32_16x16x32_bf16 v[14:17], v[140:143], v[190:193], v[14:17]
	v_mfma_f32_16x16x32_bf16 v[10:13], v[150:153], v[190:193], v[10:13]
	v_mfma_f32_16x16x32_bf16 v[62:65], v[144:147], v[162:165], v[62:65]
	v_mfma_f32_16x16x32_bf16 v[58:61], v[154:157], v[162:165], v[58:61]
	v_mfma_f32_16x16x32_bf16 v[46:49], v[144:147], v[170:173], v[46:49]
	v_mfma_f32_16x16x32_bf16 v[42:45], v[154:157], v[170:173], v[42:45]
	v_mfma_f32_16x16x32_bf16 v[30:33], v[144:147], v[186:189], v[30:33]
	v_mfma_f32_16x16x32_bf16 v[26:29], v[154:157], v[186:189], v[26:29]
	v_mfma_f32_16x16x32_bf16 v[14:17], v[144:147], v[198:201], v[14:17]
	v_mfma_f32_16x16x32_bf16 v[10:13], v[154:157], v[198:201], v[10:13]
	s_barrier
; #define PG8_STAGE(bufoff, gbase, voff) do { _Pragma("unroll") for (int _i = 0; _i < 2; ++_i) \
;     __builtin_amdgcn_global_load_lds((const unsigned*)((const char*)(gbase) + (voff)[_i]), (LAS unsigned*)(lds + (bufoff) + ldsw + _i * 8192), 16, 0, 0); } while (0)
; #define PG8_LDA(dst, b, h) do { _Pragma("unroll") for (int m = 0; m < 4; ++m) _Pragma("unroll") for (int k = 0; k < 2; ++k) dst[m][k] = *(const LAS bf16x8*)(lds + PG8_SA(b, h) + aoff + m * 2048 + k * 1024); } while (0)
; #define PG8_LDB(dst, b, h) do { _Pragma("unroll") for (int n = 0; n < 2; ++n) _Pragma("unroll") for (int k = 0; k < 2; ++k) dst[n][k] = *(const LAS bf16x8*)(lds + PG8_SB(b, h) + boff + n * 2048 + k * 1024); } while (0)
; #define PG8_MMA(ai, bj, At, Bt) do { __builtin_amdgcn_s_setprio(1); _Pragma("unroll") for (int m = 0; m < 4; ++m) _Pragma("unroll") for (int n = 0; n < 2; ++n) _Pragma("unroll") for (int k = 0; k < 2; ++k) \
;     acc[ai][bj][m][n] = __builtin_amdgcn_mfma_f32_16x16x32_bf16(Bt[n][k], At[m][k], acc[ai][bj][m][n], 0, 0, 0); __builtin_amdgcn_s_setprio(0); } while (0)
; #define PG8_WAIT_V(n) asm volatile("s_waitcnt vmcnt(" #n ")" ::: "memory")
; #define PG8_WAIT_L(n) asm volatile("s_waitcnt lgkmcnt(" #n ")" ::: "memory")
; #define PG8_BAR __builtin_amdgcn_s_barrier()
; #define PG8_SCHED __builtin_amdgcn_sched_barrier(0)
; template <class Epi, class Sched>
; DI void gemm_phase(LAS unsigned char* lds, const Gemm g, const Sched& S, const Epi& E) {
;     ...
;       PG8_STAGE(PG8_SB(0, 1), b2 + hstepB, voffB);
;       PG8_WAIT_V(6); PG8_BAR; PG8_MMA(1, 1, At, B1); PG8_BAR;
;       PG8_LDB(B0, 1, 0); PG8_SCHED; PG8_LDA(At, 1, 0); PG8_STAGE(PG8_SA(0, 1), a2 + hstep, voffA);
;       PG8_WAIT_L(8); PG8_BAR; PG8_WAIT_L(0); PG8_MMA(0, 0, At, B0); PG8_BAR; PG8_SCHED;
;       PG8_LDB(B1, 1, 1); PG8_STAGE(PG8_SB(1, 0), b3, voffB);
;       PG8_BAR; PG8_WAIT_L(0); PG8_MMA(0, 1, At, B1); PG8_BAR;
	s_add_u32 s18, s18, s0
	s_addc_u32 s19, s19, s1
	s_add_i32 s37, s38, s23
	v_lshl_add_u64 v[224:225], s[18:19], 0, v[0:1]
	s_mov_b32 m0, s37
	v_lshl_add_u64 v[226:227], s[18:19], 0, v[130:131]
	global_load_lds_dwordx4 v[224:225], off
	s_add_i32 m0, s37, 0x2000
	s_nop 0
	global_load_lds_dwordx4 v[226:227], off
	s_waitcnt vmcnt(6)
	s_barrier
	v_mfma_f32_16x16x32_bf16 v[54:57], v[202:205], v[158:161], v[54:57]
	v_mfma_f32_16x16x32_bf16 v[50:53], v[214:217], v[158:161], v[50:53]
	v_mfma_f32_16x16x32_bf16 v[38:41], v[202:205], v[166:169], v[38:41]
	v_mfma_f32_16x16x32_bf16 v[34:37], v[214:217], v[166:169], v[34:37]
	v_mfma_f32_16x16x32_bf16 v[22:25], v[202:205], v[174:177], v[22:25]
	v_mfma_f32_16x16x32_bf16 v[18:21], v[214:217], v[174:177], v[18:21]
	v_mfma_f32_16x16x32_bf16 v[6:9], v[202:205], v[190:193], v[6:9]
	v_mfma_f32_16x16x32_bf16 v[2:5], v[214:217], v[190:193], v[2:5]
	v_mfma_f32_16x16x32_bf16 v[54:57], v[206:209], v[162:165], v[54:57]
	v_mfma_f32_16x16x32_bf16 v[50:53], v[218:221], v[162:165], v[50:53]
	v_mfma_f32_16x16x32_bf16 v[38:41], v[206:209], v[170:173], v[38:41]
	v_mfma_f32_16x16x32_bf16 v[34:37], v[218:221], v[170:173], v[34:37]
	v_mfma_f32_16x16x32_bf16 v[22:25], v[206:209], v[186:189], v[22:25]
	v_mfma_f32_16x16x32_bf16 v[18:21], v[218:221], v[186:189], v[18:21]
	v_mfma_f32_16x16x32_bf16 v[6:9], v[206:209], v[198:201], v[6:9]
	v_mfma_f32_16x16x32_bf16 v[2:5], v[218:221], v[198:201], v[2:5]
	s_add_i32 s18, 16, 0x18000
	v_add_u32_e32 v139, s18, v137
	s_barrier
	ds_read_b128 v[140:143], v139
	ds_read_b128 v[144:147], v139 offset:1024
	ds_read_b128 v[150:153], v139 offset:2048
	ds_read_b128 v[154:157], v139 offset:3072
	s_add_u32 s16, s16, s0
	s_addc_u32 s17, s17, s1
	s_mov_b32 m0, s26
	v_lshl_add_u64 v[202:203], s[16:17], 0, v[0:1]
	ds_read_b128 v[158:161], v138 offset:32768
	ds_read_b128 v[162:165], v138 offset:33792
	ds_read_b128 v[166:169], v138 offset:34816
	ds_read_b128 v[170:173], v138 offset:35840
	ds_read_b128 v[174:177], v138 offset:36864
	ds_read_b128 v[186:189], v138 offset:37888
	ds_read_b128 v[190:193], v138 offset:38912
	ds_read_b128 v[198:201], v138 offset:39936
	global_load_lds_dwordx4 v[202:203], off
	v_lshl_add_u64 v[202:203], s[16:17], 0, v[130:131]
	s_mov_b32 m0, s27
	s_nop 0
	global_load_lds_dwordx4 v[202:203], off
	s_barrier
	s_waitcnt lgkmcnt(0)
	s_waitcnt lgkmcnt(0)
	v_mfma_f32_16x16x32_bf16 v[126:129], v[140:143], v[158:161], v[126:129]
	v_mfma_f32_16x16x32_bf16 v[122:125], v[150:153], v[158:161], v[122:125]
	v_mfma_f32_16x16x32_bf16 v[110:113], v[140:143], v[166:169], v[110:113]
	v_mfma_f32_16x16x32_bf16 v[106:109], v[150:153], v[166:169], v[106:109]
	v_mfma_f32_16x16x32_bf16 v[94:97], v[140:143], v[174:177], v[94:97]
	v_mfma_f32_16x16x32_bf16 v[90:93], v[150:153], v[174:177], v[90:93]
	v_mfma_f32_16x16x32_bf16 v[78:81], v[140:143], v[190:193], v[78:81]
	v_mfma_f32_16x16x32_bf16 v[74:77], v[150:153], v[190:193], v[74:77]
	v_mfma_f32_16x16x32_bf16 v[126:129], v[144:147], v[162:165], v[126:129]
	v_mfma_f32_16x16x32_bf16 v[122:125], v[154:157], v[162:165], v[122:125]
	v_mfma_f32_16x16x32_bf16 v[110:113], v[144:147], v[170:173], v[110:113]
	v_mfma_f32_16x16x32_bf16 v[106:109], v[154:157], v[170:173], v[106:109]
	v_mfma_f32_16x16x32_bf16 v[94:97], v[144:147], v[186:189], v[94:97]
	v_mfma_f32_16x16x32_bf16 v[90:93], v[154:157], v[186:189], v[90:93]
	v_mfma_f32_16x16x32_bf16 v[78:81], v[144:147], v[198:201], v[78:81]
	v_mfma_f32_16x16x32_bf16 v[74:77], v[154:157], v[198:201], v[74:77]
	s_barrier
	s_add_i32 s16, 16, 0x1c000
	s_add_i32 s17, s18, s23
	v_add_u32_e32 v139, s16, v137
	v_lshl_add_u64 v[180:181], v[180:181], 0, s[70:71]
	s_mov_b32 m0, s17
	ds_read_b128 v[202:205], v139
	ds_read_b128 v[206:209], v139 offset:1024
	ds_read_b128 v[214:217], v139 offset:2048
	ds_read_b128 v[218:221], v139 offset:3072
	global_load_lds_dwordx4 v[180:181], off
	v_lshl_add_u64 v[180:181], v[182:183], 0, s[70:71]
	s_add_i32 m0, s17, 0x2000
	s_nop 0
	global_load_lds_dwordx4 v[180:181], off
	s_barrier
; #define PG8_STAGE(bufoff, gbase, voff) do { _Pragma("unroll") for (int _i = 0; _i < 2; ++_i) \
;     __builtin_amdgcn_global_load_lds((const unsigned*)((const char*)(gbase) + (voff)[_i]), (LAS unsigned*)(lds + (bufoff) + ldsw + _i * 8192), 16, 0, 0); } while (0)
; #define PG8_LDA(dst, b, h) do { _Pragma("unroll") for (int m = 0; m < 4; ++m) _Pragma("unroll") for (int k = 0; k < 2; ++k) dst[m][k] = *(const LAS bf16x8*)(lds + PG8_SA(b, h) + aoff + m * 2048 + k * 1024); } while (0)
; #define PG8_MMA(ai, bj, At, Bt) do { __builtin_amdgcn_s_setprio(1); _Pragma("unroll") for (int m = 0; m < 4; ++m) _Pragma("unroll") for (int n = 0; n < 2; ++n) _Pragma("unroll") for (int k = 0; k < 2; ++k) \
;     acc[ai][bj][m][n] = __builtin_amdgcn_mfma_f32_16x16x32_bf16(Bt[n][k], At[m][k], acc[ai][bj][m][n], 0, 0, 0); __builtin_amdgcn_s_setprio(0); } while (0)
; #define PG8_WAIT_V(n) asm volatile("s_waitcnt vmcnt(" #n ")" ::: "memory")
; #define PG8_WAIT_L(n) asm volatile("s_waitcnt lgkmcnt(" #n ")" ::: "memory")
; #define PG8_BAR __builtin_amdgcn_s_barrier()
; #define PG8_SCHED __builtin_amdgcn_sched_barrier(0)
; template <class Epi, class Sched>
; DI void gemm_phase(LAS unsigned char* lds, const Gemm g, const Sched& S, const Epi& E) {
;     ...
;       PG8_BAR; PG8_WAIT_L(0); PG8_MMA(0, 1, At, B1); PG8_BAR;
;       PG8_LDA(At, 1, 1); PG8_STAGE(PG8_SA(1, 0), a3, voffA);
;       PG8_BAR; PG8_WAIT_L(0); PG8_MMA(1, 0, At, B0); PG8_BAR; PG8_SCHED;
;       PG8_STAGE(PG8_SB(1, 1), b3 + hstepB, voffB);
;       PG8_WAIT_V(6); PG8_BAR; PG8_MMA(1, 1, At, B1); PG8_BAR;
	s_waitcnt lgkmcnt(0)
	s_waitcnt lgkmcnt(0)
	v_mfma_f32_16x16x32_bf16 v[118:121], v[202:205], v[158:161], v[118:121]
	v_mfma_f32_16x16x32_bf16 v[114:117], v[214:217], v[158:161], v[114:117]
	v_mfma_f32_16x16x32_bf16 v[102:105], v[202:205], v[166:169], v[102:105]
	v_mfma_f32_16x16x32_bf16 v[98:101], v[214:217], v[166:169], v[98:101]
	v_mfma_f32_16x16x32_bf16 v[86:89], v[202:205], v[174:177], v[86:89]
	v_mfma_f32_16x16x32_bf16 v[82:85], v[214:217], v[174:177], v[82:85]
	v_mfma_f32_16x16x32_bf16 v[70:73], v[202:205], v[190:193], v[70:73]
	v_mfma_f32_16x16x32_bf16 v[66:69], v[214:217], v[190:193], v[66:69]
	v_mfma_f32_16x16x32_bf16 v[118:121], v[206:209], v[162:165], v[118:121]
	v_mfma_f32_16x16x32_bf16 v[114:117], v[218:221], v[162:165], v[114:117]
	v_mfma_f32_16x16x32_bf16 v[102:105], v[206:209], v[170:173], v[102:105]
	v_mfma_f32_16x16x32_bf16 v[98:101], v[218:221], v[170:173], v[98:101]
	v_mfma_f32_16x16x32_bf16 v[86:89], v[206:209], v[186:189], v[86:89]
	v_mfma_f32_16x16x32_bf16 v[82:85], v[218:221], v[186:189], v[82:85]
	v_mfma_f32_16x16x32_bf16 v[70:73], v[206:209], v[198:201], v[70:73]
	v_mfma_f32_16x16x32_bf16 v[66:69], v[218:221], v[198:201], v[66:69]
	s_mov_b32 m0, s30
	v_lshl_add_u64 v[180:181], v[184:185], 0, s[70:71]
	s_barrier
	ds_read_b128 v[158:161], v138 offset:49152
	ds_read_b128 v[162:165], v138 offset:50176
	ds_read_b128 v[166:169], v138 offset:51200
	ds_read_b128 v[170:173], v138 offset:52224
	ds_read_b128 v[174:177], v138 offset:53248
	ds_read_b128 v[186:189], v138 offset:54272
	ds_read_b128 v[190:193], v138 offset:55296
	ds_read_b128 v[198:201], v138 offset:56320
	global_load_lds_dwordx4 v[180:181], off
	v_lshl_add_u64 v[180:181], v[222:223], 0, s[70:71]
	s_mov_b32 m0, s31
	s_nop 0
	global_load_lds_dwordx4 v[180:181], off
	s_barrier
	s_waitcnt lgkmcnt(0)
	s_waitcnt lgkmcnt(0)
	v_mfma_f32_16x16x32_bf16 v[62:65], v[140:143], v[158:161], v[62:65]
	v_mfma_f32_16x16x32_bf16 v[58:61], v[150:153], v[158:161], v[58:61]
	v_mfma_f32_16x16x32_bf16 v[46:49], v[140:143], v[166:169], v[46:49]
	v_mfma_f32_16x16x32_bf16 v[42:45], v[150:153], v[166:169], v[42:45]
	v_mfma_f32_16x16x32_bf16 v[30:33], v[140:143], v[174:177], v[30:33]
	v_mfma_f32_16x16x32_bf16 v[26:29], v[150:153], v[174:177], v[26:29]
	v_mfma_f32_16x16x32_bf16 v[14:17], v[140:143], v[190:193], v[14:17]
	v_mfma_f32_16x16x32_bf16 v[10:13], v[150:153], v[190:193], v[10:13]
	v_mfma_f32_16x16x32_bf16 v[62:65], v[144:147], v[162:165], v[62:65]
	v_mfma_f32_16x16x32_bf16 v[58:61], v[154:157], v[162:165], v[58:61]
	v_mfma_f32_16x16x32_bf16 v[46:49], v[144:147], v[170:173], v[46:49]
	v_mfma_f32_16x16x32_bf16 v[42:45], v[154:157], v[170:173], v[42:45]
	v_mfma_f32_16x16x32_bf16 v[30:33], v[144:147], v[186:189], v[30:33]
	v_mfma_f32_16x16x32_bf16 v[26:29], v[154:157], v[186:189], v[26:29]
	v_mfma_f32_16x16x32_bf16 v[14:17], v[144:147], v[198:201], v[14:17]
	v_mfma_f32_16x16x32_bf16 v[10:13], v[154:157], v[198:201], v[10:13]
	s_barrier
	s_add_i32 s16, s16, s23
	v_lshl_add_u64 v[140:141], v[224:225], 0, s[70:71]
	s_mov_b32 m0, s16
	s_nop 0
	global_load_lds_dwordx4 v[140:141], off
	v_lshl_add_u64 v[140:141], v[226:227], 0, s[70:71]
	s_add_i32 m0, s16, 0x2000
	s_nop 0
	global_load_lds_dwordx4 v[140:141], off
	s_waitcnt vmcnt(6)
	s_barrier
	v_mfma_f32_16x16x32_bf16 v[54:57], v[202:205], v[158:161], v[54:57]
	v_mfma_f32_16x16x32_bf16 v[50:53], v[214:217], v[158:161], v[50:53]
	v_mfma_f32_16x16x32_bf16 v[38:41], v[202:205], v[166:169], v[38:41]
	v_mfma_f32_16x16x32_bf16 v[34:37], v[214:217], v[166:169], v[34:37]
	v_mfma_f32_16x16x32_bf16 v[22:25], v[202:205], v[174:177], v[22:25]
	v_mfma_f32_16x16x32_bf16 v[18:21], v[214:217], v[174:177], v[18:21]
	v_mfma_f32_16x16x32_bf16 v[6:9], v[202:205], v[190:193], v[6:9]
	v_mfma_f32_16x16x32_bf16 v[2:5], v[214:217], v[190:193], v[2:5]
	v_mfma_f32_16x16x32_bf16 v[54:57], v[206:209], v[162:165], v[54:57]
	v_mfma_f32_16x16x32_bf16 v[50:53], v[218:221], v[162:165], v[50:53]
	v_mfma_f32_16x16x32_bf16 v[38:41], v[206:209], v[170:173], v[38:41]
	v_mfma_f32_16x16x32_bf16 v[34:37], v[218:221], v[170:173], v[34:37]
	v_mfma_f32_16x16x32_bf16 v[22:25], v[206:209], v[186:189], v[22:25]
	v_mfma_f32_16x16x32_bf16 v[18:21], v[218:221], v[186:189], v[18:21]
	v_mfma_f32_16x16x32_bf16 v[6:9], v[206:209], v[198:201], v[6:9]
	v_mfma_f32_16x16x32_bf16 v[2:5], v[218:221], v[198:201], v[2:5]
	s_add_u32 s14, s14, 0x100
	s_addc_u32 s15, s15, 0
	s_cmp_ge_i32 s36, s34
	s_mov_b32 s16, s36
	s_barrier
	s_cbranch_scc0 .LBB0_153

; #define PG8_STAGE(bufoff, gbase, voff) do { _Pragma("unroll") for (int _i = 0; _i < 2; ++_i) \
;     __builtin_amdgcn_global_load_lds((const unsigned*)((const char*)(gbase) + (voff)[_i]), (LAS unsigned*)(lds + (bufoff) + ldsw + _i * 8192), 16, 0, 0); } while (0)
; #define PG8_LDA(dst, b, h) do { _Pragma("unroll") for (int m = 0; m < 4; ++m) _Pragma("unroll") for (int k = 0; k < 2; ++k) dst[m][k] = *(const LAS bf16x8*)(lds + PG8_SA(b, h) + aoff + m * 2048 + k * 1024); } while (0)
; #define PG8_LDB(dst, b, h) do { _Pragma("unroll") for (int n = 0; n < 2; ++n) _Pragma("unroll") for (int k = 0; k < 2; ++k) dst[n][k] = *(const LAS bf16x8*)(lds + PG8_SB(b, h) + boff + n * 2048 + k * 1024); } while (0)
; #define PG8_MMA(ai, bj, At, Bt) do { __builtin_amdgcn_s_setprio(1); _Pragma("unroll") for (int m = 0; m < 4; ++m) _Pragma("unroll") for (int n = 0; n < 2; ++n) _Pragma("unroll") for (int k = 0; k < 2; ++k) \
;     acc[ai][bj][m][n] = __builtin_amdgcn_mfma_f32_16x16x32_bf16(Bt[n][k], At[m][k], acc[ai][bj][m][n], 0, 0, 0); __builtin_amdgcn_s_setprio(0); } while (0)
; #define PG8_WAIT_L(n) asm volatile("s_waitcnt lgkmcnt(" #n ")" ::: "memory")
; #define PG8_BAR __builtin_amdgcn_s_barrier()
; #define PG8_SCHED __builtin_amdgcn_sched_barrier(0)
; template <class Epi, class Sched>
; DI void gemm_phase(LAS unsigned char* lds, const Gemm g, const Sched& S, const Epi& E) {
;     ...
;       const bool last = (t == nt - 2);
;       const char* a1 = cA + (size_t)(t + 1) * kstep;
;       const char* a2 = last ? nA : cA + (size_t)(t + 2) * kstep; const char* b2 = last ? nB : cB + (size_t)(t + 2) * kstep;
;       const char* a3 = a2 + kstep; const char* b3 = b2 + kstep;
;       PG8_LDB(B0, 0, 0); PG8_SCHED; PG8_LDA(At, 0, 0); PG8_STAGE(PG8_SA(1, 1), a1 + hstep, voffA);
;       PG8_WAIT_L(8); PG8_BAR; PG8_WAIT_L(0); PG8_MMA(0, 0, At, B0); PG8_BAR; PG8_SCHED;
;       PG8_LDB(B1, 0, 1); PG8_STAGE(PG8_SB(0, 0), b2, voffB);
;       PG8_BAR; PG8_WAIT_L(0); PG8_MMA(0, 1, At, B1); PG8_BAR;
;       PG8_LDA(At, 0, 1); PG8_STAGE(PG8_SA(0, 0), a2, voffA);
;       PG8_BAR; PG8_WAIT_L(0); PG8_MMA(1, 0, At, B0); PG8_BAR; PG8_SCHED;
.LBB0_178:
	s_add_i32 s51, s24, 2
	s_add_u32 s26, s22, 0x80
	s_addc_u32 s25, s23, 0
	s_add_i32 s52, 16, 0x10000
	v_add_u32_e32 v156, s52, v141
	ds_read_b128 v[144:147], v156
	ds_read_b128 v[148:151], v156 offset:1024
	ds_read_b128 v[152:155], v156 offset:2048
	ds_read_b128 v[156:159], v156 offset:3072
	s_cmp_eq_u32 s43, s24
	s_cselect_b32 s24, s18, s26
	s_cselect_b32 s25, s19, s25
	s_cselect_b32 s27, s21, s50
	s_cselect_b32 s26, s20, s49
	v_lshl_add_u64 v[176:177], s[22:23], 0, v[136:137]
	s_add_i32 m0, s36, 0xc000
	ds_read_b128 v[160:163], v143
	ds_read_b128 v[164:167], v143 offset:1024
	ds_read_b128 v[168:171], v143 offset:2048
	ds_read_b128 v[172:175], v143 offset:3072
	ds_read_b128 v[186:189], v143 offset:4096
	ds_read_b128 v[190:193], v143 offset:5120
	ds_read_b128 v[198:201], v143 offset:6144
	ds_read_b128 v[202:205], v143 offset:7168
	global_load_lds_dwordx4 v[176:177], off
	v_lshl_add_u64 v[176:177], s[22:23], 0, v[138:139]
	s_add_i32 m0, s36, 0xe000
	s_nop 0
	global_load_lds_dwordx4 v[176:177], off
	s_barrier
	s_waitcnt lgkmcnt(0)
	s_waitcnt lgkmcnt(0)
	v_mfma_f32_16x16x32_bf16 v[122:125], v[144:147], v[160:163], v[122:125]
	v_mfma_f32_16x16x32_bf16 v[118:121], v[152:155], v[160:163], v[118:121]
	v_mfma_f32_16x16x32_bf16 v[110:113], v[144:147], v[168:171], v[110:113]
	v_mfma_f32_16x16x32_bf16 v[102:105], v[152:155], v[168:171], v[102:105]
	v_mfma_f32_16x16x32_bf16 v[94:97], v[144:147], v[186:189], v[94:97]
	v_mfma_f32_16x16x32_bf16 v[86:89], v[152:155], v[186:189], v[86:89]
	v_mfma_f32_16x16x32_bf16 v[78:81], v[144:147], v[198:201], v[78:81]
	v_mfma_f32_16x16x32_bf16 v[70:73], v[152:155], v[198:201], v[70:73]
	v_mfma_f32_16x16x32_bf16 v[122:125], v[148:151], v[164:167], v[122:125]
	v_mfma_f32_16x16x32_bf16 v[118:121], v[156:159], v[164:167], v[118:121]
	v_mfma_f32_16x16x32_bf16 v[110:113], v[148:151], v[172:175], v[110:113]
	v_mfma_f32_16x16x32_bf16 v[102:105], v[156:159], v[172:175], v[102:105]
	v_mfma_f32_16x16x32_bf16 v[94:97], v[148:151], v[190:193], v[94:97]
	v_mfma_f32_16x16x32_bf16 v[86:89], v[156:159], v[190:193], v[86:89]
	v_mfma_f32_16x16x32_bf16 v[78:81], v[148:151], v[202:205], v[78:81]
	v_mfma_f32_16x16x32_bf16 v[70:73], v[156:159], v[202:205], v[70:73]
	s_barrier
	s_add_i32 s53, 16, 0x14000
	v_add_u32_e32 v176, s53, v141
	s_add_i32 s52, s52, s35
	ds_read_b128 v[206:209], v176
	ds_read_b128 v[214:217], v176 offset:1024
	ds_read_b128 v[218:221], v176 offset:2048
	ds_read_b128 v[222:225], v176 offset:3072
	v_lshl_add_u64 v[176:177], s[26:27], 0, v[0:1]
	s_mov_b32 m0, s52
	v_lshl_add_u64 v[180:181], s[26:27], 0, v[130:131]
	global_load_lds_dwordx4 v[176:177], off
	s_add_i32 m0, s52, 0x2000
	s_nop 0
	global_load_lds_dwordx4 v[180:181], off
	s_barrier
	s_waitcnt lgkmcnt(0)
	s_waitcnt lgkmcnt(0)
	v_mfma_f32_16x16x32_bf16 v[126:129], v[206:209], v[160:163], v[126:129]
	v_mfma_f32_16x16x32_bf16 v[114:117], v[218:221], v[160:163], v[114:117]
	v_mfma_f32_16x16x32_bf16 v[106:109], v[206:209], v[168:171], v[106:109]
	v_mfma_f32_16x16x32_bf16 v[98:101], v[218:221], v[168:171], v[98:101]
	v_mfma_f32_16x16x32_bf16 v[90:93], v[206:209], v[186:189], v[90:93]
	v_mfma_f32_16x16x32_bf16 v[82:85], v[218:221], v[186:189], v[82:85]
	v_mfma_f32_16x16x32_bf16 v[74:77], v[206:209], v[198:201], v[74:77]
	v_mfma_f32_16x16x32_bf16 v[66:69], v[218:221], v[198:201], v[66:69]
	v_mfma_f32_16x16x32_bf16 v[126:129], v[214:217], v[164:167], v[126:129]
	v_mfma_f32_16x16x32_bf16 v[114:117], v[222:225], v[164:167], v[114:117]
	v_mfma_f32_16x16x32_bf16 v[106:109], v[214:217], v[172:175], v[106:109]
	v_mfma_f32_16x16x32_bf16 v[98:101], v[222:225], v[172:175], v[98:101]
	v_mfma_f32_16x16x32_bf16 v[90:93], v[214:217], v[190:193], v[90:93]
	v_mfma_f32_16x16x32_bf16 v[82:85], v[222:225], v[190:193], v[82:85]
	v_mfma_f32_16x16x32_bf16 v[74:77], v[214:217], v[202:205], v[74:77]
	v_mfma_f32_16x16x32_bf16 v[66:69], v[222:225], v[202:205], v[66:69]
	s_mov_b32 m0, s36
	v_lshl_add_u64 v[182:183], s[24:25], 0, v[134:135]
	s_barrier
	ds_read_b128 v[160:163], v143 offset:16384
	ds_read_b128 v[164:167], v143 offset:17408
	ds_read_b128 v[168:171], v143 offset:18432
	ds_read_b128 v[172:175], v143 offset:19456
	ds_read_b128 v[186:189], v143 offset:20480
	ds_read_b128 v[190:193], v143 offset:21504
	ds_read_b128 v[198:201], v143 offset:22528
	ds_read_b128 v[202:205], v143 offset:23552
	global_load_lds_dwordx4 v[182:183], off
	v_lshl_add_u64 v[184:185], s[24:25], 0, v[132:133]
	s_mov_b32 m0, s37
	s_nop 0
	global_load_lds_dwordx4 v[184:185], off
	s_barrier
	s_waitcnt lgkmcnt(0)
	s_waitcnt lgkmcnt(0)
	v_mfma_f32_16x16x32_bf16 v[62:65], v[144:147], v[160:163], v[62:65]
	v_mfma_f32_16x16x32_bf16 v[54:57], v[152:155], v[160:163], v[54:57]
	v_mfma_f32_16x16x32_bf16 v[46:49], v[144:147], v[168:171], v[46:49]
	v_mfma_f32_16x16x32_bf16 v[38:41], v[152:155], v[168:171], v[38:41]
	v_mfma_f32_16x16x32_bf16 v[30:33], v[144:147], v[186:189], v[30:33]
	v_mfma_f32_16x16x32_bf16 v[22:25], v[152:155], v[186:189], v[22:25]
	v_mfma_f32_16x16x32_bf16 v[14:17], v[144:147], v[198:201], v[14:17]
	v_mfma_f32_16x16x32_bf16 v[6:9], v[152:155], v[198:201], v[6:9]
	v_mfma_f32_16x16x32_bf16 v[62:65], v[148:151], v[164:167], v[62:65]
	v_mfma_f32_16x16x32_bf16 v[54:57], v[156:159], v[164:167], v[54:57]
	v_mfma_f32_16x16x32_bf16 v[46:49], v[148:151], v[172:175], v[46:49]
	v_mfma_f32_16x16x32_bf16 v[38:41], v[156:159], v[172:175], v[38:41]
	v_mfma_f32_16x16x32_bf16 v[30:33], v[148:151], v[190:193], v[30:33]
	v_mfma_f32_16x16x32_bf16 v[22:25], v[156:159], v[190:193], v[22:25]
	v_mfma_f32_16x16x32_bf16 v[14:17], v[148:151], v[202:205], v[14:17]
	v_mfma_f32_16x16x32_bf16 v[6:9], v[156:159], v[202:205], v[6:9]
	s_barrier
; #define PG8_STAGE(bufoff, gbase, voff) do { _Pragma("unroll") for (int _i = 0; _i < 2; ++_i) \
;     __builtin_amdgcn_global_load_lds((const unsigned*)((const char*)(gbase) + (voff)[_i]), (LAS unsigned*)(lds + (bufoff) + ldsw + _i * 8192), 16, 0, 0); } while (0)
; #define PG8_LDA(dst, b, h) do { _Pragma("unroll") for (int m = 0; m < 4; ++m) _Pragma("unroll") for (int k = 0; k < 2; ++k) dst[m][k] = *(const LAS bf16x8*)(lds + PG8_SA(b, h) + aoff + m * 2048 + k * 1024); } while (0)
; #define PG8_LDB(dst, b, h) do { _Pragma("unroll") for (int n = 0; n < 2; ++n) _Pragma("unroll") for (int k = 0; k < 2; ++k) dst[n][k] = *(const LAS bf16x8*)(lds + PG8_SB(b, h) + boff + n * 2048 + k * 1024); } while (0)
; #define PG8_MMA(ai, bj, At, Bt) do { __builtin_amdgcn_s_setprio(1); _Pragma("unroll") for (int m = 0; m < 4; ++m) _Pragma("unroll") for (int n = 0; n < 2; ++n) _Pragma("unroll") for (int k = 0; k < 2; ++k) \
;     acc[ai][bj][m][n] = __builtin_amdgcn_mfma_f32_16x16x32_bf16(Bt[n][k], At[m][k], acc[ai][bj][m][n], 0, 0, 0); __builtin_amdgcn_s_setprio(0); } while (0)
; #define PG8_WAIT_V(n) asm volatile("s_waitcnt vmcnt(" #n ")" ::: "memory")
; #define PG8_WAIT_L(n) asm volatile("s_waitcnt lgkmcnt(" #n ")" ::: "memory")
; #define PG8_BAR __builtin_amdgcn_s_barrier()
; #define PG8_SCHED __builtin_amdgcn_sched_barrier(0)
; template <class Epi, class Sched>
; DI void gemm_phase(LAS unsigned char* lds, const Gemm g, const Sched& S, const Epi& E) {
;     ...
;       PG8_STAGE(PG8_SB(0, 1), b2 + hstepB, voffB);
;       PG8_WAIT_V(6); PG8_BAR; PG8_MMA(1, 1, At, B1); PG8_BAR;
;       PG8_LDB(B0, 1, 0); PG8_SCHED; PG8_LDA(At, 1, 0); PG8_STAGE(PG8_SA(0, 1), a2 + hstep, voffA);
;       PG8_WAIT_L(8); PG8_BAR; PG8_WAIT_L(0); PG8_MMA(0, 0, At, B0); PG8_BAR; PG8_SCHED;
;       PG8_LDB(B1, 1, 1); PG8_STAGE(PG8_SB(1, 0), b3, voffB);
;       PG8_BAR; PG8_WAIT_L(0); PG8_MMA(0, 1, At, B1); PG8_BAR;
	s_add_u32 s26, s26, s0
	s_addc_u32 s27, s27, s1
	s_add_i32 s52, s53, s35
	v_lshl_add_u64 v[226:227], s[26:27], 0, v[0:1]
	s_mov_b32 m0, s52
	v_lshl_add_u64 v[228:229], s[26:27], 0, v[130:131]
	global_load_lds_dwordx4 v[226:227], off
	s_add_i32 m0, s52, 0x2000
	s_nop 0
	global_load_lds_dwordx4 v[228:229], off
	s_waitcnt vmcnt(6)
	s_barrier
	v_mfma_f32_16x16x32_bf16 v[58:61], v[206:209], v[160:163], v[58:61]
	v_mfma_f32_16x16x32_bf16 v[50:53], v[218:221], v[160:163], v[50:53]
	v_mfma_f32_16x16x32_bf16 v[42:45], v[206:209], v[168:171], v[42:45]
	v_mfma_f32_16x16x32_bf16 v[34:37], v[218:221], v[168:171], v[34:37]
	v_mfma_f32_16x16x32_bf16 v[26:29], v[206:209], v[186:189], v[26:29]
	v_mfma_f32_16x16x32_bf16 v[18:21], v[218:221], v[186:189], v[18:21]
	v_mfma_f32_16x16x32_bf16 v[10:13], v[206:209], v[198:201], v[10:13]
	v_mfma_f32_16x16x32_bf16 v[2:5], v[218:221], v[198:201], v[2:5]
	v_mfma_f32_16x16x32_bf16 v[58:61], v[214:217], v[164:167], v[58:61]
	v_mfma_f32_16x16x32_bf16 v[50:53], v[222:225], v[164:167], v[50:53]
	v_mfma_f32_16x16x32_bf16 v[42:45], v[214:217], v[172:175], v[42:45]
	v_mfma_f32_16x16x32_bf16 v[34:37], v[222:225], v[172:175], v[34:37]
	v_mfma_f32_16x16x32_bf16 v[26:29], v[214:217], v[190:193], v[26:29]
	v_mfma_f32_16x16x32_bf16 v[18:21], v[222:225], v[190:193], v[18:21]
	v_mfma_f32_16x16x32_bf16 v[10:13], v[214:217], v[202:205], v[10:13]
	v_mfma_f32_16x16x32_bf16 v[2:5], v[222:225], v[202:205], v[2:5]
	s_add_i32 s26, 16, 0x18000
	v_add_u32_e32 v156, s26, v141
	s_barrier
	ds_read_b128 v[144:147], v156
	ds_read_b128 v[148:151], v156 offset:1024
	ds_read_b128 v[152:155], v156 offset:2048
	ds_read_b128 v[156:159], v156 offset:3072
	s_add_u32 s24, s24, s0
	s_addc_u32 s25, s25, s1
	s_mov_b32 m0, s38
	v_lshl_add_u64 v[206:207], s[24:25], 0, v[134:135]
	ds_read_b128 v[160:163], v143 offset:32768
	ds_read_b128 v[164:167], v143 offset:33792
	ds_read_b128 v[168:171], v143 offset:34816
	ds_read_b128 v[172:175], v143 offset:35840
	ds_read_b128 v[186:189], v143 offset:36864
	ds_read_b128 v[190:193], v143 offset:37888
	ds_read_b128 v[198:201], v143 offset:38912
	ds_read_b128 v[202:205], v143 offset:39936
	global_load_lds_dwordx4 v[206:207], off
	v_lshl_add_u64 v[206:207], s[24:25], 0, v[132:133]
	s_mov_b32 m0, s39
	s_nop 0
	global_load_lds_dwordx4 v[206:207], off
	s_barrier
	s_waitcnt lgkmcnt(0)
	s_waitcnt lgkmcnt(0)
	v_mfma_f32_16x16x32_bf16 v[122:125], v[144:147], v[160:163], v[122:125]
	v_mfma_f32_16x16x32_bf16 v[118:121], v[152:155], v[160:163], v[118:121]
	v_mfma_f32_16x16x32_bf16 v[110:113], v[144:147], v[168:171], v[110:113]
	v_mfma_f32_16x16x32_bf16 v[102:105], v[152:155], v[168:171], v[102:105]
	v_mfma_f32_16x16x32_bf16 v[94:97], v[144:147], v[186:189], v[94:97]
	v_mfma_f32_16x16x32_bf16 v[86:89], v[152:155], v[186:189], v[86:89]
	v_mfma_f32_16x16x32_bf16 v[78:81], v[144:147], v[198:201], v[78:81]
	v_mfma_f32_16x16x32_bf16 v[70:73], v[152:155], v[198:201], v[70:73]
	v_mfma_f32_16x16x32_bf16 v[122:125], v[148:151], v[164:167], v[122:125]
	v_mfma_f32_16x16x32_bf16 v[118:121], v[156:159], v[164:167], v[118:121]
	v_mfma_f32_16x16x32_bf16 v[110:113], v[148:151], v[172:175], v[110:113]
	v_mfma_f32_16x16x32_bf16 v[102:105], v[156:159], v[172:175], v[102:105]
	v_mfma_f32_16x16x32_bf16 v[94:97], v[148:151], v[190:193], v[94:97]
	v_mfma_f32_16x16x32_bf16 v[86:89], v[156:159], v[190:193], v[86:89]
	v_mfma_f32_16x16x32_bf16 v[78:81], v[148:151], v[202:205], v[78:81]
	v_mfma_f32_16x16x32_bf16 v[70:73], v[156:159], v[202:205], v[70:73]
	s_barrier
	s_add_i32 s24, 16, 0x1c000
	s_add_i32 s25, s26, s35
	v_add_u32_e32 v194, s24, v141
	v_lshl_add_u64 v[176:177], v[176:177], 0, s[70:71]
	s_mov_b32 m0, s25
	ds_read_b128 v[206:209], v194
	ds_read_b128 v[214:217], v194 offset:1024
	ds_read_b128 v[218:221], v194 offset:2048
	ds_read_b128 v[222:225], v194 offset:3072
	global_load_lds_dwordx4 v[176:177], off
	v_lshl_add_u64 v[176:177], v[180:181], 0, s[70:71]
	s_add_i32 m0, s25, 0x2000
	s_nop 0
	global_load_lds_dwordx4 v[176:177], off
	s_barrier
; #define PG8_STAGE(bufoff, gbase, voff) do { _Pragma("unroll") for (int _i = 0; _i < 2; ++_i) \
;     __builtin_amdgcn_global_load_lds((const unsigned*)((const char*)(gbase) + (voff)[_i]), (LAS unsigned*)(lds + (bufoff) + ldsw + _i * 8192), 16, 0, 0); } while (0)
; #define PG8_LDA(dst, b, h) do { _Pragma("unroll") for (int m = 0; m < 4; ++m) _Pragma("unroll") for (int k = 0; k < 2; ++k) dst[m][k] = *(const LAS bf16x8*)(lds + PG8_SA(b, h) + aoff + m * 2048 + k * 1024); } while (0)
; #define PG8_MMA(ai, bj, At, Bt) do { __builtin_amdgcn_s_setprio(1); _Pragma("unroll") for (int m = 0; m < 4; ++m) _Pragma("unroll") for (int n = 0; n < 2; ++n) _Pragma("unroll") for (int k = 0; k < 2; ++k) \
;     acc[ai][bj][m][n] = __builtin_amdgcn_mfma_f32_16x16x32_bf16(Bt[n][k], At[m][k], acc[ai][bj][m][n], 0, 0, 0); __builtin_amdgcn_s_setprio(0); } while (0)
; #define PG8_WAIT_V(n) asm volatile("s_waitcnt vmcnt(" #n ")" ::: "memory")
; #define PG8_WAIT_L(n) asm volatile("s_waitcnt lgkmcnt(" #n ")" ::: "memory")
; #define PG8_BAR __builtin_amdgcn_s_barrier()
; #define PG8_SCHED __builtin_amdgcn_sched_barrier(0)
; template <class Epi, class Sched>
; DI void gemm_phase(LAS unsigned char* lds, const Gemm g, const Sched& S, const Epi& E) {
;     ...
;       PG8_BAR; PG8_WAIT_L(0); PG8_MMA(0, 1, At, B1); PG8_BAR;
;       PG8_LDA(At, 1, 1); PG8_STAGE(PG8_SA(1, 0), a3, voffA);
;       PG8_BAR; PG8_WAIT_L(0); PG8_MMA(1, 0, At, B0); PG8_BAR; PG8_SCHED;
;       PG8_STAGE(PG8_SB(1, 1), b3 + hstepB, voffB);
;       PG8_WAIT_V(6); PG8_BAR; PG8_MMA(1, 1, At, B1); PG8_BAR;
;     }
	s_waitcnt lgkmcnt(0)
	s_waitcnt lgkmcnt(0)
	v_mfma_f32_16x16x32_bf16 v[126:129], v[206:209], v[160:163], v[126:129]
	v_mfma_f32_16x16x32_bf16 v[114:117], v[218:221], v[160:163], v[114:117]
	v_mfma_f32_16x16x32_bf16 v[106:109], v[206:209], v[168:171], v[106:109]
	v_mfma_f32_16x16x32_bf16 v[98:101], v[218:221], v[168:171], v[98:101]
	v_mfma_f32_16x16x32_bf16 v[90:93], v[206:209], v[186:189], v[90:93]
	v_mfma_f32_16x16x32_bf16 v[82:85], v[218:221], v[186:189], v[82:85]
	v_mfma_f32_16x16x32_bf16 v[74:77], v[206:209], v[198:201], v[74:77]
	v_mfma_f32_16x16x32_bf16 v[66:69], v[218:221], v[198:201], v[66:69]
	v_mfma_f32_16x16x32_bf16 v[126:129], v[214:217], v[164:167], v[126:129]
	v_mfma_f32_16x16x32_bf16 v[114:117], v[222:225], v[164:167], v[114:117]
	v_mfma_f32_16x16x32_bf16 v[106:109], v[214:217], v[172:175], v[106:109]
	v_mfma_f32_16x16x32_bf16 v[98:101], v[222:225], v[172:175], v[98:101]
	v_mfma_f32_16x16x32_bf16 v[90:93], v[214:217], v[190:193], v[90:93]
	v_mfma_f32_16x16x32_bf16 v[82:85], v[222:225], v[190:193], v[82:85]
	v_mfma_f32_16x16x32_bf16 v[74:77], v[214:217], v[202:205], v[74:77]
	v_mfma_f32_16x16x32_bf16 v[66:69], v[222:225], v[202:205], v[66:69]
	s_mov_b32 m0, s41
	v_lshl_add_u64 v[176:177], v[182:183], 0, s[70:71]
	s_barrier
	ds_read_b128 v[160:163], v143 offset:49152
	ds_read_b128 v[164:167], v143 offset:50176
	ds_read_b128 v[168:171], v143 offset:51200
	ds_read_b128 v[172:175], v143 offset:52224
	ds_read_b128 v[186:189], v143 offset:53248
	ds_read_b128 v[190:193], v143 offset:54272
	ds_read_b128 v[198:201], v143 offset:55296
	ds_read_b128 v[202:205], v143 offset:56320
	global_load_lds_dwordx4 v[176:177], off
	v_lshl_add_u64 v[176:177], v[184:185], 0, s[70:71]
	s_mov_b32 m0, s42
	s_nop 0
	global_load_lds_dwordx4 v[176:177], off
	s_barrier
	s_waitcnt lgkmcnt(0)
	s_waitcnt lgkmcnt(0)
	v_mfma_f32_16x16x32_bf16 v[62:65], v[144:147], v[160:163], v[62:65]
	v_mfma_f32_16x16x32_bf16 v[54:57], v[152:155], v[160:163], v[54:57]
	v_mfma_f32_16x16x32_bf16 v[46:49], v[144:147], v[168:171], v[46:49]
	v_mfma_f32_16x16x32_bf16 v[38:41], v[152:155], v[168:171], v[38:41]
	v_mfma_f32_16x16x32_bf16 v[30:33], v[144:147], v[186:189], v[30:33]
	v_mfma_f32_16x16x32_bf16 v[22:25], v[152:155], v[186:189], v[22:25]
	v_mfma_f32_16x16x32_bf16 v[14:17], v[144:147], v[198:201], v[14:17]
	v_mfma_f32_16x16x32_bf16 v[6:9], v[152:155], v[198:201], v[6:9]
	v_mfma_f32_16x16x32_bf16 v[62:65], v[148:151], v[164:167], v[62:65]
	v_mfma_f32_16x16x32_bf16 v[54:57], v[156:159], v[164:167], v[54:57]
	v_mfma_f32_16x16x32_bf16 v[46:49], v[148:151], v[172:175], v[46:49]
	v_mfma_f32_16x16x32_bf16 v[38:41], v[156:159], v[172:175], v[38:41]
	v_mfma_f32_16x16x32_bf16 v[30:33], v[148:151], v[190:193], v[30:33]
	v_mfma_f32_16x16x32_bf16 v[22:25], v[156:159], v[190:193], v[22:25]
	v_mfma_f32_16x16x32_bf16 v[14:17], v[148:151], v[202:205], v[14:17]
	v_mfma_f32_16x16x32_bf16 v[6:9], v[156:159], v[202:205], v[6:9]
	s_barrier
	s_add_i32 s24, s24, s35
	v_lshl_add_u64 v[144:145], v[226:227], 0, s[70:71]
	s_mov_b32 m0, s24
	s_nop 0
	global_load_lds_dwordx4 v[144:145], off
	v_lshl_add_u64 v[144:145], v[228:229], 0, s[70:71]
	s_add_i32 m0, s24, 0x2000
	s_nop 0
	global_load_lds_dwordx4 v[144:145], off
	s_waitcnt vmcnt(6)
	s_barrier
	v_mfma_f32_16x16x32_bf16 v[58:61], v[206:209], v[160:163], v[58:61]
	v_mfma_f32_16x16x32_bf16 v[50:53], v[218:221], v[160:163], v[50:53]
	v_mfma_f32_16x16x32_bf16 v[42:45], v[206:209], v[168:171], v[42:45]
	v_mfma_f32_16x16x32_bf16 v[34:37], v[218:221], v[168:171], v[34:37]
	v_mfma_f32_16x16x32_bf16 v[26:29], v[206:209], v[186:189], v[26:29]
	v_mfma_f32_16x16x32_bf16 v[18:21], v[218:221], v[186:189], v[18:21]
	v_mfma_f32_16x16x32_bf16 v[10:13], v[206:209], v[198:201], v[10:13]
	v_mfma_f32_16x16x32_bf16 v[2:5], v[218:221], v[198:201], v[2:5]
	v_mfma_f32_16x16x32_bf16 v[58:61], v[214:217], v[164:167], v[58:61]
	v_mfma_f32_16x16x32_bf16 v[50:53], v[222:225], v[164:167], v[50:53]
	v_mfma_f32_16x16x32_bf16 v[42:45], v[214:217], v[172:175], v[42:45]
	v_mfma_f32_16x16x32_bf16 v[34:37], v[222:225], v[172:175], v[34:37]
	v_mfma_f32_16x16x32_bf16 v[26:29], v[214:217], v[190:193], v[26:29]
	v_mfma_f32_16x16x32_bf16 v[18:21], v[222:225], v[190:193], v[18:21]
	v_mfma_f32_16x16x32_bf16 v[10:13], v[214:217], v[202:205], v[10:13]
	v_mfma_f32_16x16x32_bf16 v[2:5], v[222:225], v[202:205], v[2:5]
	s_add_u32 s22, s22, 0x100
	s_addc_u32 s23, s23, 0
	s_add_u32 s49, s49, 0x100
	s_addc_u32 s50, s50, 0
	s_cmp_ge_i32 s51, s40
	s_mov_b32 s24, s51
	s_barrier
	s_cbranch_scc0 .LBB0_178
	s_branch .LBB0_161

; #define PG8_STAGE(bufoff, gbase, voff) do { _Pragma("unroll") for (int _i = 0; _i < 2; ++_i) \
;     __builtin_amdgcn_global_load_lds((const unsigned*)((const char*)(gbase) + (voff)[_i]), (LAS unsigned*)(lds + (bufoff) + ldsw + _i * 8192), 16, 0, 0); } while (0)
; #define PG8_LDA(dst, b, h) do { _Pragma("unroll") for (int m = 0; m < 4; ++m) _Pragma("unroll") for (int k = 0; k < 2; ++k) dst[m][k] = *(const LAS bf16x8*)(lds + PG8_SA(b, h) + aoff + m * 2048 + k * 1024); } while (0)
; #define PG8_LDB(dst, b, h) do { _Pragma("unroll") for (int n = 0; n < 2; ++n) _Pragma("unroll") for (int k = 0; k < 2; ++k) dst[n][k] = *(const LAS bf16x8*)(lds + PG8_SB(b, h) + boff + n * 2048 + k * 1024); } while (0)
; #define PG8_MMA(ai, bj, At, Bt) do { __builtin_amdgcn_s_setprio(1); _Pragma("unroll") for (int m = 0; m < 4; ++m) _Pragma("unroll") for (int n = 0; n < 2; ++n) _Pragma("unroll") for (int k = 0; k < 2; ++k) \
;     acc[ai][bj][m][n] = __builtin_amdgcn_mfma_f32_16x16x32_bf16(Bt[n][k], At[m][k], acc[ai][bj][m][n], 0, 0, 0); __builtin_amdgcn_s_setprio(0); } while (0)
; #define PG8_WAIT_L(n) asm volatile("s_waitcnt lgkmcnt(" #n ")" ::: "memory")
; #define PG8_BAR __builtin_amdgcn_s_barrier()
; #define PG8_SCHED __builtin_amdgcn_sched_barrier(0)
; template <class Epi, class Sched>
; DI void gemm_phase(LAS unsigned char* lds, const Gemm g, const Sched& S, const Epi& E) {
;     ...
;       const bool last = (t == nt - 2);
;       const char* a1 = cA + (size_t)(t + 1) * kstep;
;       const char* a2 = last ? nA : cA + (size_t)(t + 2) * kstep; const char* b2 = last ? nB : cB + (size_t)(t + 2) * kstep;
;       const char* a3 = a2 + kstep; const char* b3 = b2 + kstep;
;       PG8_LDB(B0, 0, 0); PG8_SCHED; PG8_LDA(At, 0, 0); PG8_STAGE(PG8_SA(1, 1), a1 + hstep, voffA);
;       PG8_WAIT_L(8); PG8_BAR; PG8_WAIT_L(0); PG8_MMA(0, 0, At, B0); PG8_BAR; PG8_SCHED;
;       PG8_LDB(B1, 0, 1); PG8_STAGE(PG8_SB(0, 0), b2, voffB);
;       PG8_BAR; PG8_WAIT_L(0); PG8_MMA(0, 1, At, B1); PG8_BAR;
;       PG8_LDA(At, 0, 1); PG8_STAGE(PG8_SA(0, 0), a2, voffA);
;       PG8_BAR; PG8_WAIT_L(0); PG8_MMA(1, 0, At, B0); PG8_BAR; PG8_SCHED;
.LBB0_191:
	s_add_i32 s34, s16, 2
	s_add_u32 s17, s14, 0xfe000080
	s_addc_u32 s18, s15, -1
	s_cmp_lg_u32 s31, s16
	s_cselect_b32 s19, s18, 0
	s_cselect_b32 s18, s17, 0
	s_add_u32 s16, s12, s18
	s_addc_u32 s17, s13, s19
	s_add_i32 s35, 16, 0x10000
	v_add_u32_e32 v156, s35, v142
	ds_read_b128 v[144:147], v156
	ds_read_b128 v[148:151], v156 offset:1024
	ds_read_b128 v[152:155], v156 offset:2048
	ds_read_b128 v[156:159], v156 offset:3072
	s_add_u32 s18, s2, s18
	s_addc_u32 s19, s3, s19
	v_lshl_add_u64 v[176:177], v[136:137], 0, s[14:15]
	s_add_i32 m0, s23, 0xc000
	ds_read_b128 v[160:163], v143
	ds_read_b128 v[164:167], v143 offset:1024
	ds_read_b128 v[168:171], v143 offset:2048
	ds_read_b128 v[172:175], v143 offset:3072
	ds_read_b128 v[186:189], v143 offset:4096
	ds_read_b128 v[190:193], v143 offset:5120
	ds_read_b128 v[198:201], v143 offset:6144
	ds_read_b128 v[202:205], v143 offset:7168
	global_load_lds_dwordx4 v[176:177], off
	v_lshl_add_u64 v[176:177], v[138:139], 0, s[14:15]
	s_add_i32 m0, s23, 0xe000
	s_nop 0
	global_load_lds_dwordx4 v[176:177], off
	s_barrier
	s_waitcnt lgkmcnt(0)
	s_waitcnt lgkmcnt(0)
	v_mfma_f32_16x16x32_bf16 v[126:129], v[144:147], v[160:163], v[126:129]
	v_mfma_f32_16x16x32_bf16 v[118:121], v[152:155], v[160:163], v[118:121]
	v_mfma_f32_16x16x32_bf16 v[110:113], v[144:147], v[168:171], v[110:113]
	v_mfma_f32_16x16x32_bf16 v[102:105], v[152:155], v[168:171], v[102:105]
	v_mfma_f32_16x16x32_bf16 v[94:97], v[144:147], v[186:189], v[94:97]
	v_mfma_f32_16x16x32_bf16 v[86:89], v[152:155], v[186:189], v[86:89]
	v_mfma_f32_16x16x32_bf16 v[78:81], v[144:147], v[198:201], v[78:81]
	v_mfma_f32_16x16x32_bf16 v[70:73], v[152:155], v[198:201], v[70:73]
	v_mfma_f32_16x16x32_bf16 v[126:129], v[148:151], v[164:167], v[126:129]
	v_mfma_f32_16x16x32_bf16 v[118:121], v[156:159], v[164:167], v[118:121]
	v_mfma_f32_16x16x32_bf16 v[110:113], v[148:151], v[172:175], v[110:113]
	v_mfma_f32_16x16x32_bf16 v[102:105], v[156:159], v[172:175], v[102:105]
	v_mfma_f32_16x16x32_bf16 v[94:97], v[148:151], v[190:193], v[94:97]
	v_mfma_f32_16x16x32_bf16 v[86:89], v[156:159], v[190:193], v[86:89]
	v_mfma_f32_16x16x32_bf16 v[78:81], v[148:151], v[202:205], v[78:81]
	v_mfma_f32_16x16x32_bf16 v[70:73], v[156:159], v[202:205], v[70:73]
	s_barrier
	s_add_i32 s36, 16, 0x14000
	v_add_u32_e32 v176, s36, v142
	s_add_i32 s35, s35, s22
	ds_read_b128 v[206:209], v176
	ds_read_b128 v[214:217], v176 offset:1024
	ds_read_b128 v[218:221], v176 offset:2048
	ds_read_b128 v[222:225], v176 offset:3072
	v_lshl_add_u64 v[176:177], s[18:19], 0, v[0:1]
	s_mov_b32 m0, s35
	v_lshl_add_u64 v[180:181], s[18:19], 0, v[130:131]
	global_load_lds_dwordx4 v[176:177], off
	s_add_i32 m0, s35, 0x2000
	s_nop 0
	global_load_lds_dwordx4 v[180:181], off
	s_barrier
	s_waitcnt lgkmcnt(0)
	s_waitcnt lgkmcnt(0)
	v_mfma_f32_16x16x32_bf16 v[122:125], v[206:209], v[160:163], v[122:125]
	v_mfma_f32_16x16x32_bf16 v[114:117], v[218:221], v[160:163], v[114:117]
	v_mfma_f32_16x16x32_bf16 v[106:109], v[206:209], v[168:171], v[106:109]
	v_mfma_f32_16x16x32_bf16 v[98:101], v[218:221], v[168:171], v[98:101]
	v_mfma_f32_16x16x32_bf16 v[90:93], v[206:209], v[186:189], v[90:93]
	v_mfma_f32_16x16x32_bf16 v[82:85], v[218:221], v[186:189], v[82:85]
	v_mfma_f32_16x16x32_bf16 v[74:77], v[206:209], v[198:201], v[74:77]
	v_mfma_f32_16x16x32_bf16 v[66:69], v[218:221], v[198:201], v[66:69]
	v_mfma_f32_16x16x32_bf16 v[122:125], v[214:217], v[164:167], v[122:125]
	v_mfma_f32_16x16x32_bf16 v[114:117], v[222:225], v[164:167], v[114:117]
	v_mfma_f32_16x16x32_bf16 v[106:109], v[214:217], v[172:175], v[106:109]
	v_mfma_f32_16x16x32_bf16 v[98:101], v[222:225], v[172:175], v[98:101]
	v_mfma_f32_16x16x32_bf16 v[90:93], v[214:217], v[190:193], v[90:93]
	v_mfma_f32_16x16x32_bf16 v[82:85], v[222:225], v[190:193], v[82:85]
	v_mfma_f32_16x16x32_bf16 v[74:77], v[214:217], v[202:205], v[74:77]
	v_mfma_f32_16x16x32_bf16 v[66:69], v[222:225], v[202:205], v[66:69]
	s_mov_b32 m0, s23
	v_lshl_add_u64 v[182:183], s[16:17], 0, v[134:135]
	s_barrier
	ds_read_b128 v[160:163], v143 offset:16384
	ds_read_b128 v[164:167], v143 offset:17408
	ds_read_b128 v[168:171], v143 offset:18432
	ds_read_b128 v[172:175], v143 offset:19456
	ds_read_b128 v[186:189], v143 offset:20480
	ds_read_b128 v[190:193], v143 offset:21504
	ds_read_b128 v[198:201], v143 offset:22528
	ds_read_b128 v[202:205], v143 offset:23552
	global_load_lds_dwordx4 v[182:183], off
	v_lshl_add_u64 v[184:185], s[16:17], 0, v[132:133]
	s_mov_b32 m0, s24
	s_nop 0
	global_load_lds_dwordx4 v[184:185], off
	s_barrier
	s_waitcnt lgkmcnt(0)
	s_waitcnt lgkmcnt(0)
	v_mfma_f32_16x16x32_bf16 v[62:65], v[144:147], v[160:163], v[62:65]
	v_mfma_f32_16x16x32_bf16 v[54:57], v[152:155], v[160:163], v[54:57]
	v_mfma_f32_16x16x32_bf16 v[46:49], v[144:147], v[168:171], v[46:49]
	v_mfma_f32_16x16x32_bf16 v[38:41], v[152:155], v[168:171], v[38:41]
	v_mfma_f32_16x16x32_bf16 v[30:33], v[144:147], v[186:189], v[30:33]
	v_mfma_f32_16x16x32_bf16 v[22:25], v[152:155], v[186:189], v[22:25]
	v_mfma_f32_16x16x32_bf16 v[14:17], v[144:147], v[198:201], v[14:17]
	v_mfma_f32_16x16x32_bf16 v[6:9], v[152:155], v[198:201], v[6:9]
	v_mfma_f32_16x16x32_bf16 v[62:65], v[148:151], v[164:167], v[62:65]
	v_mfma_f32_16x16x32_bf16 v[54:57], v[156:159], v[164:167], v[54:57]
	v_mfma_f32_16x16x32_bf16 v[46:49], v[148:151], v[172:175], v[46:49]
	v_mfma_f32_16x16x32_bf16 v[38:41], v[156:159], v[172:175], v[38:41]
	v_mfma_f32_16x16x32_bf16 v[30:33], v[148:151], v[190:193], v[30:33]
	v_mfma_f32_16x16x32_bf16 v[22:25], v[156:159], v[190:193], v[22:25]
	v_mfma_f32_16x16x32_bf16 v[14:17], v[148:151], v[202:205], v[14:17]
	v_mfma_f32_16x16x32_bf16 v[6:9], v[156:159], v[202:205], v[6:9]
	s_barrier
; #define PG8_STAGE(bufoff, gbase, voff) do { _Pragma("unroll") for (int _i = 0; _i < 2; ++_i) \
;     __builtin_amdgcn_global_load_lds((const unsigned*)((const char*)(gbase) + (voff)[_i]), (LAS unsigned*)(lds + (bufoff) + ldsw + _i * 8192), 16, 0, 0); } while (0)
; #define PG8_LDA(dst, b, h) do { _Pragma("unroll") for (int m = 0; m < 4; ++m) _Pragma("unroll") for (int k = 0; k < 2; ++k) dst[m][k] = *(const LAS bf16x8*)(lds + PG8_SA(b, h) + aoff + m * 2048 + k * 1024); } while (0)
; #define PG8_LDB(dst, b, h) do { _Pragma("unroll") for (int n = 0; n < 2; ++n) _Pragma("unroll") for (int k = 0; k < 2; ++k) dst[n][k] = *(const LAS bf16x8*)(lds + PG8_SB(b, h) + boff + n * 2048 + k * 1024); } while (0)
; #define PG8_MMA(ai, bj, At, Bt) do { __builtin_amdgcn_s_setprio(1); _Pragma("unroll") for (int m = 0; m < 4; ++m) _Pragma("unroll") for (int n = 0; n < 2; ++n) _Pragma("unroll") for (int k = 0; k < 2; ++k) \
;     acc[ai][bj][m][n] = __builtin_amdgcn_mfma_f32_16x16x32_bf16(Bt[n][k], At[m][k], acc[ai][bj][m][n], 0, 0, 0); __builtin_amdgcn_s_setprio(0); } while (0)
; #define PG8_WAIT_V(n) asm volatile("s_waitcnt vmcnt(" #n ")" ::: "memory")
; #define PG8_WAIT_L(n) asm volatile("s_waitcnt lgkmcnt(" #n ")" ::: "memory")
; #define PG8_BAR __builtin_amdgcn_s_barrier()
; #define PG8_SCHED __builtin_amdgcn_sched_barrier(0)
; template <class Epi, class Sched>
; DI void gemm_phase(LAS unsigned char* lds, const Gemm g, const Sched& S, const Epi& E) {
;     ...
;       PG8_STAGE(PG8_SB(0, 1), b2 + hstepB, voffB);
;       PG8_WAIT_V(6); PG8_BAR; PG8_MMA(1, 1, At, B1); PG8_BAR;
;       PG8_LDB(B0, 1, 0); PG8_SCHED; PG8_LDA(At, 1, 0); PG8_STAGE(PG8_SA(0, 1), a2 + hstep, voffA);
;       PG8_WAIT_L(8); PG8_BAR; PG8_WAIT_L(0); PG8_MMA(0, 0, At, B0); PG8_BAR; PG8_SCHED;
;       PG8_LDB(B1, 1, 1); PG8_STAGE(PG8_SB(1, 0), b3, voffB);
;       PG8_BAR; PG8_WAIT_L(0); PG8_MMA(0, 1, At, B1); PG8_BAR;
	s_add_u32 s18, s18, s0
	s_addc_u32 s19, s19, s1
	s_add_i32 s35, s36, s22
	v_lshl_add_u64 v[226:227], s[18:19], 0, v[0:1]
	s_mov_b32 m0, s35
	v_lshl_add_u64 v[228:229], s[18:19], 0, v[130:131]
	global_load_lds_dwordx4 v[226:227], off
	s_add_i32 m0, s35, 0x2000
	s_nop 0
	global_load_lds_dwordx4 v[228:229], off
	s_waitcnt vmcnt(6)
	s_barrier
	v_mfma_f32_16x16x32_bf16 v[58:61], v[206:209], v[160:163], v[58:61]
	v_mfma_f32_16x16x32_bf16 v[50:53], v[218:221], v[160:163], v[50:53]
	v_mfma_f32_16x16x32_bf16 v[42:45], v[206:209], v[168:171], v[42:45]
	v_mfma_f32_16x16x32_bf16 v[34:37], v[218:221], v[168:171], v[34:37]
	v_mfma_f32_16x16x32_bf16 v[26:29], v[206:209], v[186:189], v[26:29]
	v_mfma_f32_16x16x32_bf16 v[18:21], v[218:221], v[186:189], v[18:21]
	v_mfma_f32_16x16x32_bf16 v[10:13], v[206:209], v[198:201], v[10:13]
	v_mfma_f32_16x16x32_bf16 v[2:5], v[218:221], v[198:201], v[2:5]
	v_mfma_f32_16x16x32_bf16 v[58:61], v[214:217], v[164:167], v[58:61]
	v_mfma_f32_16x16x32_bf16 v[50:53], v[222:225], v[164:167], v[50:53]
	v_mfma_f32_16x16x32_bf16 v[42:45], v[214:217], v[172:175], v[42:45]
	v_mfma_f32_16x16x32_bf16 v[34:37], v[222:225], v[172:175], v[34:37]
	v_mfma_f32_16x16x32_bf16 v[26:29], v[214:217], v[190:193], v[26:29]
	v_mfma_f32_16x16x32_bf16 v[18:21], v[222:225], v[190:193], v[18:21]
	v_mfma_f32_16x16x32_bf16 v[10:13], v[214:217], v[202:205], v[10:13]
	v_mfma_f32_16x16x32_bf16 v[2:5], v[222:225], v[202:205], v[2:5]
	s_add_i32 s18, 16, 0x18000
	v_add_u32_e32 v156, s18, v142
	s_barrier
	ds_read_b128 v[144:147], v156
	ds_read_b128 v[148:151], v156 offset:1024
	ds_read_b128 v[152:155], v156 offset:2048
	ds_read_b128 v[156:159], v156 offset:3072
	s_add_u32 s16, s16, s0
	s_addc_u32 s17, s17, s1
	s_mov_b32 m0, s25
	v_lshl_add_u64 v[206:207], s[16:17], 0, v[134:135]
	ds_read_b128 v[160:163], v143 offset:32768
	ds_read_b128 v[164:167], v143 offset:33792
	ds_read_b128 v[168:171], v143 offset:34816
	ds_read_b128 v[172:175], v143 offset:35840
	ds_read_b128 v[186:189], v143 offset:36864
	ds_read_b128 v[190:193], v143 offset:37888
	ds_read_b128 v[198:201], v143 offset:38912
	ds_read_b128 v[202:205], v143 offset:39936
	global_load_lds_dwordx4 v[206:207], off
	v_lshl_add_u64 v[206:207], s[16:17], 0, v[132:133]
	s_mov_b32 m0, s26
	s_nop 0
	global_load_lds_dwordx4 v[206:207], off
	s_barrier
	s_waitcnt lgkmcnt(0)
	s_waitcnt lgkmcnt(0)
	v_mfma_f32_16x16x32_bf16 v[126:129], v[144:147], v[160:163], v[126:129]
	v_mfma_f32_16x16x32_bf16 v[118:121], v[152:155], v[160:163], v[118:121]
	v_mfma_f32_16x16x32_bf16 v[110:113], v[144:147], v[168:171], v[110:113]
	v_mfma_f32_16x16x32_bf16 v[102:105], v[152:155], v[168:171], v[102:105]
	v_mfma_f32_16x16x32_bf16 v[94:97], v[144:147], v[186:189], v[94:97]
	v_mfma_f32_16x16x32_bf16 v[86:89], v[152:155], v[186:189], v[86:89]
	v_mfma_f32_16x16x32_bf16 v[78:81], v[144:147], v[198:201], v[78:81]
	v_mfma_f32_16x16x32_bf16 v[70:73], v[152:155], v[198:201], v[70:73]
	v_mfma_f32_16x16x32_bf16 v[126:129], v[148:151], v[164:167], v[126:129]
	v_mfma_f32_16x16x32_bf16 v[118:121], v[156:159], v[164:167], v[118:121]
	v_mfma_f32_16x16x32_bf16 v[110:113], v[148:151], v[172:175], v[110:113]
	v_mfma_f32_16x16x32_bf16 v[102:105], v[156:159], v[172:175], v[102:105]
	v_mfma_f32_16x16x32_bf16 v[94:97], v[148:151], v[190:193], v[94:97]
	v_mfma_f32_16x16x32_bf16 v[86:89], v[156:159], v[190:193], v[86:89]
	v_mfma_f32_16x16x32_bf16 v[78:81], v[148:151], v[202:205], v[78:81]
	v_mfma_f32_16x16x32_bf16 v[70:73], v[156:159], v[202:205], v[70:73]
	s_barrier
	s_add_i32 s16, 16, 0x1c000
	s_add_i32 s17, s18, s22
	v_add_u32_e32 v194, s16, v142
	v_lshl_add_u64 v[176:177], v[176:177], 0, s[70:71]
	s_mov_b32 m0, s17
	ds_read_b128 v[206:209], v194
	ds_read_b128 v[214:217], v194 offset:1024
	ds_read_b128 v[218:221], v194 offset:2048
	ds_read_b128 v[222:225], v194 offset:3072
	global_load_lds_dwordx4 v[176:177], off
	v_lshl_add_u64 v[176:177], v[180:181], 0, s[70:71]
	s_add_i32 m0, s17, 0x2000
	s_nop 0
	global_load_lds_dwordx4 v[176:177], off
	s_barrier
; #define PG8_STAGE(bufoff, gbase, voff) do { _Pragma("unroll") for (int _i = 0; _i < 2; ++_i) \
;     __builtin_amdgcn_global_load_lds((const unsigned*)((const char*)(gbase) + (voff)[_i]), (LAS unsigned*)(lds + (bufoff) + ldsw + _i * 8192), 16, 0, 0); } while (0)
; #define PG8_LDA(dst, b, h) do { _Pragma("unroll") for (int m = 0; m < 4; ++m) _Pragma("unroll") for (int k = 0; k < 2; ++k) dst[m][k] = *(const LAS bf16x8*)(lds + PG8_SA(b, h) + aoff + m * 2048 + k * 1024); } while (0)
; #define PG8_MMA(ai, bj, At, Bt) do { __builtin_amdgcn_s_setprio(1); _Pragma("unroll") for (int m = 0; m < 4; ++m) _Pragma("unroll") for (int n = 0; n < 2; ++n) _Pragma("unroll") for (int k = 0; k < 2; ++k) \
;     acc[ai][bj][m][n] = __builtin_amdgcn_mfma_f32_16x16x32_bf16(Bt[n][k], At[m][k], acc[ai][bj][m][n], 0, 0, 0); __builtin_amdgcn_s_setprio(0); } while (0)
; #define PG8_WAIT_V(n) asm volatile("s_waitcnt vmcnt(" #n ")" ::: "memory")
; #define PG8_WAIT_L(n) asm volatile("s_waitcnt lgkmcnt(" #n ")" ::: "memory")
; #define PG8_BAR __builtin_amdgcn_s_barrier()
; #define PG8_SCHED __builtin_amdgcn_sched_barrier(0)
; template <class Epi, class Sched>
; DI void gemm_phase(LAS unsigned char* lds, const Gemm g, const Sched& S, const Epi& E) {
;     ...
;       PG8_BAR; PG8_WAIT_L(0); PG8_MMA(0, 1, At, B1); PG8_BAR;
;       PG8_LDA(At, 1, 1); PG8_STAGE(PG8_SA(1, 0), a3, voffA);
;       PG8_BAR; PG8_WAIT_L(0); PG8_MMA(1, 0, At, B0); PG8_BAR; PG8_SCHED;
;       PG8_STAGE(PG8_SB(1, 1), b3 + hstepB, voffB);
;       PG8_WAIT_V(6); PG8_BAR; PG8_MMA(1, 1, At, B1); PG8_BAR;
	s_waitcnt lgkmcnt(0)
	s_waitcnt lgkmcnt(0)
	v_mfma_f32_16x16x32_bf16 v[122:125], v[206:209], v[160:163], v[122:125]
	v_mfma_f32_16x16x32_bf16 v[114:117], v[218:221], v[160:163], v[114:117]
	v_mfma_f32_16x16x32_bf16 v[106:109], v[206:209], v[168:171], v[106:109]
	v_mfma_f32_16x16x32_bf16 v[98:101], v[218:221], v[168:171], v[98:101]
	v_mfma_f32_16x16x32_bf16 v[90:93], v[206:209], v[186:189], v[90:93]
	v_mfma_f32_16x16x32_bf16 v[82:85], v[218:221], v[186:189], v[82:85]
	v_mfma_f32_16x16x32_bf16 v[74:77], v[206:209], v[198:201], v[74:77]
	v_mfma_f32_16x16x32_bf16 v[66:69], v[218:221], v[198:201], v[66:69]
	v_mfma_f32_16x16x32_bf16 v[122:125], v[214:217], v[164:167], v[122:125]
	v_mfma_f32_16x16x32_bf16 v[114:117], v[222:225], v[164:167], v[114:117]
	v_mfma_f32_16x16x32_bf16 v[106:109], v[214:217], v[172:175], v[106:109]
	v_mfma_f32_16x16x32_bf16 v[98:101], v[222:225], v[172:175], v[98:101]
	v_mfma_f32_16x16x32_bf16 v[90:93], v[214:217], v[190:193], v[90:93]
	v_mfma_f32_16x16x32_bf16 v[82:85], v[222:225], v[190:193], v[82:85]
	v_mfma_f32_16x16x32_bf16 v[74:77], v[214:217], v[202:205], v[74:77]
	v_mfma_f32_16x16x32_bf16 v[66:69], v[222:225], v[202:205], v[66:69]
	s_mov_b32 m0, s27
	v_lshl_add_u64 v[176:177], v[182:183], 0, s[70:71]
	s_barrier
	ds_read_b128 v[160:163], v143 offset:49152
	ds_read_b128 v[164:167], v143 offset:50176
	ds_read_b128 v[168:171], v143 offset:51200
	ds_read_b128 v[172:175], v143 offset:52224
	ds_read_b128 v[186:189], v143 offset:53248
	ds_read_b128 v[190:193], v143 offset:54272
	ds_read_b128 v[198:201], v143 offset:55296
	ds_read_b128 v[202:205], v143 offset:56320
	global_load_lds_dwordx4 v[176:177], off
	v_lshl_add_u64 v[176:177], v[184:185], 0, s[70:71]
	s_mov_b32 m0, s29
	s_nop 0
	global_load_lds_dwordx4 v[176:177], off
	s_barrier
	s_waitcnt lgkmcnt(0)
	s_waitcnt lgkmcnt(0)
	v_mfma_f32_16x16x32_bf16 v[62:65], v[144:147], v[160:163], v[62:65]
	v_mfma_f32_16x16x32_bf16 v[54:57], v[152:155], v[160:163], v[54:57]
	v_mfma_f32_16x16x32_bf16 v[46:49], v[144:147], v[168:171], v[46:49]
	v_mfma_f32_16x16x32_bf16 v[38:41], v[152:155], v[168:171], v[38:41]
	v_mfma_f32_16x16x32_bf16 v[30:33], v[144:147], v[186:189], v[30:33]
	v_mfma_f32_16x16x32_bf16 v[22:25], v[152:155], v[186:189], v[22:25]
	v_mfma_f32_16x16x32_bf16 v[14:17], v[144:147], v[198:201], v[14:17]
	v_mfma_f32_16x16x32_bf16 v[6:9], v[152:155], v[198:201], v[6:9]
	v_mfma_f32_16x16x32_bf16 v[62:65], v[148:151], v[164:167], v[62:65]
	v_mfma_f32_16x16x32_bf16 v[54:57], v[156:159], v[164:167], v[54:57]
	v_mfma_f32_16x16x32_bf16 v[46:49], v[148:151], v[172:175], v[46:49]
	v_mfma_f32_16x16x32_bf16 v[38:41], v[156:159], v[172:175], v[38:41]
	v_mfma_f32_16x16x32_bf16 v[30:33], v[148:151], v[190:193], v[30:33]
	v_mfma_f32_16x16x32_bf16 v[22:25], v[156:159], v[190:193], v[22:25]
	v_mfma_f32_16x16x32_bf16 v[14:17], v[148:151], v[202:205], v[14:17]
	v_mfma_f32_16x16x32_bf16 v[6:9], v[156:159], v[202:205], v[6:9]
	s_barrier
	s_add_i32 s16, s16, s22
	v_lshl_add_u64 v[144:145], v[226:227], 0, s[70:71]
	s_mov_b32 m0, s16
	s_nop 0
	global_load_lds_dwordx4 v[144:145], off
	v_lshl_add_u64 v[144:145], v[228:229], 0, s[70:71]
	s_add_i32 m0, s16, 0x2000
	s_nop 0
	global_load_lds_dwordx4 v[144:145], off
	s_waitcnt vmcnt(6)
	s_barrier
	v_mfma_f32_16x16x32_bf16 v[58:61], v[206:209], v[160:163], v[58:61]
	v_mfma_f32_16x16x32_bf16 v[50:53], v[218:221], v[160:163], v[50:53]
	v_mfma_f32_16x16x32_bf16 v[42:45], v[206:209], v[168:171], v[42:45]
	v_mfma_f32_16x16x32_bf16 v[34:37], v[218:221], v[168:171], v[34:37]
	v_mfma_f32_16x16x32_bf16 v[26:29], v[206:209], v[186:189], v[26:29]
	v_mfma_f32_16x16x32_bf16 v[18:21], v[218:221], v[186:189], v[18:21]
	v_mfma_f32_16x16x32_bf16 v[10:13], v[206:209], v[198:201], v[10:13]
	v_mfma_f32_16x16x32_bf16 v[2:5], v[218:221], v[198:201], v[2:5]
	v_mfma_f32_16x16x32_bf16 v[58:61], v[214:217], v[164:167], v[58:61]
	v_mfma_f32_16x16x32_bf16 v[50:53], v[222:225], v[164:167], v[50:53]
	v_mfma_f32_16x16x32_bf16 v[42:45], v[214:217], v[172:175], v[42:45]
	v_mfma_f32_16x16x32_bf16 v[34:37], v[222:225], v[172:175], v[34:37]
	v_mfma_f32_16x16x32_bf16 v[26:29], v[214:217], v[190:193], v[26:29]
	v_mfma_f32_16x16x32_bf16 v[18:21], v[222:225], v[190:193], v[18:21]
	v_mfma_f32_16x16x32_bf16 v[10:13], v[214:217], v[202:205], v[10:13]
	v_mfma_f32_16x16x32_bf16 v[2:5], v[222:225], v[202:205], v[2:5]
	s_add_u32 s14, s14, 0x100
	s_addc_u32 s15, s15, 0
	s_cmp_ge_i32 s34, s30
	s_mov_b32 s16, s34
	s_barrier
	s_cbranch_scc0 .LBB0_191

; #define PG8_STAGE(bufoff, gbase, voff) do { _Pragma("unroll") for (int _i = 0; _i < 2; ++_i) \
;     __builtin_amdgcn_global_load_lds((const unsigned*)((const char*)(gbase) + (voff)[_i]), (LAS unsigned*)(lds + (bufoff) + ldsw + _i * 8192), 16, 0, 0); } while (0)
; #define PG8_LDA(dst, b, h) do { _Pragma("unroll") for (int m = 0; m < 4; ++m) _Pragma("unroll") for (int k = 0; k < 2; ++k) dst[m][k] = *(const LAS bf16x8*)(lds + PG8_SA(b, h) + aoff + m * 2048 + k * 1024); } while (0)
; #define PG8_LDB(dst, b, h) do { _Pragma("unroll") for (int n = 0; n < 2; ++n) _Pragma("unroll") for (int k = 0; k < 2; ++k) dst[n][k] = *(const LAS bf16x8*)(lds + PG8_SB(b, h) + boff + n * 2048 + k * 1024); } while (0)
; #define PG8_MMA(ai, bj, At, Bt) do { __builtin_amdgcn_s_setprio(1); _Pragma("unroll") for (int m = 0; m < 4; ++m) _Pragma("unroll") for (int n = 0; n < 2; ++n) _Pragma("unroll") for (int k = 0; k < 2; ++k) \
;     acc[ai][bj][m][n] = __builtin_amdgcn_mfma_f32_16x16x32_bf16(Bt[n][k], At[m][k], acc[ai][bj][m][n], 0, 0, 0); __builtin_amdgcn_s_setprio(0); } while (0)
; #define PG8_WAIT_L(n) asm volatile("s_waitcnt lgkmcnt(" #n ")" ::: "memory")
; #define PG8_BAR __builtin_amdgcn_s_barrier()
; #define PG8_SCHED __builtin_amdgcn_sched_barrier(0)
; template <class Epi, class Sched>
; DI void gemm_phase(LAS unsigned char* lds, const Gemm g, const Sched& S, const Epi& E) {
;     ...
;       const bool last = (t == nt - 2);
;       const char* a1 = cA + (size_t)(t + 1) * kstep;
;       const char* a2 = last ? nA : cA + (size_t)(t + 2) * kstep; const char* b2 = last ? nB : cB + (size_t)(t + 2) * kstep;
;       const char* a3 = a2 + kstep; const char* b3 = b2 + kstep;
;       PG8_LDB(B0, 0, 0); PG8_SCHED; PG8_LDA(At, 0, 0); PG8_STAGE(PG8_SA(1, 1), a1 + hstep, voffA);
;       PG8_WAIT_L(8); PG8_BAR; PG8_WAIT_L(0); PG8_MMA(0, 0, At, B0); PG8_BAR; PG8_SCHED;
;       PG8_LDB(B1, 0, 1); PG8_STAGE(PG8_SB(0, 0), b2, voffB);
;       PG8_BAR; PG8_WAIT_L(0); PG8_MMA(0, 1, At, B1); PG8_BAR;
;       PG8_LDA(At, 0, 1); PG8_STAGE(PG8_SA(0, 0), a2, voffA);
;       PG8_BAR; PG8_WAIT_L(0); PG8_MMA(1, 0, At, B0); PG8_BAR; PG8_SCHED;
.LBB0_217:
	s_add_i32 s40, s3, 2
	s_add_u32 s18, s16, 0x80
	s_addc_u32 s19, s17, 0
	s_cmp_lg_u32 s39, s3
	s_cselect_b32 s20, s18, 0
	s_cselect_b32 s3, s19, 0
	s_add_u32 s18, s14, s20
	s_addc_u32 s19, s15, s3
	s_add_i32 s41, 16, 0x10000
	v_add_u32_e32 v139, s41, v137
	ds_read_b128 v[140:143], v139
	ds_read_b128 v[148:151], v139 offset:1024
	ds_read_b128 v[152:155], v139 offset:2048
	ds_read_b128 v[156:159], v139 offset:3072
	s_add_u32 s20, s12, s20
	s_addc_u32 s21, s13, s3
	v_lshl_add_u64 v[144:145], v[132:133], 0, s[16:17]
	s_add_i32 m0, s30, 0xc000
	ds_read_b128 v[160:163], v138
	ds_read_b128 v[164:167], v138 offset:1024
	ds_read_b128 v[168:171], v138 offset:2048
	ds_read_b128 v[172:175], v138 offset:3072
	ds_read_b128 v[186:189], v138 offset:4096
	ds_read_b128 v[190:193], v138 offset:5120
	ds_read_b128 v[198:201], v138 offset:6144
	ds_read_b128 v[202:205], v138 offset:7168
	global_load_lds_dwordx4 v[144:145], off
	v_lshl_add_u64 v[144:145], v[134:135], 0, s[16:17]
	s_add_i32 m0, s30, 0xe000
	s_nop 0
	global_load_lds_dwordx4 v[144:145], off
	s_barrier
	s_waitcnt lgkmcnt(0)
	s_waitcnt lgkmcnt(0)
	v_mfma_f32_16x16x32_bf16 v[126:129], v[140:143], v[160:163], v[126:129]
	v_mfma_f32_16x16x32_bf16 v[122:125], v[152:155], v[160:163], v[122:125]
	v_mfma_f32_16x16x32_bf16 v[110:113], v[140:143], v[168:171], v[110:113]
	v_mfma_f32_16x16x32_bf16 v[106:109], v[152:155], v[168:171], v[106:109]
	v_mfma_f32_16x16x32_bf16 v[94:97], v[140:143], v[186:189], v[94:97]
	v_mfma_f32_16x16x32_bf16 v[90:93], v[152:155], v[186:189], v[90:93]
	v_mfma_f32_16x16x32_bf16 v[78:81], v[140:143], v[198:201], v[78:81]
	v_mfma_f32_16x16x32_bf16 v[74:77], v[152:155], v[198:201], v[74:77]
	v_mfma_f32_16x16x32_bf16 v[126:129], v[148:151], v[164:167], v[126:129]
	v_mfma_f32_16x16x32_bf16 v[122:125], v[156:159], v[164:167], v[122:125]
	v_mfma_f32_16x16x32_bf16 v[110:113], v[148:151], v[172:175], v[110:113]
	v_mfma_f32_16x16x32_bf16 v[106:109], v[156:159], v[172:175], v[106:109]
	v_mfma_f32_16x16x32_bf16 v[94:97], v[148:151], v[190:193], v[94:97]
	v_mfma_f32_16x16x32_bf16 v[90:93], v[156:159], v[190:193], v[90:93]
	v_mfma_f32_16x16x32_bf16 v[78:81], v[148:151], v[202:205], v[78:81]
	v_mfma_f32_16x16x32_bf16 v[74:77], v[156:159], v[202:205], v[74:77]
	s_barrier
	s_add_i32 s3, 16, 0x14000
	s_add_i32 s41, s41, s29
	v_add_u32_e32 v139, s3, v137
	v_lshl_add_u64 v[144:145], s[20:21], 0, v[0:1]
	s_mov_b32 m0, s41
	ds_read_b128 v[206:209], v139
	ds_read_b128 v[214:217], v139 offset:1024
	ds_read_b128 v[218:221], v139 offset:2048
	ds_read_b128 v[222:225], v139 offset:3072
	global_load_lds_dwordx4 v[144:145], off
	v_lshl_add_u64 v[176:177], s[20:21], 0, v[130:131]
	s_add_i32 m0, s41, 0x2000
	s_nop 0
	global_load_lds_dwordx4 v[176:177], off
	s_barrier
	s_waitcnt lgkmcnt(0)
	s_waitcnt lgkmcnt(0)
	v_mfma_f32_16x16x32_bf16 v[118:121], v[206:209], v[160:163], v[118:121]
	v_mfma_f32_16x16x32_bf16 v[114:117], v[218:221], v[160:163], v[114:117]
	v_mfma_f32_16x16x32_bf16 v[102:105], v[206:209], v[168:171], v[102:105]
	v_mfma_f32_16x16x32_bf16 v[98:101], v[218:221], v[168:171], v[98:101]
	v_mfma_f32_16x16x32_bf16 v[86:89], v[206:209], v[186:189], v[86:89]
	v_mfma_f32_16x16x32_bf16 v[82:85], v[218:221], v[186:189], v[82:85]
	v_mfma_f32_16x16x32_bf16 v[70:73], v[206:209], v[198:201], v[70:73]
	v_mfma_f32_16x16x32_bf16 v[66:69], v[218:221], v[198:201], v[66:69]
	v_mfma_f32_16x16x32_bf16 v[118:121], v[214:217], v[164:167], v[118:121]
	v_mfma_f32_16x16x32_bf16 v[114:117], v[222:225], v[164:167], v[114:117]
	v_mfma_f32_16x16x32_bf16 v[102:105], v[214:217], v[172:175], v[102:105]
	v_mfma_f32_16x16x32_bf16 v[98:101], v[222:225], v[172:175], v[98:101]
	v_mfma_f32_16x16x32_bf16 v[86:89], v[214:217], v[190:193], v[86:89]
	v_mfma_f32_16x16x32_bf16 v[82:85], v[222:225], v[190:193], v[82:85]
	v_mfma_f32_16x16x32_bf16 v[70:73], v[214:217], v[202:205], v[70:73]
	v_mfma_f32_16x16x32_bf16 v[66:69], v[222:225], v[202:205], v[66:69]
	s_mov_b32 m0, s30
	v_lshl_add_u64 v[180:181], s[18:19], 0, v[0:1]
	s_barrier
	ds_read_b128 v[160:163], v138 offset:16384
	ds_read_b128 v[164:167], v138 offset:17408
	ds_read_b128 v[168:171], v138 offset:18432
	ds_read_b128 v[172:175], v138 offset:19456
	ds_read_b128 v[186:189], v138 offset:20480
	ds_read_b128 v[190:193], v138 offset:21504
	ds_read_b128 v[198:201], v138 offset:22528
	ds_read_b128 v[202:205], v138 offset:23552
	global_load_lds_dwordx4 v[180:181], off
	v_lshl_add_u64 v[182:183], s[18:19], 0, v[130:131]
	s_mov_b32 m0, s31
	s_nop 0
	global_load_lds_dwordx4 v[182:183], off
	s_barrier
	s_waitcnt lgkmcnt(0)
	s_waitcnt lgkmcnt(0)
	v_mfma_f32_16x16x32_bf16 v[62:65], v[140:143], v[160:163], v[62:65]
	v_mfma_f32_16x16x32_bf16 v[58:61], v[152:155], v[160:163], v[58:61]
	v_mfma_f32_16x16x32_bf16 v[50:53], v[140:143], v[168:171], v[50:53]
	v_mfma_f32_16x16x32_bf16 v[42:45], v[152:155], v[168:171], v[42:45]
	v_mfma_f32_16x16x32_bf16 v[34:37], v[140:143], v[186:189], v[34:37]
	v_mfma_f32_16x16x32_bf16 v[26:29], v[152:155], v[186:189], v[26:29]
	v_mfma_f32_16x16x32_bf16 v[14:17], v[140:143], v[198:201], v[14:17]
	v_mfma_f32_16x16x32_bf16 v[10:13], v[152:155], v[198:201], v[10:13]
	v_mfma_f32_16x16x32_bf16 v[62:65], v[148:151], v[164:167], v[62:65]
	v_mfma_f32_16x16x32_bf16 v[58:61], v[156:159], v[164:167], v[58:61]
	v_mfma_f32_16x16x32_bf16 v[50:53], v[148:151], v[172:175], v[50:53]
	v_mfma_f32_16x16x32_bf16 v[42:45], v[156:159], v[172:175], v[42:45]
	v_mfma_f32_16x16x32_bf16 v[34:37], v[148:151], v[190:193], v[34:37]
	v_mfma_f32_16x16x32_bf16 v[26:29], v[156:159], v[190:193], v[26:29]
	v_mfma_f32_16x16x32_bf16 v[14:17], v[148:151], v[202:205], v[14:17]
	v_mfma_f32_16x16x32_bf16 v[10:13], v[156:159], v[202:205], v[10:13]
	s_barrier
; #define PG8_STAGE(bufoff, gbase, voff) do { _Pragma("unroll") for (int _i = 0; _i < 2; ++_i) \
;     __builtin_amdgcn_global_load_lds((const unsigned*)((const char*)(gbase) + (voff)[_i]), (LAS unsigned*)(lds + (bufoff) + ldsw + _i * 8192), 16, 0, 0); } while (0)
; #define PG8_LDA(dst, b, h) do { _Pragma("unroll") for (int m = 0; m < 4; ++m) _Pragma("unroll") for (int k = 0; k < 2; ++k) dst[m][k] = *(const LAS bf16x8*)(lds + PG8_SA(b, h) + aoff + m * 2048 + k * 1024); } while (0)
; #define PG8_LDB(dst, b, h) do { _Pragma("unroll") for (int n = 0; n < 2; ++n) _Pragma("unroll") for (int k = 0; k < 2; ++k) dst[n][k] = *(const LAS bf16x8*)(lds + PG8_SB(b, h) + boff + n * 2048 + k * 1024); } while (0)
; #define PG8_MMA(ai, bj, At, Bt) do { __builtin_amdgcn_s_setprio(1); _Pragma("unroll") for (int m = 0; m < 4; ++m) _Pragma("unroll") for (int n = 0; n < 2; ++n) _Pragma("unroll") for (int k = 0; k < 2; ++k) \
;     acc[ai][bj][m][n] = __builtin_amdgcn_mfma_f32_16x16x32_bf16(Bt[n][k], At[m][k], acc[ai][bj][m][n], 0, 0, 0); __builtin_amdgcn_s_setprio(0); } while (0)
; #define PG8_WAIT_V(n) asm volatile("s_waitcnt vmcnt(" #n ")" ::: "memory")
; #define PG8_WAIT_L(n) asm volatile("s_waitcnt lgkmcnt(" #n ")" ::: "memory")
; #define PG8_BAR __builtin_amdgcn_s_barrier()
; #define PG8_SCHED __builtin_amdgcn_sched_barrier(0)
; template <class Epi, class Sched>
; DI void gemm_phase(LAS unsigned char* lds, const Gemm g, const Sched& S, const Epi& E) {
;     ...
;       PG8_STAGE(PG8_SB(0, 1), b2 + hstepB, voffB);
;       PG8_WAIT_V(6); PG8_BAR; PG8_MMA(1, 1, At, B1); PG8_BAR;
;       PG8_LDB(B0, 1, 0); PG8_SCHED; PG8_LDA(At, 1, 0); PG8_STAGE(PG8_SA(0, 1), a2 + hstep, voffA);
;       PG8_WAIT_L(8); PG8_BAR; PG8_WAIT_L(0); PG8_MMA(0, 0, At, B0); PG8_BAR; PG8_SCHED;
;       PG8_LDB(B1, 1, 1); PG8_STAGE(PG8_SB(1, 0), b3, voffB);
;       PG8_BAR; PG8_WAIT_L(0); PG8_MMA(0, 1, At, B1); PG8_BAR;
	s_add_u32 s20, s20, s10
	s_addc_u32 s21, s21, s11
	s_add_i32 s3, s3, s29
	v_lshl_add_u64 v[184:185], s[20:21], 0, v[0:1]
	s_mov_b32 m0, s3
	v_lshl_add_u64 v[226:227], s[20:21], 0, v[130:131]
	global_load_lds_dwordx4 v[184:185], off
	s_add_i32 m0, s3, 0x2000
	s_nop 0
	global_load_lds_dwordx4 v[226:227], off
	s_waitcnt vmcnt(6)
	s_barrier
	v_mfma_f32_16x16x32_bf16 v[54:57], v[206:209], v[160:163], v[54:57]
	v_mfma_f32_16x16x32_bf16 v[46:49], v[218:221], v[160:163], v[46:49]
	v_mfma_f32_16x16x32_bf16 v[38:41], v[206:209], v[168:171], v[38:41]
	v_mfma_f32_16x16x32_bf16 v[30:33], v[218:221], v[168:171], v[30:33]
	v_mfma_f32_16x16x32_bf16 v[22:25], v[206:209], v[186:189], v[22:25]
	v_mfma_f32_16x16x32_bf16 v[18:21], v[218:221], v[186:189], v[18:21]
	v_mfma_f32_16x16x32_bf16 v[6:9], v[206:209], v[198:201], v[6:9]
	v_mfma_f32_16x16x32_bf16 v[2:5], v[218:221], v[198:201], v[2:5]
	v_mfma_f32_16x16x32_bf16 v[54:57], v[214:217], v[164:167], v[54:57]
	v_mfma_f32_16x16x32_bf16 v[46:49], v[222:225], v[164:167], v[46:49]
	v_mfma_f32_16x16x32_bf16 v[38:41], v[214:217], v[172:175], v[38:41]
	v_mfma_f32_16x16x32_bf16 v[30:33], v[222:225], v[172:175], v[30:33]
	v_mfma_f32_16x16x32_bf16 v[22:25], v[214:217], v[190:193], v[22:25]
	v_mfma_f32_16x16x32_bf16 v[18:21], v[222:225], v[190:193], v[18:21]
	v_mfma_f32_16x16x32_bf16 v[6:9], v[214:217], v[202:205], v[6:9]
	v_mfma_f32_16x16x32_bf16 v[2:5], v[222:225], v[202:205], v[2:5]
	s_add_i32 s3, 16, 0x18000
	v_add_u32_e32 v139, s3, v137
	s_barrier
	ds_read_b128 v[140:143], v139
	ds_read_b128 v[148:151], v139 offset:1024
	ds_read_b128 v[152:155], v139 offset:2048
	ds_read_b128 v[156:159], v139 offset:3072
	s_add_u32 s18, s18, s10
	s_addc_u32 s19, s19, s11
	s_mov_b32 m0, s34
	v_lshl_add_u64 v[206:207], s[18:19], 0, v[0:1]
	ds_read_b128 v[160:163], v138 offset:32768
	ds_read_b128 v[164:167], v138 offset:33792
	ds_read_b128 v[168:171], v138 offset:34816
	ds_read_b128 v[172:175], v138 offset:35840
	ds_read_b128 v[186:189], v138 offset:36864
	ds_read_b128 v[190:193], v138 offset:37888
	ds_read_b128 v[198:201], v138 offset:38912
	ds_read_b128 v[202:205], v138 offset:39936
	global_load_lds_dwordx4 v[206:207], off
	v_lshl_add_u64 v[206:207], s[18:19], 0, v[130:131]
	s_mov_b32 m0, s35
	s_nop 0
	global_load_lds_dwordx4 v[206:207], off
	s_barrier
	s_waitcnt lgkmcnt(0)
	s_waitcnt lgkmcnt(0)
	v_mfma_f32_16x16x32_bf16 v[126:129], v[140:143], v[160:163], v[126:129]
	v_mfma_f32_16x16x32_bf16 v[122:125], v[152:155], v[160:163], v[122:125]
	v_mfma_f32_16x16x32_bf16 v[110:113], v[140:143], v[168:171], v[110:113]
	v_mfma_f32_16x16x32_bf16 v[106:109], v[152:155], v[168:171], v[106:109]
	v_mfma_f32_16x16x32_bf16 v[94:97], v[140:143], v[186:189], v[94:97]
	v_mfma_f32_16x16x32_bf16 v[90:93], v[152:155], v[186:189], v[90:93]
	v_mfma_f32_16x16x32_bf16 v[78:81], v[140:143], v[198:201], v[78:81]
	v_mfma_f32_16x16x32_bf16 v[74:77], v[152:155], v[198:201], v[74:77]
	v_mfma_f32_16x16x32_bf16 v[126:129], v[148:151], v[164:167], v[126:129]
	v_mfma_f32_16x16x32_bf16 v[122:125], v[156:159], v[164:167], v[122:125]
	v_mfma_f32_16x16x32_bf16 v[110:113], v[148:151], v[172:175], v[110:113]
	v_mfma_f32_16x16x32_bf16 v[106:109], v[156:159], v[172:175], v[106:109]
	v_mfma_f32_16x16x32_bf16 v[94:97], v[148:151], v[190:193], v[94:97]
	v_mfma_f32_16x16x32_bf16 v[90:93], v[156:159], v[190:193], v[90:93]
	v_mfma_f32_16x16x32_bf16 v[78:81], v[148:151], v[202:205], v[78:81]
	v_mfma_f32_16x16x32_bf16 v[74:77], v[156:159], v[202:205], v[74:77]
	s_barrier
	s_add_i32 s18, 16, 0x1c000
	s_add_i32 s3, s3, s29
	v_add_u32_e32 v139, s18, v137
	v_lshl_add_u64 v[144:145], v[144:145], 0, s[70:71]
	s_mov_b32 m0, s3
	ds_read_b128 v[206:209], v139
	ds_read_b128 v[214:217], v139 offset:1024
	ds_read_b128 v[218:221], v139 offset:2048
	ds_read_b128 v[222:225], v139 offset:3072
	global_load_lds_dwordx4 v[144:145], off
	v_lshl_add_u64 v[144:145], v[176:177], 0, s[70:71]
	s_add_i32 m0, s3, 0x2000
	s_nop 0
	global_load_lds_dwordx4 v[144:145], off
	s_barrier
; #define PG8_STAGE(bufoff, gbase, voff) do { _Pragma("unroll") for (int _i = 0; _i < 2; ++_i) \
;     __builtin_amdgcn_global_load_lds((const unsigned*)((const char*)(gbase) + (voff)[_i]), (LAS unsigned*)(lds + (bufoff) + ldsw + _i * 8192), 16, 0, 0); } while (0)
; #define PG8_LDA(dst, b, h) do { _Pragma("unroll") for (int m = 0; m < 4; ++m) _Pragma("unroll") for (int k = 0; k < 2; ++k) dst[m][k] = *(const LAS bf16x8*)(lds + PG8_SA(b, h) + aoff + m * 2048 + k * 1024); } while (0)
; #define PG8_MMA(ai, bj, At, Bt) do { __builtin_amdgcn_s_setprio(1); _Pragma("unroll") for (int m = 0; m < 4; ++m) _Pragma("unroll") for (int n = 0; n < 2; ++n) _Pragma("unroll") for (int k = 0; k < 2; ++k) \
;     acc[ai][bj][m][n] = __builtin_amdgcn_mfma_f32_16x16x32_bf16(Bt[n][k], At[m][k], acc[ai][bj][m][n], 0, 0, 0); __builtin_amdgcn_s_setprio(0); } while (0)
; #define PG8_WAIT_V(n) asm volatile("s_waitcnt vmcnt(" #n ")" ::: "memory")
; #define PG8_WAIT_L(n) asm volatile("s_waitcnt lgkmcnt(" #n ")" ::: "memory")
; #define PG8_BAR __builtin_amdgcn_s_barrier()
; #define PG8_SCHED __builtin_amdgcn_sched_barrier(0)
; template <class Epi, class Sched>
; DI void gemm_phase(LAS unsigned char* lds, const Gemm g, const Sched& S, const Epi& E) {
;     ...
;       PG8_BAR; PG8_WAIT_L(0); PG8_MMA(0, 1, At, B1); PG8_BAR;
;       PG8_LDA(At, 1, 1); PG8_STAGE(PG8_SA(1, 0), a3, voffA);
;       PG8_BAR; PG8_WAIT_L(0); PG8_MMA(1, 0, At, B0); PG8_BAR; PG8_SCHED;
;       PG8_STAGE(PG8_SB(1, 1), b3 + hstepB, voffB);
;       PG8_WAIT_V(6); PG8_BAR; PG8_MMA(1, 1, At, B1); PG8_BAR;
	s_waitcnt lgkmcnt(0)
	s_waitcnt lgkmcnt(0)
	v_mfma_f32_16x16x32_bf16 v[118:121], v[206:209], v[160:163], v[118:121]
	v_mfma_f32_16x16x32_bf16 v[114:117], v[218:221], v[160:163], v[114:117]
	v_mfma_f32_16x16x32_bf16 v[102:105], v[206:209], v[168:171], v[102:105]
	v_mfma_f32_16x16x32_bf16 v[98:101], v[218:221], v[168:171], v[98:101]
	v_mfma_f32_16x16x32_bf16 v[86:89], v[206:209], v[186:189], v[86:89]
	v_mfma_f32_16x16x32_bf16 v[82:85], v[218:221], v[186:189], v[82:85]
	v_mfma_f32_16x16x32_bf16 v[70:73], v[206:209], v[198:201], v[70:73]
	v_mfma_f32_16x16x32_bf16 v[66:69], v[218:221], v[198:201], v[66:69]
	v_mfma_f32_16x16x32_bf16 v[118:121], v[214:217], v[164:167], v[118:121]
	v_mfma_f32_16x16x32_bf16 v[114:117], v[222:225], v[164:167], v[114:117]
	v_mfma_f32_16x16x32_bf16 v[102:105], v[214:217], v[172:175], v[102:105]
	v_mfma_f32_16x16x32_bf16 v[98:101], v[222:225], v[172:175], v[98:101]
	v_mfma_f32_16x16x32_bf16 v[86:89], v[214:217], v[190:193], v[86:89]
	v_mfma_f32_16x16x32_bf16 v[82:85], v[222:225], v[190:193], v[82:85]
	v_mfma_f32_16x16x32_bf16 v[70:73], v[214:217], v[202:205], v[70:73]
	v_mfma_f32_16x16x32_bf16 v[66:69], v[222:225], v[202:205], v[66:69]
	s_mov_b32 m0, s36
	v_lshl_add_u64 v[144:145], v[180:181], 0, s[70:71]
	s_barrier
	ds_read_b128 v[160:163], v138 offset:49152
	ds_read_b128 v[164:167], v138 offset:50176
	ds_read_b128 v[168:171], v138 offset:51200
	ds_read_b128 v[172:175], v138 offset:52224
	ds_read_b128 v[186:189], v138 offset:53248
	ds_read_b128 v[190:193], v138 offset:54272
	ds_read_b128 v[198:201], v138 offset:55296
	ds_read_b128 v[202:205], v138 offset:56320
	global_load_lds_dwordx4 v[144:145], off
	v_lshl_add_u64 v[144:145], v[182:183], 0, s[70:71]
	s_mov_b32 m0, s37
	s_nop 0
	global_load_lds_dwordx4 v[144:145], off
	s_barrier
	s_waitcnt lgkmcnt(0)
	s_waitcnt lgkmcnt(0)
	v_mfma_f32_16x16x32_bf16 v[62:65], v[140:143], v[160:163], v[62:65]
	v_mfma_f32_16x16x32_bf16 v[58:61], v[152:155], v[160:163], v[58:61]
	v_mfma_f32_16x16x32_bf16 v[50:53], v[140:143], v[168:171], v[50:53]
	v_mfma_f32_16x16x32_bf16 v[42:45], v[152:155], v[168:171], v[42:45]
	v_mfma_f32_16x16x32_bf16 v[34:37], v[140:143], v[186:189], v[34:37]
	v_mfma_f32_16x16x32_bf16 v[26:29], v[152:155], v[186:189], v[26:29]
	v_mfma_f32_16x16x32_bf16 v[14:17], v[140:143], v[198:201], v[14:17]
	v_mfma_f32_16x16x32_bf16 v[10:13], v[152:155], v[198:201], v[10:13]
	v_mfma_f32_16x16x32_bf16 v[62:65], v[148:151], v[164:167], v[62:65]
	v_mfma_f32_16x16x32_bf16 v[58:61], v[156:159], v[164:167], v[58:61]
	v_mfma_f32_16x16x32_bf16 v[50:53], v[148:151], v[172:175], v[50:53]
	v_mfma_f32_16x16x32_bf16 v[42:45], v[156:159], v[172:175], v[42:45]
	v_mfma_f32_16x16x32_bf16 v[34:37], v[148:151], v[190:193], v[34:37]
	v_mfma_f32_16x16x32_bf16 v[26:29], v[156:159], v[190:193], v[26:29]
	v_mfma_f32_16x16x32_bf16 v[14:17], v[148:151], v[202:205], v[14:17]
	v_mfma_f32_16x16x32_bf16 v[10:13], v[156:159], v[202:205], v[10:13]
	s_barrier
	s_add_i32 s3, s18, s29
	v_lshl_add_u64 v[140:141], v[184:185], 0, s[70:71]
	s_mov_b32 m0, s3
	s_nop 0
	global_load_lds_dwordx4 v[140:141], off
	v_lshl_add_u64 v[140:141], v[226:227], 0, s[70:71]
	s_add_i32 m0, s3, 0x2000
	s_nop 0
	global_load_lds_dwordx4 v[140:141], off
	s_waitcnt vmcnt(6)
	s_barrier
	v_mfma_f32_16x16x32_bf16 v[54:57], v[206:209], v[160:163], v[54:57]
	v_mfma_f32_16x16x32_bf16 v[46:49], v[218:221], v[160:163], v[46:49]
	v_mfma_f32_16x16x32_bf16 v[38:41], v[206:209], v[168:171], v[38:41]
	v_mfma_f32_16x16x32_bf16 v[30:33], v[218:221], v[168:171], v[30:33]
	v_mfma_f32_16x16x32_bf16 v[22:25], v[206:209], v[186:189], v[22:25]
	v_mfma_f32_16x16x32_bf16 v[18:21], v[218:221], v[186:189], v[18:21]
	v_mfma_f32_16x16x32_bf16 v[6:9], v[206:209], v[198:201], v[6:9]
	v_mfma_f32_16x16x32_bf16 v[2:5], v[218:221], v[198:201], v[2:5]
	v_mfma_f32_16x16x32_bf16 v[54:57], v[214:217], v[164:167], v[54:57]
	v_mfma_f32_16x16x32_bf16 v[46:49], v[222:225], v[164:167], v[46:49]
	v_mfma_f32_16x16x32_bf16 v[38:41], v[214:217], v[172:175], v[38:41]
	v_mfma_f32_16x16x32_bf16 v[30:33], v[222:225], v[172:175], v[30:33]
	v_mfma_f32_16x16x32_bf16 v[22:25], v[214:217], v[190:193], v[22:25]
	v_mfma_f32_16x16x32_bf16 v[18:21], v[222:225], v[190:193], v[18:21]
	v_mfma_f32_16x16x32_bf16 v[6:9], v[214:217], v[202:205], v[6:9]
	v_mfma_f32_16x16x32_bf16 v[2:5], v[222:225], v[202:205], v[2:5]
	s_add_u32 s16, s16, 0x100
	s_addc_u32 s17, s17, 0
	s_cmp_ge_i32 s40, s38
	s_mov_b32 s3, s40
	s_barrier
	s_cbranch_scc0 .LBB0_217

; #define PG8_STAGE(bufoff, gbase, voff) do { _Pragma("unroll") for (int _i = 0; _i < 2; ++_i) \
;     __builtin_amdgcn_global_load_lds((const unsigned*)((const char*)(gbase) + (voff)[_i]), (LAS unsigned*)(lds + (bufoff) + ldsw + _i * 8192), 16, 0, 0); } while (0)
; #define PG8_LDA(dst, b, h) do { _Pragma("unroll") for (int m = 0; m < 4; ++m) _Pragma("unroll") for (int k = 0; k < 2; ++k) dst[m][k] = *(const LAS bf16x8*)(lds + PG8_SA(b, h) + aoff + m * 2048 + k * 1024); } while (0)
; #define PG8_LDB(dst, b, h) do { _Pragma("unroll") for (int n = 0; n < 2; ++n) _Pragma("unroll") for (int k = 0; k < 2; ++k) dst[n][k] = *(const LAS bf16x8*)(lds + PG8_SB(b, h) + boff + n * 2048 + k * 1024); } while (0)
; #define PG8_MMA(ai, bj, At, Bt) do { __builtin_amdgcn_s_setprio(1); _Pragma("unroll") for (int m = 0; m < 4; ++m) _Pragma("unroll") for (int n = 0; n < 2; ++n) _Pragma("unroll") for (int k = 0; k < 2; ++k) \
;     acc[ai][bj][m][n] = __builtin_amdgcn_mfma_f32_16x16x32_bf16(Bt[n][k], At[m][k], acc[ai][bj][m][n], 0, 0, 0); __builtin_amdgcn_s_setprio(0); } while (0)
; #define PG8_WAIT_L(n) asm volatile("s_waitcnt lgkmcnt(" #n ")" ::: "memory")
; #define PG8_BAR __builtin_amdgcn_s_barrier()
; #define PG8_SCHED __builtin_amdgcn_sched_barrier(0)
; template <class Epi, class Sched>
; DI void gemm_phase(LAS unsigned char* lds, const Gemm g, const Sched& S, const Epi& E) {
;     ...
;       const bool last = (t == nt - 2);
;       const char* a1 = cA + (size_t)(t + 1) * kstep;
;       const char* a2 = last ? nA : cA + (size_t)(t + 2) * kstep; const char* b2 = last ? nB : cB + (size_t)(t + 2) * kstep;
;       const char* a3 = a2 + kstep; const char* b3 = b2 + kstep;
;       PG8_LDB(B0, 0, 0); PG8_SCHED; PG8_LDA(At, 0, 0); PG8_STAGE(PG8_SA(1, 1), a1 + hstep, voffA);
;       PG8_WAIT_L(8); PG8_BAR; PG8_WAIT_L(0); PG8_MMA(0, 0, At, B0); PG8_BAR; PG8_SCHED;
;       PG8_LDB(B1, 0, 1); PG8_STAGE(PG8_SB(0, 0), b2, voffB);
;       PG8_BAR; PG8_WAIT_L(0); PG8_MMA(0, 1, At, B1); PG8_BAR;
;       PG8_LDA(At, 0, 1); PG8_STAGE(PG8_SA(0, 0), a2, voffA);
;       PG8_BAR; PG8_WAIT_L(0); PG8_MMA(1, 0, At, B0); PG8_BAR; PG8_SCHED;
.LBB0_491:
	s_add_i32 s26, s8, 2
	s_add_u32 s9, s6, 0xfe000080
	s_addc_u32 s10, s7, -1
	s_cmp_lg_u32 s25, s8
	s_cselect_b32 s11, s10, 0
	s_cselect_b32 s10, s9, 0
	s_add_u32 s8, s4, s10
	s_addc_u32 s9, s5, s11
	s_add_i32 s27, 16, 0x10000
	v_add_u32_e32 v139, s27, v133
	ds_read_b128 v[140:143], v139
	ds_read_b128 v[148:151], v139 offset:1024
	ds_read_b128 v[152:155], v139 offset:2048
	ds_read_b128 v[156:159], v139 offset:3072
	s_add_u32 s10, s2, s10
	s_addc_u32 s11, s3, s11
	v_lshl_add_u64 v[144:145], v[128:129], 0, s[6:7]
	s_add_i32 m0, s18, 0xc000
	ds_read_b128 v[160:163], v138
	ds_read_b128 v[164:167], v138 offset:1024
	ds_read_b128 v[168:171], v138 offset:2048
	ds_read_b128 v[172:175], v138 offset:3072
	ds_read_b128 v[186:189], v138 offset:4096
	ds_read_b128 v[190:193], v138 offset:5120
	ds_read_b128 v[198:201], v138 offset:6144
	ds_read_b128 v[202:205], v138 offset:7168
	global_load_lds_dwordx4 v[144:145], off
	v_lshl_add_u64 v[144:145], v[130:131], 0, s[6:7]
	s_add_i32 m0, s18, 0xe000
	s_nop 0
	global_load_lds_dwordx4 v[144:145], off
	s_barrier
	s_waitcnt lgkmcnt(0)
	s_waitcnt lgkmcnt(0)
	v_mfma_f32_16x16x32_bf16 v[134:137], v[140:143], v[160:163], v[134:137]
	v_mfma_f32_16x16x32_bf16 v[122:125], v[152:155], v[160:163], v[122:125]
	v_mfma_f32_16x16x32_bf16 v[110:113], v[140:143], v[168:171], v[110:113]
	v_mfma_f32_16x16x32_bf16 v[106:109], v[152:155], v[168:171], v[106:109]
	v_mfma_f32_16x16x32_bf16 v[94:97], v[140:143], v[186:189], v[94:97]
	v_mfma_f32_16x16x32_bf16 v[90:93], v[152:155], v[186:189], v[90:93]
	v_mfma_f32_16x16x32_bf16 v[78:81], v[140:143], v[198:201], v[78:81]
	v_mfma_f32_16x16x32_bf16 v[74:77], v[152:155], v[198:201], v[74:77]
	v_mfma_f32_16x16x32_bf16 v[134:137], v[148:151], v[164:167], v[134:137]
	v_mfma_f32_16x16x32_bf16 v[122:125], v[156:159], v[164:167], v[122:125]
	v_mfma_f32_16x16x32_bf16 v[110:113], v[148:151], v[172:175], v[110:113]
	v_mfma_f32_16x16x32_bf16 v[106:109], v[156:159], v[172:175], v[106:109]
	v_mfma_f32_16x16x32_bf16 v[94:97], v[148:151], v[190:193], v[94:97]
	v_mfma_f32_16x16x32_bf16 v[90:93], v[156:159], v[190:193], v[90:93]
	v_mfma_f32_16x16x32_bf16 v[78:81], v[148:151], v[202:205], v[78:81]
	v_mfma_f32_16x16x32_bf16 v[74:77], v[156:159], v[202:205], v[74:77]
	s_barrier
	s_add_i32 s28, 16, 0x14000
	s_add_i32 s27, s27, s17
	v_add_u32_e32 v139, s28, v133
	v_lshl_add_u64 v[144:145], s[10:11], 0, v[0:1]
	s_mov_b32 m0, s27
	ds_read_b128 v[206:209], v139
	ds_read_b128 v[214:217], v139 offset:1024
	ds_read_b128 v[218:221], v139 offset:2048
	ds_read_b128 v[222:225], v139 offset:3072
	global_load_lds_dwordx4 v[144:145], off
	v_lshl_add_u64 v[176:177], s[10:11], 0, v[126:127]
	s_add_i32 m0, s27, 0x2000
	s_nop 0
	global_load_lds_dwordx4 v[176:177], off
	s_barrier
	s_waitcnt lgkmcnt(0)
	s_waitcnt lgkmcnt(0)
	v_mfma_f32_16x16x32_bf16 v[118:121], v[206:209], v[160:163], v[118:121]
	v_mfma_f32_16x16x32_bf16 v[114:117], v[218:221], v[160:163], v[114:117]
	v_mfma_f32_16x16x32_bf16 v[102:105], v[206:209], v[168:171], v[102:105]
	v_mfma_f32_16x16x32_bf16 v[98:101], v[218:221], v[168:171], v[98:101]
	v_mfma_f32_16x16x32_bf16 v[86:89], v[206:209], v[186:189], v[86:89]
	v_mfma_f32_16x16x32_bf16 v[82:85], v[218:221], v[186:189], v[82:85]
	v_mfma_f32_16x16x32_bf16 v[70:73], v[206:209], v[198:201], v[70:73]
	v_mfma_f32_16x16x32_bf16 v[66:69], v[218:221], v[198:201], v[66:69]
	v_mfma_f32_16x16x32_bf16 v[118:121], v[214:217], v[164:167], v[118:121]
	v_mfma_f32_16x16x32_bf16 v[114:117], v[222:225], v[164:167], v[114:117]
	v_mfma_f32_16x16x32_bf16 v[102:105], v[214:217], v[172:175], v[102:105]
	v_mfma_f32_16x16x32_bf16 v[98:101], v[222:225], v[172:175], v[98:101]
	v_mfma_f32_16x16x32_bf16 v[86:89], v[214:217], v[190:193], v[86:89]
	v_mfma_f32_16x16x32_bf16 v[82:85], v[222:225], v[190:193], v[82:85]
	v_mfma_f32_16x16x32_bf16 v[70:73], v[214:217], v[202:205], v[70:73]
	v_mfma_f32_16x16x32_bf16 v[66:69], v[222:225], v[202:205], v[66:69]
	s_mov_b32 m0, s18
	v_lshl_add_u64 v[180:181], s[8:9], 0, v[0:1]
	s_barrier
	ds_read_b128 v[160:163], v138 offset:16384
	ds_read_b128 v[164:167], v138 offset:17408
	ds_read_b128 v[168:171], v138 offset:18432
	ds_read_b128 v[172:175], v138 offset:19456
	ds_read_b128 v[186:189], v138 offset:20480
	ds_read_b128 v[190:193], v138 offset:21504
	ds_read_b128 v[198:201], v138 offset:22528
	ds_read_b128 v[202:205], v138 offset:23552
	global_load_lds_dwordx4 v[180:181], off
	v_lshl_add_u64 v[182:183], s[8:9], 0, v[126:127]
	s_mov_b32 m0, s19
	s_nop 0
	global_load_lds_dwordx4 v[182:183], off
	s_barrier
	s_waitcnt lgkmcnt(0)
	s_waitcnt lgkmcnt(0)
	v_mfma_f32_16x16x32_bf16 v[62:65], v[140:143], v[160:163], v[62:65]
	v_mfma_f32_16x16x32_bf16 v[58:61], v[152:155], v[160:163], v[58:61]
	v_mfma_f32_16x16x32_bf16 v[50:53], v[140:143], v[168:171], v[50:53]
	v_mfma_f32_16x16x32_bf16 v[42:45], v[152:155], v[168:171], v[42:45]
	v_mfma_f32_16x16x32_bf16 v[34:37], v[140:143], v[186:189], v[34:37]
	v_mfma_f32_16x16x32_bf16 v[26:29], v[152:155], v[186:189], v[26:29]
	v_mfma_f32_16x16x32_bf16 v[18:21], v[140:143], v[198:201], v[18:21]
	v_mfma_f32_16x16x32_bf16 v[10:13], v[152:155], v[198:201], v[10:13]
	v_mfma_f32_16x16x32_bf16 v[62:65], v[148:151], v[164:167], v[62:65]
	v_mfma_f32_16x16x32_bf16 v[58:61], v[156:159], v[164:167], v[58:61]
	v_mfma_f32_16x16x32_bf16 v[50:53], v[148:151], v[172:175], v[50:53]
	v_mfma_f32_16x16x32_bf16 v[42:45], v[156:159], v[172:175], v[42:45]
	v_mfma_f32_16x16x32_bf16 v[34:37], v[148:151], v[190:193], v[34:37]
	v_mfma_f32_16x16x32_bf16 v[26:29], v[156:159], v[190:193], v[26:29]
	v_mfma_f32_16x16x32_bf16 v[18:21], v[148:151], v[202:205], v[18:21]
	v_mfma_f32_16x16x32_bf16 v[10:13], v[156:159], v[202:205], v[10:13]
	s_barrier
; #define PG8_STAGE(bufoff, gbase, voff) do { _Pragma("unroll") for (int _i = 0; _i < 2; ++_i) \
;     __builtin_amdgcn_global_load_lds((const unsigned*)((const char*)(gbase) + (voff)[_i]), (LAS unsigned*)(lds + (bufoff) + ldsw + _i * 8192), 16, 0, 0); } while (0)
; #define PG8_LDA(dst, b, h) do { _Pragma("unroll") for (int m = 0; m < 4; ++m) _Pragma("unroll") for (int k = 0; k < 2; ++k) dst[m][k] = *(const LAS bf16x8*)(lds + PG8_SA(b, h) + aoff + m * 2048 + k * 1024); } while (0)
; #define PG8_LDB(dst, b, h) do { _Pragma("unroll") for (int n = 0; n < 2; ++n) _Pragma("unroll") for (int k = 0; k < 2; ++k) dst[n][k] = *(const LAS bf16x8*)(lds + PG8_SB(b, h) + boff + n * 2048 + k * 1024); } while (0)
; #define PG8_MMA(ai, bj, At, Bt) do { __builtin_amdgcn_s_setprio(1); _Pragma("unroll") for (int m = 0; m < 4; ++m) _Pragma("unroll") for (int n = 0; n < 2; ++n) _Pragma("unroll") for (int k = 0; k < 2; ++k) \
;     acc[ai][bj][m][n] = __builtin_amdgcn_mfma_f32_16x16x32_bf16(Bt[n][k], At[m][k], acc[ai][bj][m][n], 0, 0, 0); __builtin_amdgcn_s_setprio(0); } while (0)
; #define PG8_WAIT_V(n) asm volatile("s_waitcnt vmcnt(" #n ")" ::: "memory")
; #define PG8_WAIT_L(n) asm volatile("s_waitcnt lgkmcnt(" #n ")" ::: "memory")
; #define PG8_BAR __builtin_amdgcn_s_barrier()
; #define PG8_SCHED __builtin_amdgcn_sched_barrier(0)
; template <class Epi, class Sched>
; DI void gemm_phase(LAS unsigned char* lds, const Gemm g, const Sched& S, const Epi& E) {
;     ...
;       PG8_STAGE(PG8_SB(0, 1), b2 + hstepB, voffB);
;       PG8_WAIT_V(6); PG8_BAR; PG8_MMA(1, 1, At, B1); PG8_BAR;
;       PG8_LDB(B0, 1, 0); PG8_SCHED; PG8_LDA(At, 1, 0); PG8_STAGE(PG8_SA(0, 1), a2 + hstep, voffA);
;       PG8_WAIT_L(8); PG8_BAR; PG8_WAIT_L(0); PG8_MMA(0, 0, At, B0); PG8_BAR; PG8_SCHED;
;       PG8_LDB(B1, 1, 1); PG8_STAGE(PG8_SB(1, 0), b3, voffB);
;       PG8_BAR; PG8_WAIT_L(0); PG8_MMA(0, 1, At, B1); PG8_BAR;
	s_add_u32 s10, s10, s0
	s_addc_u32 s11, s11, s1
	s_add_i32 s27, s28, s17
	v_lshl_add_u64 v[184:185], s[10:11], 0, v[0:1]
	s_mov_b32 m0, s27
	v_lshl_add_u64 v[226:227], s[10:11], 0, v[126:127]
	global_load_lds_dwordx4 v[184:185], off
	s_add_i32 m0, s27, 0x2000
	s_nop 0
	global_load_lds_dwordx4 v[226:227], off
	s_waitcnt vmcnt(6)
	s_barrier
	v_mfma_f32_16x16x32_bf16 v[54:57], v[206:209], v[160:163], v[54:57]
	v_mfma_f32_16x16x32_bf16 v[46:49], v[218:221], v[160:163], v[46:49]
	v_mfma_f32_16x16x32_bf16 v[38:41], v[206:209], v[168:171], v[38:41]
	v_mfma_f32_16x16x32_bf16 v[30:33], v[218:221], v[168:171], v[30:33]
	v_mfma_f32_16x16x32_bf16 v[22:25], v[206:209], v[186:189], v[22:25]
	v_mfma_f32_16x16x32_bf16 v[14:17], v[218:221], v[186:189], v[14:17]
	v_mfma_f32_16x16x32_bf16 v[6:9], v[206:209], v[198:201], v[6:9]
	v_mfma_f32_16x16x32_bf16 v[2:5], v[218:221], v[198:201], v[2:5]
	v_mfma_f32_16x16x32_bf16 v[54:57], v[214:217], v[164:167], v[54:57]
	v_mfma_f32_16x16x32_bf16 v[46:49], v[222:225], v[164:167], v[46:49]
	v_mfma_f32_16x16x32_bf16 v[38:41], v[214:217], v[172:175], v[38:41]
	v_mfma_f32_16x16x32_bf16 v[30:33], v[222:225], v[172:175], v[30:33]
	v_mfma_f32_16x16x32_bf16 v[22:25], v[214:217], v[190:193], v[22:25]
	v_mfma_f32_16x16x32_bf16 v[14:17], v[222:225], v[190:193], v[14:17]
	v_mfma_f32_16x16x32_bf16 v[6:9], v[214:217], v[202:205], v[6:9]
	v_mfma_f32_16x16x32_bf16 v[2:5], v[222:225], v[202:205], v[2:5]
	s_add_i32 s10, 16, 0x18000
	v_add_u32_e32 v139, s10, v133
	s_barrier
	ds_read_b128 v[140:143], v139
	ds_read_b128 v[148:151], v139 offset:1024
	ds_read_b128 v[152:155], v139 offset:2048
	ds_read_b128 v[156:159], v139 offset:3072
	s_add_u32 s8, s8, s0
	s_addc_u32 s9, s9, s1
	s_mov_b32 m0, s20
	v_lshl_add_u64 v[206:207], s[8:9], 0, v[0:1]
	ds_read_b128 v[160:163], v138 offset:32768
	ds_read_b128 v[164:167], v138 offset:33792
	ds_read_b128 v[168:171], v138 offset:34816
	ds_read_b128 v[172:175], v138 offset:35840
	ds_read_b128 v[186:189], v138 offset:36864
	ds_read_b128 v[190:193], v138 offset:37888
	ds_read_b128 v[198:201], v138 offset:38912
	ds_read_b128 v[202:205], v138 offset:39936
	global_load_lds_dwordx4 v[206:207], off
	v_lshl_add_u64 v[206:207], s[8:9], 0, v[126:127]
	s_mov_b32 m0, s21
	s_nop 0
	global_load_lds_dwordx4 v[206:207], off
	s_barrier
	s_waitcnt lgkmcnt(0)
	s_waitcnt lgkmcnt(0)
	v_mfma_f32_16x16x32_bf16 v[134:137], v[140:143], v[160:163], v[134:137]
	v_mfma_f32_16x16x32_bf16 v[122:125], v[152:155], v[160:163], v[122:125]
	v_mfma_f32_16x16x32_bf16 v[110:113], v[140:143], v[168:171], v[110:113]
	v_mfma_f32_16x16x32_bf16 v[106:109], v[152:155], v[168:171], v[106:109]
	v_mfma_f32_16x16x32_bf16 v[94:97], v[140:143], v[186:189], v[94:97]
	v_mfma_f32_16x16x32_bf16 v[90:93], v[152:155], v[186:189], v[90:93]
	v_mfma_f32_16x16x32_bf16 v[78:81], v[140:143], v[198:201], v[78:81]
	v_mfma_f32_16x16x32_bf16 v[74:77], v[152:155], v[198:201], v[74:77]
	v_mfma_f32_16x16x32_bf16 v[134:137], v[148:151], v[164:167], v[134:137]
	v_mfma_f32_16x16x32_bf16 v[122:125], v[156:159], v[164:167], v[122:125]
	v_mfma_f32_16x16x32_bf16 v[110:113], v[148:151], v[172:175], v[110:113]
	v_mfma_f32_16x16x32_bf16 v[106:109], v[156:159], v[172:175], v[106:109]
	v_mfma_f32_16x16x32_bf16 v[94:97], v[148:151], v[190:193], v[94:97]
	v_mfma_f32_16x16x32_bf16 v[90:93], v[156:159], v[190:193], v[90:93]
	v_mfma_f32_16x16x32_bf16 v[78:81], v[148:151], v[202:205], v[78:81]
	v_mfma_f32_16x16x32_bf16 v[74:77], v[156:159], v[202:205], v[74:77]
	s_barrier
	s_add_i32 s8, 16, 0x1c000
	s_add_i32 s9, s10, s17
	v_add_u32_e32 v139, s8, v133
	v_lshl_add_u64 v[144:145], v[144:145], 0, s[70:71]
	s_mov_b32 m0, s9
	ds_read_b128 v[206:209], v139
	ds_read_b128 v[214:217], v139 offset:1024
	ds_read_b128 v[218:221], v139 offset:2048
	ds_read_b128 v[222:225], v139 offset:3072
	global_load_lds_dwordx4 v[144:145], off
	v_lshl_add_u64 v[144:145], v[176:177], 0, s[70:71]
	s_add_i32 m0, s9, 0x2000
	s_nop 0
	global_load_lds_dwordx4 v[144:145], off
	s_barrier
; #define PG8_STAGE(bufoff, gbase, voff) do { _Pragma("unroll") for (int _i = 0; _i < 2; ++_i) \
;     __builtin_amdgcn_global_load_lds((const unsigned*)((const char*)(gbase) + (voff)[_i]), (LAS unsigned*)(lds + (bufoff) + ldsw + _i * 8192), 16, 0, 0); } while (0)
; #define PG8_LDA(dst, b, h) do { _Pragma("unroll") for (int m = 0; m < 4; ++m) _Pragma("unroll") for (int k = 0; k < 2; ++k) dst[m][k] = *(const LAS bf16x8*)(lds + PG8_SA(b, h) + aoff + m * 2048 + k * 1024); } while (0)
; #define PG8_LDB(dst, b, h) do { _Pragma("unroll") for (int n = 0; n < 2; ++n) _Pragma("unroll") for (int k = 0; k < 2; ++k) dst[n][k] = *(const LAS bf16x8*)(lds + PG8_SB(b, h) + boff + n * 2048 + k * 1024); } while (0)
; #define PG8_MMA(ai, bj, At, Bt) do { __builtin_amdgcn_s_setprio(1); _Pragma("unroll") for (int m = 0; m < 4; ++m) _Pragma("unroll") for (int n = 0; n < 2; ++n) _Pragma("unroll") for (int k = 0; k < 2; ++k) \
;     acc[ai][bj][m][n] = __builtin_amdgcn_mfma_f32_16x16x32_bf16(Bt[n][k], At[m][k], acc[ai][bj][m][n], 0, 0, 0); __builtin_amdgcn_s_setprio(0); } while (0)
; #define PG8_WAIT_V(n) asm volatile("s_waitcnt vmcnt(" #n ")" ::: "memory")
; #define PG8_WAIT_L(n) asm volatile("s_waitcnt lgkmcnt(" #n ")" ::: "memory")
; #define PG8_BAR __builtin_amdgcn_s_barrier()
; #define PG8_SCHED __builtin_amdgcn_sched_barrier(0)
; template <class Epi, class Sched>
; DI void gemm_phase(LAS unsigned char* lds, const Gemm g, const Sched& S, const Epi& E) {
;     ...
;       PG8_LDB(B1, 1, 1); PG8_STAGE(PG8_SB(1, 0), b3, voffB);
;       PG8_BAR; PG8_WAIT_L(0); PG8_MMA(0, 1, At, B1); PG8_BAR;
;       PG8_LDA(At, 1, 1); PG8_STAGE(PG8_SA(1, 0), a3, voffA);
;       PG8_BAR; PG8_WAIT_L(0); PG8_MMA(1, 0, At, B0); PG8_BAR; PG8_SCHED;
;       PG8_STAGE(PG8_SB(1, 1), b3 + hstepB, voffB);
;       PG8_WAIT_V(6); PG8_BAR; PG8_MMA(1, 1, At, B1); PG8_BAR;
;     }
	s_waitcnt lgkmcnt(0)
	s_waitcnt lgkmcnt(0)
	v_mfma_f32_16x16x32_bf16 v[118:121], v[206:209], v[160:163], v[118:121]
	v_mfma_f32_16x16x32_bf16 v[114:117], v[218:221], v[160:163], v[114:117]
	v_mfma_f32_16x16x32_bf16 v[102:105], v[206:209], v[168:171], v[102:105]
	v_mfma_f32_16x16x32_bf16 v[98:101], v[218:221], v[168:171], v[98:101]
	v_mfma_f32_16x16x32_bf16 v[86:89], v[206:209], v[186:189], v[86:89]
	v_mfma_f32_16x16x32_bf16 v[82:85], v[218:221], v[186:189], v[82:85]
	v_mfma_f32_16x16x32_bf16 v[70:73], v[206:209], v[198:201], v[70:73]
	v_mfma_f32_16x16x32_bf16 v[66:69], v[218:221], v[198:201], v[66:69]
	v_mfma_f32_16x16x32_bf16 v[118:121], v[214:217], v[164:167], v[118:121]
	v_mfma_f32_16x16x32_bf16 v[114:117], v[222:225], v[164:167], v[114:117]
	v_mfma_f32_16x16x32_bf16 v[102:105], v[214:217], v[172:175], v[102:105]
	v_mfma_f32_16x16x32_bf16 v[98:101], v[222:225], v[172:175], v[98:101]
	v_mfma_f32_16x16x32_bf16 v[86:89], v[214:217], v[190:193], v[86:89]
	v_mfma_f32_16x16x32_bf16 v[82:85], v[222:225], v[190:193], v[82:85]
	v_mfma_f32_16x16x32_bf16 v[70:73], v[214:217], v[202:205], v[70:73]
	v_mfma_f32_16x16x32_bf16 v[66:69], v[222:225], v[202:205], v[66:69]
	s_mov_b32 m0, s22
	v_lshl_add_u64 v[144:145], v[180:181], 0, s[70:71]
	s_barrier
	ds_read_b128 v[160:163], v138 offset:49152
	ds_read_b128 v[164:167], v138 offset:50176
	ds_read_b128 v[168:171], v138 offset:51200
	ds_read_b128 v[172:175], v138 offset:52224
	ds_read_b128 v[186:189], v138 offset:53248
	ds_read_b128 v[190:193], v138 offset:54272
	ds_read_b128 v[198:201], v138 offset:55296
	ds_read_b128 v[202:205], v138 offset:56320
	global_load_lds_dwordx4 v[144:145], off
	v_lshl_add_u64 v[144:145], v[182:183], 0, s[70:71]
	s_mov_b32 m0, s23
	s_nop 0
	global_load_lds_dwordx4 v[144:145], off
	s_barrier
	s_waitcnt lgkmcnt(0)
	s_waitcnt lgkmcnt(0)
	v_mfma_f32_16x16x32_bf16 v[62:65], v[140:143], v[160:163], v[62:65]
	v_mfma_f32_16x16x32_bf16 v[58:61], v[152:155], v[160:163], v[58:61]
	v_mfma_f32_16x16x32_bf16 v[50:53], v[140:143], v[168:171], v[50:53]
	v_mfma_f32_16x16x32_bf16 v[42:45], v[152:155], v[168:171], v[42:45]
	v_mfma_f32_16x16x32_bf16 v[34:37], v[140:143], v[186:189], v[34:37]
	v_mfma_f32_16x16x32_bf16 v[26:29], v[152:155], v[186:189], v[26:29]
	v_mfma_f32_16x16x32_bf16 v[18:21], v[140:143], v[198:201], v[18:21]
	v_mfma_f32_16x16x32_bf16 v[10:13], v[152:155], v[198:201], v[10:13]
	v_mfma_f32_16x16x32_bf16 v[62:65], v[148:151], v[164:167], v[62:65]
	v_mfma_f32_16x16x32_bf16 v[58:61], v[156:159], v[164:167], v[58:61]
	v_mfma_f32_16x16x32_bf16 v[50:53], v[148:151], v[172:175], v[50:53]
	v_mfma_f32_16x16x32_bf16 v[42:45], v[156:159], v[172:175], v[42:45]
	v_mfma_f32_16x16x32_bf16 v[34:37], v[148:151], v[190:193], v[34:37]
	v_mfma_f32_16x16x32_bf16 v[26:29], v[156:159], v[190:193], v[26:29]
	v_mfma_f32_16x16x32_bf16 v[18:21], v[148:151], v[202:205], v[18:21]
	v_mfma_f32_16x16x32_bf16 v[10:13], v[156:159], v[202:205], v[10:13]
	s_barrier
	s_add_i32 s8, s8, s17
	v_lshl_add_u64 v[140:141], v[184:185], 0, s[70:71]
	s_mov_b32 m0, s8
	s_nop 0
	global_load_lds_dwordx4 v[140:141], off
	v_lshl_add_u64 v[140:141], v[226:227], 0, s[70:71]
	s_add_i32 m0, s8, 0x2000
	s_nop 0
	global_load_lds_dwordx4 v[140:141], off
	s_waitcnt vmcnt(6)
	s_barrier
	v_mfma_f32_16x16x32_bf16 v[54:57], v[206:209], v[160:163], v[54:57]
	v_mfma_f32_16x16x32_bf16 v[46:49], v[218:221], v[160:163], v[46:49]
	v_mfma_f32_16x16x32_bf16 v[38:41], v[206:209], v[168:171], v[38:41]
	v_mfma_f32_16x16x32_bf16 v[30:33], v[218:221], v[168:171], v[30:33]
	v_mfma_f32_16x16x32_bf16 v[22:25], v[206:209], v[186:189], v[22:25]
	v_mfma_f32_16x16x32_bf16 v[14:17], v[218:221], v[186:189], v[14:17]
	v_mfma_f32_16x16x32_bf16 v[6:9], v[206:209], v[198:201], v[6:9]
	v_mfma_f32_16x16x32_bf16 v[2:5], v[218:221], v[198:201], v[2:5]
	v_mfma_f32_16x16x32_bf16 v[54:57], v[214:217], v[164:167], v[54:57]
	v_mfma_f32_16x16x32_bf16 v[46:49], v[222:225], v[164:167], v[46:49]
	v_mfma_f32_16x16x32_bf16 v[38:41], v[214:217], v[172:175], v[38:41]
	v_mfma_f32_16x16x32_bf16 v[30:33], v[222:225], v[172:175], v[30:33]
	v_mfma_f32_16x16x32_bf16 v[22:25], v[214:217], v[190:193], v[22:25]
	v_mfma_f32_16x16x32_bf16 v[14:17], v[222:225], v[190:193], v[14:17]
	v_mfma_f32_16x16x32_bf16 v[6:9], v[214:217], v[202:205], v[6:9]
	v_mfma_f32_16x16x32_bf16 v[2:5], v[222:225], v[202:205], v[2:5]
	s_add_u32 s6, s6, 0x100
	s_addc_u32 s7, s7, 0
	s_cmp_ge_i32 s26, s24
	s_mov_b32 s8, s26
	s_barrier
	s_cbranch_scc0 .LBB0_491
	s_movk_i32 s27, 0xffd0
	s_movk_i32 s28, 0x2200

; #define PG8_STAGE(bufoff, gbase, voff) do { _Pragma("unroll") for (int _i = 0; _i < 2; ++_i) \
;     __builtin_amdgcn_global_load_lds((const unsigned*)((const char*)(gbase) + (voff)[_i]), (LAS unsigned*)(lds + (bufoff) + ldsw + _i * 8192), 16, 0, 0); } while (0)
; #define PG8_LDA(dst, b, h) do { _Pragma("unroll") for (int m = 0; m < 4; ++m) _Pragma("unroll") for (int k = 0; k < 2; ++k) dst[m][k] = *(const LAS bf16x8*)(lds + PG8_SA(b, h) + aoff + m * 2048 + k * 1024); } while (0)
; #define PG8_LDB(dst, b, h) do { _Pragma("unroll") for (int n = 0; n < 2; ++n) _Pragma("unroll") for (int k = 0; k < 2; ++k) dst[n][k] = *(const LAS bf16x8*)(lds + PG8_SB(b, h) + boff + n * 2048 + k * 1024); } while (0)
; #define PG8_MMA(ai, bj, At, Bt) do { __builtin_amdgcn_s_setprio(1); _Pragma("unroll") for (int m = 0; m < 4; ++m) _Pragma("unroll") for (int n = 0; n < 2; ++n) _Pragma("unroll") for (int k = 0; k < 2; ++k) \
;     acc[ai][bj][m][n] = __builtin_amdgcn_mfma_f32_16x16x32_bf16(Bt[n][k], At[m][k], acc[ai][bj][m][n], 0, 0, 0); __builtin_amdgcn_s_setprio(0); } while (0)
; #define PG8_WAIT_L(n) asm volatile("s_waitcnt lgkmcnt(" #n ")" ::: "memory")
; #define PG8_BAR __builtin_amdgcn_s_barrier()
; #define PG8_SCHED __builtin_amdgcn_sched_barrier(0)
; template <class Epi, class Sched>
; DI void gemm_phase(LAS unsigned char* lds, const Gemm g, const Sched& S, const Epi& E) {
;     ...
;       const bool last = (t == nt - 2);
;       const char* a1 = cA + (size_t)(t + 1) * kstep;
;       const char* a2 = last ? nA : cA + (size_t)(t + 2) * kstep; const char* b2 = last ? nB : cB + (size_t)(t + 2) * kstep;
;       const char* a3 = a2 + kstep; const char* b3 = b2 + kstep;
;       PG8_LDB(B0, 0, 0); PG8_SCHED; PG8_LDA(At, 0, 0); PG8_STAGE(PG8_SA(1, 1), a1 + hstep, voffA);
;       PG8_WAIT_L(8); PG8_BAR; PG8_WAIT_L(0); PG8_MMA(0, 0, At, B0); PG8_BAR; PG8_SCHED;
;       PG8_LDB(B1, 0, 1); PG8_STAGE(PG8_SB(0, 0), b2, voffB);
;       PG8_BAR; PG8_WAIT_L(0); PG8_MMA(0, 1, At, B1); PG8_BAR;
;       PG8_LDA(At, 0, 1); PG8_STAGE(PG8_SA(0, 0), a2, voffA);
;       PG8_BAR; PG8_WAIT_L(0); PG8_MMA(1, 0, At, B0); PG8_BAR; PG8_SCHED;
.LBB0_519:
	s_add_i32 s23, s6, 2
	s_add_u32 s8, s2, 0x80
	s_addc_u32 s7, s3, 0
	s_add_i32 s24, 16, 0x10000
	v_add_u32_e32 v0, s24, v215
	ds_read_b128 v[66:69], v0
	ds_read_b128 v[70:73], v0 offset:1024
	ds_read_b128 v[74:77], v0 offset:2048
	ds_read_b128 v[78:81], v0 offset:3072
	s_cmp_eq_u32 s41, s6
	s_cselect_b32 s6, s0, s8
	s_cselect_b32 s7, s1, s7
	s_cselect_b32 s9, s21, s22
	s_cselect_b32 s8, s20, s11
	v_lshl_add_u64 v[206:207], s[2:3], 0, v[202:203]
	s_add_i32 m0, s30, 0xc000
	ds_read_b128 v[82:85], v216
	ds_read_b128 v[86:89], v216 offset:1024
	ds_read_b128 v[94:97], v216 offset:2048
	ds_read_b128 v[98:101], v216 offset:3072
	ds_read_b128 v[114:117], v216 offset:4096
	ds_read_b128 v[118:121], v216 offset:5120
	ds_read_b128 v[122:125], v216 offset:6144
	ds_read_b128 v[126:129], v216 offset:7168
	global_load_lds_dwordx4 v[206:207], off
	v_lshl_add_u64 v[206:207], s[2:3], 0, v[204:205]
	s_add_i32 m0, s30, 0xe000
	s_nop 0
	global_load_lds_dwordx4 v[206:207], off
	s_barrier
	s_waitcnt lgkmcnt(0)
	s_waitcnt lgkmcnt(0)
	v_mfma_f32_16x16x32_bf16 v[174:177], v[66:69], v[82:85], v[174:177]
	v_mfma_f32_16x16x32_bf16 v[170:173], v[74:77], v[82:85], v[170:173]
	v_mfma_f32_16x16x32_bf16 v[158:161], v[66:69], v[94:97], v[158:161]
	v_mfma_f32_16x16x32_bf16 v[154:157], v[74:77], v[94:97], v[154:157]
	v_mfma_f32_16x16x32_bf16 v[142:145], v[66:69], v[114:117], v[142:145]
	v_mfma_f32_16x16x32_bf16 v[138:141], v[74:77], v[114:117], v[138:141]
	v_mfma_f32_16x16x32_bf16 v[110:113], v[66:69], v[122:125], v[110:113]
	v_mfma_f32_16x16x32_bf16 v[106:109], v[74:77], v[122:125], v[106:109]
	v_mfma_f32_16x16x32_bf16 v[174:177], v[70:73], v[86:89], v[174:177]
	v_mfma_f32_16x16x32_bf16 v[170:173], v[78:81], v[86:89], v[170:173]
	v_mfma_f32_16x16x32_bf16 v[158:161], v[70:73], v[98:101], v[158:161]
	v_mfma_f32_16x16x32_bf16 v[154:157], v[78:81], v[98:101], v[154:157]
	v_mfma_f32_16x16x32_bf16 v[142:145], v[70:73], v[118:121], v[142:145]
	v_mfma_f32_16x16x32_bf16 v[138:141], v[78:81], v[118:121], v[138:141]
	v_mfma_f32_16x16x32_bf16 v[110:113], v[70:73], v[126:129], v[110:113]
	v_mfma_f32_16x16x32_bf16 v[106:109], v[78:81], v[126:129], v[106:109]
	s_barrier
	s_add_i32 s25, 16, 0x14000
	s_add_i32 s24, s24, s29
	v_add_u32_e32 v0, s25, v215
	v_lshl_add_u64 v[246:247], s[8:9], 0, v[190:191]
	s_mov_b32 m0, s24
	ds_read_b128 v[206:209], v0
	ds_read_b128 v[218:221], v0 offset:1024
	ds_read_b128 v[222:225], v0 offset:2048
	ds_read_b128 v[226:229], v0 offset:3072
	global_load_lds_dwordx4 v[246:247], off
	v_lshl_add_u64 v[248:249], s[8:9], 0, v[186:187]
	s_add_i32 m0, s24, 0x2000
	s_nop 0
	global_load_lds_dwordx4 v[248:249], off
	s_barrier
	s_waitcnt lgkmcnt(0)
	s_waitcnt lgkmcnt(0)
	v_mfma_f32_16x16x32_bf16 v[166:169], v[206:209], v[82:85], v[166:169]
	v_mfma_f32_16x16x32_bf16 v[82:85], v[222:225], v[82:85], v[162:165]
	v_mfma_f32_16x16x32_bf16 v[166:169], v[218:221], v[86:89], v[166:169]
	v_mfma_f32_16x16x32_bf16 v[82:85], v[226:229], v[86:89], v[82:85]
	v_mfma_f32_16x16x32_bf16 v[86:89], v[206:209], v[94:97], v[150:153]
	v_mfma_f32_16x16x32_bf16 v[94:97], v[222:225], v[94:97], v[146:149]
	v_mfma_f32_16x16x32_bf16 v[102:105], v[206:209], v[122:125], v[102:105]
	v_mfma_f32_16x16x32_bf16 v[90:93], v[222:225], v[122:125], v[90:93]
	v_mfma_f32_16x16x32_bf16 v[86:89], v[218:221], v[98:101], v[86:89]
	v_mfma_f32_16x16x32_bf16 v[94:97], v[226:229], v[98:101], v[94:97]
	v_mfma_f32_16x16x32_bf16 v[98:101], v[206:209], v[114:117], v[134:137]
	v_mfma_f32_16x16x32_bf16 v[114:117], v[222:225], v[114:117], v[130:133]
	v_mfma_f32_16x16x32_bf16 v[102:105], v[218:221], v[126:129], v[102:105]
	v_mfma_f32_16x16x32_bf16 v[90:93], v[226:229], v[126:129], v[90:93]
	v_mfma_f32_16x16x32_bf16 v[98:101], v[218:221], v[118:121], v[98:101]
	v_mfma_f32_16x16x32_bf16 v[114:117], v[226:229], v[118:121], v[114:117]
	s_mov_b32 m0, s30
	v_lshl_add_u64 v[250:251], s[6:7], 0, v[192:193]
	s_barrier
	ds_read_b128 v[118:121], v216 offset:16384
	ds_read_b128 v[122:125], v216 offset:17408
	ds_read_b128 v[126:129], v216 offset:18432
	ds_read_b128 v[130:133], v216 offset:19456
	ds_read_b128 v[134:137], v216 offset:20480
	ds_read_b128 v[146:149], v216 offset:21504
	ds_read_b128 v[150:153], v216 offset:22528
	ds_read_b128 v[162:165], v216 offset:23552
	global_load_lds_dwordx4 v[250:251], off
	v_lshl_add_u64 v[180:181], s[6:7], 0, v[188:189]
	s_mov_b32 m0, s31
	s_nop 0
	global_load_lds_dwordx4 v[180:181], off
	s_barrier
	s_waitcnt lgkmcnt(0)
	s_waitcnt lgkmcnt(0)
	v_mfma_f32_16x16x32_bf16 v[62:65], v[66:69], v[118:121], v[62:65]
	v_mfma_f32_16x16x32_bf16 v[58:61], v[74:77], v[118:121], v[58:61]
	v_mfma_f32_16x16x32_bf16 v[46:49], v[66:69], v[126:129], v[46:49]
	v_mfma_f32_16x16x32_bf16 v[42:45], v[74:77], v[126:129], v[42:45]
	v_mfma_f32_16x16x32_bf16 v[30:33], v[66:69], v[134:137], v[30:33]
	v_mfma_f32_16x16x32_bf16 v[26:29], v[74:77], v[134:137], v[26:29]
	v_mfma_f32_16x16x32_bf16 v[14:17], v[66:69], v[150:153], v[14:17]
	v_mfma_f32_16x16x32_bf16 v[10:13], v[74:77], v[150:153], v[10:13]
	v_mfma_f32_16x16x32_bf16 v[62:65], v[70:73], v[122:125], v[62:65]
	v_mfma_f32_16x16x32_bf16 v[58:61], v[78:81], v[122:125], v[58:61]
	v_mfma_f32_16x16x32_bf16 v[46:49], v[70:73], v[130:133], v[46:49]
	v_mfma_f32_16x16x32_bf16 v[42:45], v[78:81], v[130:133], v[42:45]
	v_mfma_f32_16x16x32_bf16 v[30:33], v[70:73], v[146:149], v[30:33]
	v_mfma_f32_16x16x32_bf16 v[26:29], v[78:81], v[146:149], v[26:29]
	v_mfma_f32_16x16x32_bf16 v[14:17], v[70:73], v[162:165], v[14:17]
	v_mfma_f32_16x16x32_bf16 v[10:13], v[78:81], v[162:165], v[10:13]
	s_barrier
; #define PG8_STAGE(bufoff, gbase, voff) do { _Pragma("unroll") for (int _i = 0; _i < 2; ++_i) \
;     __builtin_amdgcn_global_load_lds((const unsigned*)((const char*)(gbase) + (voff)[_i]), (LAS unsigned*)(lds + (bufoff) + ldsw + _i * 8192), 16, 0, 0); } while (0)
; #define PG8_LDA(dst, b, h) do { _Pragma("unroll") for (int m = 0; m < 4; ++m) _Pragma("unroll") for (int k = 0; k < 2; ++k) dst[m][k] = *(const LAS bf16x8*)(lds + PG8_SA(b, h) + aoff + m * 2048 + k * 1024); } while (0)
; #define PG8_LDB(dst, b, h) do { _Pragma("unroll") for (int n = 0; n < 2; ++n) _Pragma("unroll") for (int k = 0; k < 2; ++k) dst[n][k] = *(const LAS bf16x8*)(lds + PG8_SB(b, h) + boff + n * 2048 + k * 1024); } while (0)
; #define PG8_MMA(ai, bj, At, Bt) do { __builtin_amdgcn_s_setprio(1); _Pragma("unroll") for (int m = 0; m < 4; ++m) _Pragma("unroll") for (int n = 0; n < 2; ++n) _Pragma("unroll") for (int k = 0; k < 2; ++k) \
;     acc[ai][bj][m][n] = __builtin_amdgcn_mfma_f32_16x16x32_bf16(Bt[n][k], At[m][k], acc[ai][bj][m][n], 0, 0, 0); __builtin_amdgcn_s_setprio(0); } while (0)
; #define PG8_WAIT_V(n) asm volatile("s_waitcnt vmcnt(" #n ")" ::: "memory")
; #define PG8_WAIT_L(n) asm volatile("s_waitcnt lgkmcnt(" #n ")" ::: "memory")
; #define PG8_BAR __builtin_amdgcn_s_barrier()
; #define PG8_SCHED __builtin_amdgcn_sched_barrier(0)
; template <class Epi, class Sched>
; DI void gemm_phase(LAS unsigned char* lds, const Gemm g, const Sched& S, const Epi& E) {
;     ...
;       PG8_STAGE(PG8_SB(0, 1), b2 + hstepB, voffB);
;       PG8_WAIT_V(6); PG8_BAR; PG8_MMA(1, 1, At, B1); PG8_BAR;
;       PG8_LDB(B0, 1, 0); PG8_SCHED; PG8_LDA(At, 1, 0); PG8_STAGE(PG8_SA(0, 1), a2 + hstep, voffA);
;       PG8_WAIT_L(8); PG8_BAR; PG8_WAIT_L(0); PG8_MMA(0, 0, At, B0); PG8_BAR; PG8_SCHED;
;       PG8_LDB(B1, 1, 1); PG8_STAGE(PG8_SB(1, 0), b3, voffB);
	s_add_u32 s8, s8, s14
	s_addc_u32 s9, s9, s15
	s_add_i32 s24, s25, s29
	v_lshl_add_u64 v[182:183], s[8:9], 0, v[190:191]
	s_mov_b32 m0, s24
	v_lshl_add_u64 v[184:185], s[8:9], 0, v[186:187]
	global_load_lds_dwordx4 v[182:183], off
	s_add_i32 m0, s24, 0x2000
	s_nop 0
	global_load_lds_dwordx4 v[184:185], off
	s_waitcnt vmcnt(6)
	s_barrier
	v_mfma_f32_16x16x32_bf16 v[54:57], v[206:209], v[118:121], v[54:57]
	v_mfma_f32_16x16x32_bf16 v[50:53], v[222:225], v[118:121], v[50:53]
	v_mfma_f32_16x16x32_bf16 v[38:41], v[206:209], v[126:129], v[38:41]
	v_mfma_f32_16x16x32_bf16 v[34:37], v[222:225], v[126:129], v[34:37]
	v_mfma_f32_16x16x32_bf16 v[22:25], v[206:209], v[134:137], v[22:25]
	v_mfma_f32_16x16x32_bf16 v[18:21], v[222:225], v[134:137], v[18:21]
	v_mfma_f32_16x16x32_bf16 v[6:9], v[206:209], v[150:153], v[6:9]
	v_mfma_f32_16x16x32_bf16 v[2:5], v[222:225], v[150:153], v[2:5]
	v_mfma_f32_16x16x32_bf16 v[54:57], v[218:221], v[122:125], v[54:57]
	v_mfma_f32_16x16x32_bf16 v[50:53], v[226:229], v[122:125], v[50:53]
	v_mfma_f32_16x16x32_bf16 v[38:41], v[218:221], v[130:133], v[38:41]
	v_mfma_f32_16x16x32_bf16 v[34:37], v[226:229], v[130:133], v[34:37]
	v_mfma_f32_16x16x32_bf16 v[22:25], v[218:221], v[146:149], v[22:25]
	v_mfma_f32_16x16x32_bf16 v[18:21], v[226:229], v[146:149], v[18:21]
	v_mfma_f32_16x16x32_bf16 v[6:9], v[218:221], v[162:165], v[6:9]
	v_mfma_f32_16x16x32_bf16 v[2:5], v[226:229], v[162:165], v[2:5]
	s_add_i32 s8, 16, 0x18000
	v_add_u32_e32 v0, s8, v215
	s_barrier
	ds_read_b128 v[66:69], v0
	ds_read_b128 v[70:73], v0 offset:1024
	ds_read_b128 v[74:77], v0 offset:2048
	ds_read_b128 v[78:81], v0 offset:3072
	s_add_u32 s6, s6, s12
	s_addc_u32 s7, s7, s13
	s_mov_b32 m0, s34
	v_lshl_add_u64 v[134:135], s[6:7], 0, v[192:193]
	ds_read_b128 v[118:121], v216 offset:32768
	ds_read_b128 v[122:125], v216 offset:33792
	ds_read_b128 v[126:129], v216 offset:34816
	ds_read_b128 v[130:133], v216 offset:35840
	ds_read_b128 v[206:209], v216 offset:36864
	ds_read_b128 v[218:221], v216 offset:37888
	ds_read_b128 v[222:225], v216 offset:38912
	ds_read_b128 v[226:229], v216 offset:39936
	global_load_lds_dwordx4 v[134:135], off
	v_lshl_add_u64 v[134:135], s[6:7], 0, v[188:189]
	s_mov_b32 m0, s35
	s_nop 0
	global_load_lds_dwordx4 v[134:135], off
	s_barrier
	s_waitcnt lgkmcnt(0)
	s_waitcnt lgkmcnt(0)
	v_mfma_f32_16x16x32_bf16 v[134:137], v[66:69], v[118:121], v[174:177]
	v_mfma_f32_16x16x32_bf16 v[174:177], v[70:73], v[122:125], v[134:137]
	v_mfma_f32_16x16x32_bf16 v[134:137], v[74:77], v[118:121], v[170:173]
	v_mfma_f32_16x16x32_bf16 v[170:173], v[78:81], v[122:125], v[134:137]
	v_mfma_f32_16x16x32_bf16 v[134:137], v[66:69], v[126:129], v[158:161]
	v_mfma_f32_16x16x32_bf16 v[158:161], v[70:73], v[130:133], v[134:137]
	v_mfma_f32_16x16x32_bf16 v[134:137], v[74:77], v[126:129], v[154:157]
	v_mfma_f32_16x16x32_bf16 v[154:157], v[78:81], v[130:133], v[134:137]
	v_mfma_f32_16x16x32_bf16 v[134:137], v[66:69], v[206:209], v[142:145]
	v_mfma_f32_16x16x32_bf16 v[142:145], v[70:73], v[218:221], v[134:137]
	v_mfma_f32_16x16x32_bf16 v[134:137], v[74:77], v[206:209], v[138:141]
	v_mfma_f32_16x16x32_bf16 v[110:113], v[66:69], v[222:225], v[110:113]
	v_mfma_f32_16x16x32_bf16 v[106:109], v[74:77], v[222:225], v[106:109]
	v_mfma_f32_16x16x32_bf16 v[138:141], v[78:81], v[218:221], v[134:137]
	v_mfma_f32_16x16x32_bf16 v[110:113], v[70:73], v[226:229], v[110:113]
	v_mfma_f32_16x16x32_bf16 v[106:109], v[78:81], v[226:229], v[106:109]
	s_barrier
	s_add_i32 s6, 16, 0x1c000
	s_add_i32 s7, s8, s29
	v_add_u32_e32 v0, s6, v215
	v_lshl_add_u64 v[134:135], v[246:247], 0, s[70:71]
	s_mov_b32 m0, s7
	ds_read_b128 v[230:233], v0
	ds_read_b128 v[234:237], v0 offset:1024
	ds_read_b128 v[238:241], v0 offset:2048
	ds_read_b128 v[242:245], v0 offset:3072
	global_load_lds_dwordx4 v[134:135], off
	v_lshl_add_u64 v[134:135], v[248:249], 0, s[70:71]
	s_add_i32 m0, s7, 0x2000
	s_nop 0
	global_load_lds_dwordx4 v[134:135], off
	s_barrier
; #define PG8_STAGE(bufoff, gbase, voff) do { _Pragma("unroll") for (int _i = 0; _i < 2; ++_i) \
;     __builtin_amdgcn_global_load_lds((const unsigned*)((const char*)(gbase) + (voff)[_i]), (LAS unsigned*)(lds + (bufoff) + ldsw + _i * 8192), 16, 0, 0); } while (0)
; #define PG8_LDA(dst, b, h) do { _Pragma("unroll") for (int m = 0; m < 4; ++m) _Pragma("unroll") for (int k = 0; k < 2; ++k) dst[m][k] = *(const LAS bf16x8*)(lds + PG8_SA(b, h) + aoff + m * 2048 + k * 1024); } while (0)
; #define PG8_MMA(ai, bj, At, Bt) do { __builtin_amdgcn_s_setprio(1); _Pragma("unroll") for (int m = 0; m < 4; ++m) _Pragma("unroll") for (int n = 0; n < 2; ++n) _Pragma("unroll") for (int k = 0; k < 2; ++k) \
;     acc[ai][bj][m][n] = __builtin_amdgcn_mfma_f32_16x16x32_bf16(Bt[n][k], At[m][k], acc[ai][bj][m][n], 0, 0, 0); __builtin_amdgcn_s_setprio(0); } while (0)
; #define PG8_WAIT_V(n) asm volatile("s_waitcnt vmcnt(" #n ")" ::: "memory")
; #define PG8_WAIT_L(n) asm volatile("s_waitcnt lgkmcnt(" #n ")" ::: "memory")
; #define PG8_BAR __builtin_amdgcn_s_barrier()
; #define PG8_SCHED __builtin_amdgcn_sched_barrier(0)
; template <class Epi, class Sched>
; DI void gemm_phase(LAS unsigned char* lds, const Gemm g, const Sched& S, const Epi& E) {
;     ...
;       PG8_BAR; PG8_WAIT_L(0); PG8_MMA(0, 1, At, B1); PG8_BAR;
;       PG8_LDA(At, 1, 1); PG8_STAGE(PG8_SA(1, 0), a3, voffA);
;       PG8_BAR; PG8_WAIT_L(0); PG8_MMA(1, 0, At, B0); PG8_BAR; PG8_SCHED;
;       PG8_STAGE(PG8_SB(1, 1), b3 + hstepB, voffB);
;       PG8_WAIT_V(6); PG8_BAR; PG8_MMA(1, 1, At, B1); PG8_BAR;
;     }
;     E(acc, cur, wr, wc, fr, fq);
	s_waitcnt lgkmcnt(0)
	s_waitcnt lgkmcnt(0)
	v_mfma_f32_16x16x32_bf16 v[82:85], v[238:241], v[118:121], v[82:85]
	v_mfma_f32_16x16x32_bf16 v[162:165], v[242:245], v[122:125], v[82:85]
	v_mfma_f32_16x16x32_bf16 v[82:85], v[230:233], v[126:129], v[86:89]
	v_mfma_f32_16x16x32_bf16 v[150:153], v[234:237], v[130:133], v[82:85]
	v_mfma_f32_16x16x32_bf16 v[82:85], v[238:241], v[126:129], v[94:97]
	v_mfma_f32_16x16x32_bf16 v[134:137], v[230:233], v[118:121], v[166:169]
	v_mfma_f32_16x16x32_bf16 v[146:149], v[242:245], v[130:133], v[82:85]
	v_mfma_f32_16x16x32_bf16 v[82:85], v[230:233], v[206:209], v[98:101]
	v_mfma_f32_16x16x32_bf16 v[166:169], v[234:237], v[122:125], v[134:137]
	v_mfma_f32_16x16x32_bf16 v[134:137], v[234:237], v[218:221], v[82:85]
	v_mfma_f32_16x16x32_bf16 v[82:85], v[238:241], v[206:209], v[114:117]
	v_mfma_f32_16x16x32_bf16 v[130:133], v[242:245], v[218:221], v[82:85]
	v_mfma_f32_16x16x32_bf16 v[82:85], v[230:233], v[222:225], v[102:105]
	v_mfma_f32_16x16x32_bf16 v[102:105], v[234:237], v[226:229], v[82:85]
	v_mfma_f32_16x16x32_bf16 v[82:85], v[238:241], v[222:225], v[90:93]
	v_mfma_f32_16x16x32_bf16 v[90:93], v[242:245], v[226:229], v[82:85]
	s_mov_b32 m0, s36
	v_lshl_add_u64 v[206:207], v[250:251], 0, s[70:71]
	s_barrier
	s_nop 2
	ds_read_b128 v[82:85], v216 offset:49152
	ds_read_b128 v[86:89], v216 offset:50176
	ds_read_b128 v[94:97], v216 offset:51200
	ds_read_b128 v[98:101], v216 offset:52224
	ds_read_b128 v[114:117], v216 offset:53248
	ds_read_b128 v[118:121], v216 offset:54272
	ds_read_b128 v[122:125], v216 offset:55296
	ds_read_b128 v[126:129], v216 offset:56320
	global_load_lds_dwordx4 v[206:207], off
	v_lshl_add_u64 v[180:181], v[180:181], 0, s[70:71]
	s_mov_b32 m0, s37
	s_nop 0
	global_load_lds_dwordx4 v[180:181], off
	s_barrier
	s_waitcnt lgkmcnt(0)
	s_waitcnt lgkmcnt(0)
	v_mfma_f32_16x16x32_bf16 v[62:65], v[66:69], v[82:85], v[62:65]
	v_mfma_f32_16x16x32_bf16 v[58:61], v[74:77], v[82:85], v[58:61]
	v_mfma_f32_16x16x32_bf16 v[46:49], v[66:69], v[94:97], v[46:49]
	v_mfma_f32_16x16x32_bf16 v[42:45], v[74:77], v[94:97], v[42:45]
	v_mfma_f32_16x16x32_bf16 v[30:33], v[66:69], v[114:117], v[30:33]
	v_mfma_f32_16x16x32_bf16 v[26:29], v[74:77], v[114:117], v[26:29]
	v_mfma_f32_16x16x32_bf16 v[14:17], v[66:69], v[122:125], v[14:17]
	v_mfma_f32_16x16x32_bf16 v[10:13], v[74:77], v[122:125], v[10:13]
	v_mfma_f32_16x16x32_bf16 v[62:65], v[70:73], v[86:89], v[62:65]
	v_mfma_f32_16x16x32_bf16 v[58:61], v[78:81], v[86:89], v[58:61]
	v_mfma_f32_16x16x32_bf16 v[46:49], v[70:73], v[98:101], v[46:49]
	v_mfma_f32_16x16x32_bf16 v[42:45], v[78:81], v[98:101], v[42:45]
	v_mfma_f32_16x16x32_bf16 v[30:33], v[70:73], v[118:121], v[30:33]
	v_mfma_f32_16x16x32_bf16 v[26:29], v[78:81], v[118:121], v[26:29]
	v_mfma_f32_16x16x32_bf16 v[14:17], v[70:73], v[126:129], v[14:17]
	v_mfma_f32_16x16x32_bf16 v[10:13], v[78:81], v[126:129], v[10:13]
	s_barrier
	s_add_i32 s6, s6, s29
	v_lshl_add_u64 v[66:67], v[182:183], 0, s[70:71]
	s_mov_b32 m0, s6
	s_nop 0
	global_load_lds_dwordx4 v[66:67], off
	v_lshl_add_u64 v[66:67], v[184:185], 0, s[70:71]
	s_add_i32 m0, s6, 0x2000
	s_nop 0
	global_load_lds_dwordx4 v[66:67], off
	s_waitcnt vmcnt(6)
	s_barrier
	v_mfma_f32_16x16x32_bf16 v[54:57], v[230:233], v[82:85], v[54:57]
	v_mfma_f32_16x16x32_bf16 v[50:53], v[238:241], v[82:85], v[50:53]
	v_mfma_f32_16x16x32_bf16 v[38:41], v[230:233], v[94:97], v[38:41]
	v_mfma_f32_16x16x32_bf16 v[34:37], v[238:241], v[94:97], v[34:37]
	v_mfma_f32_16x16x32_bf16 v[22:25], v[230:233], v[114:117], v[22:25]
	v_mfma_f32_16x16x32_bf16 v[18:21], v[238:241], v[114:117], v[18:21]
	v_mfma_f32_16x16x32_bf16 v[6:9], v[230:233], v[122:125], v[6:9]
	v_mfma_f32_16x16x32_bf16 v[2:5], v[238:241], v[122:125], v[2:5]
	v_mfma_f32_16x16x32_bf16 v[54:57], v[234:237], v[86:89], v[54:57]
	v_mfma_f32_16x16x32_bf16 v[50:53], v[242:245], v[86:89], v[50:53]
	v_mfma_f32_16x16x32_bf16 v[38:41], v[234:237], v[98:101], v[38:41]
	v_mfma_f32_16x16x32_bf16 v[34:37], v[242:245], v[98:101], v[34:37]
	v_mfma_f32_16x16x32_bf16 v[22:25], v[234:237], v[118:121], v[22:25]
	v_mfma_f32_16x16x32_bf16 v[18:21], v[242:245], v[118:121], v[18:21]
	v_mfma_f32_16x16x32_bf16 v[6:9], v[234:237], v[126:129], v[6:9]
	v_mfma_f32_16x16x32_bf16 v[2:5], v[242:245], v[126:129], v[2:5]
	s_add_u32 s2, s2, 0x100
	s_addc_u32 s3, s3, 0
	s_add_u32 s11, s11, 0x100
	s_addc_u32 s22, s22, 0
	s_cmp_ge_i32 s23, s39
	s_mov_b32 s6, s23
	s_barrier
	s_cbranch_scc0 .LBB0_519
	v_mov_b64_e32 v[244:245], v[178:179]
	v_mov_b64_e32 v[178:179], 0xff
	v_mov_b64_e32 v[246:247], 0x1ff
	v_mov_b32_e32 v195, v217
	v_mov_b32_e32 v248, v210
	v_mov_b32_e32 v210, v201
	v_mov_b32_e32 v184, v200

; #define PG8_STAGE(bufoff, gbase, voff) do { _Pragma("unroll") for (int _i = 0; _i < 2; ++_i) \
;     __builtin_amdgcn_global_load_lds((const unsigned*)((const char*)(gbase) + (voff)[_i]), (LAS unsigned*)(lds + (bufoff) + ldsw + _i * 8192), 16, 0, 0); } while (0)
; #define PG8_LDA(dst, b, h) do { _Pragma("unroll") for (int m = 0; m < 4; ++m) _Pragma("unroll") for (int k = 0; k < 2; ++k) dst[m][k] = *(const LAS bf16x8*)(lds + PG8_SA(b, h) + aoff + m * 2048 + k * 1024); } while (0)
; #define PG8_LDB(dst, b, h) do { _Pragma("unroll") for (int n = 0; n < 2; ++n) _Pragma("unroll") for (int k = 0; k < 2; ++k) dst[n][k] = *(const LAS bf16x8*)(lds + PG8_SB(b, h) + boff + n * 2048 + k * 1024); } while (0)
; #define PG8_MMA(ai, bj, At, Bt) do { __builtin_amdgcn_s_setprio(1); _Pragma("unroll") for (int m = 0; m < 4; ++m) _Pragma("unroll") for (int n = 0; n < 2; ++n) _Pragma("unroll") for (int k = 0; k < 2; ++k) \
;     acc[ai][bj][m][n] = __builtin_amdgcn_mfma_f32_16x16x32_bf16(Bt[n][k], At[m][k], acc[ai][bj][m][n], 0, 0, 0); __builtin_amdgcn_s_setprio(0); } while (0)
; #define PG8_WAIT_L(n) asm volatile("s_waitcnt lgkmcnt(" #n ")" ::: "memory")
; #define PG8_BAR __builtin_amdgcn_s_barrier()
; #define PG8_SCHED __builtin_amdgcn_sched_barrier(0)
; template <class Epi, class Sched>
; DI void gemm_phase(LAS unsigned char* lds, const Gemm g, const Sched& S, const Epi& E) {
;     ...
;       const bool last = (t == nt - 2);
;       const char* a1 = cA + (size_t)(t + 1) * kstep;
;       const char* a2 = last ? nA : cA + (size_t)(t + 2) * kstep; const char* b2 = last ? nB : cB + (size_t)(t + 2) * kstep;
;       const char* a3 = a2 + kstep; const char* b3 = b2 + kstep;
;       PG8_LDB(B0, 0, 0); PG8_SCHED; PG8_LDA(At, 0, 0); PG8_STAGE(PG8_SA(1, 1), a1 + hstep, voffA);
;       PG8_WAIT_L(8); PG8_BAR; PG8_WAIT_L(0); PG8_MMA(0, 0, At, B0); PG8_BAR; PG8_SCHED;
;       PG8_LDB(B1, 0, 1); PG8_STAGE(PG8_SB(0, 0), b2, voffB);
;       PG8_BAR; PG8_WAIT_L(0); PG8_MMA(0, 1, At, B1); PG8_BAR;
;       PG8_LDA(At, 0, 1); PG8_STAGE(PG8_SA(0, 0), a2, voffA);
;       PG8_BAR; PG8_WAIT_L(0); PG8_MMA(1, 0, At, B0); PG8_BAR; PG8_SCHED;
.LBB0_831:
	s_add_i32 s26, s10, 2
	s_add_u32 s11, s8, 0xfe000080
	s_addc_u32 s12, s9, -1
	s_cmp_lg_u32 s25, s10
	s_cselect_b32 s13, s12, 0
	s_cselect_b32 s12, s11, 0
	s_add_u32 s10, s6, s12
	s_addc_u32 s11, s7, s13
	s_add_i32 s27, 16, 0x10000
	v_add_u32_e32 v146, s27, v92
	ds_read_b128 v[94:97], v146
	ds_read_b128 v[152:155], v146 offset:1024
	ds_read_b128 v[156:159], v146 offset:2048
	ds_read_b128 v[160:163], v146 offset:3072
	s_add_u32 s12, s4, s12
	s_addc_u32 s13, s5, s13
	v_lshl_add_u64 v[146:147], v[88:89], 0, s[8:9]
	s_add_i32 m0, s18, 0xc000
	ds_read_b128 v[164:167], v93
	ds_read_b128 v[168:171], v93 offset:1024
	ds_read_b128 v[172:175], v93 offset:2048
	ds_read_b128 v[186:189], v93 offset:3072
	ds_read_b128 v[190:193], v93 offset:4096
	ds_read_b128 v[198:201], v93 offset:5120
	ds_read_b128 v[202:205], v93 offset:6144
	ds_read_b128 v[206:209], v93 offset:7168
	global_load_lds_dwordx4 v[146:147], off
	v_lshl_add_u64 v[146:147], v[90:91], 0, s[8:9]
	s_add_i32 m0, s18, 0xe000
	s_nop 0
	global_load_lds_dwordx4 v[146:147], off
	s_barrier
	s_waitcnt lgkmcnt(0)
	s_waitcnt lgkmcnt(0)
	v_mfma_f32_16x16x32_bf16 v[142:145], v[94:97], v[164:167], v[142:145]
	v_mfma_f32_16x16x32_bf16 v[138:141], v[156:159], v[164:167], v[138:141]
	v_mfma_f32_16x16x32_bf16 v[126:129], v[94:97], v[172:175], v[126:129]
	v_mfma_f32_16x16x32_bf16 v[122:125], v[156:159], v[172:175], v[122:125]
	v_mfma_f32_16x16x32_bf16 v[110:113], v[94:97], v[190:193], v[110:113]
	v_mfma_f32_16x16x32_bf16 v[106:109], v[156:159], v[190:193], v[106:109]
	v_mfma_f32_16x16x32_bf16 v[78:81], v[94:97], v[202:205], v[78:81]
	v_mfma_f32_16x16x32_bf16 v[74:77], v[156:159], v[202:205], v[74:77]
	v_mfma_f32_16x16x32_bf16 v[142:145], v[152:155], v[168:171], v[142:145]
	v_mfma_f32_16x16x32_bf16 v[138:141], v[160:163], v[168:171], v[138:141]
	v_mfma_f32_16x16x32_bf16 v[126:129], v[152:155], v[186:189], v[126:129]
	v_mfma_f32_16x16x32_bf16 v[122:125], v[160:163], v[186:189], v[122:125]
	v_mfma_f32_16x16x32_bf16 v[110:113], v[152:155], v[198:201], v[110:113]
	v_mfma_f32_16x16x32_bf16 v[106:109], v[160:163], v[198:201], v[106:109]
	v_mfma_f32_16x16x32_bf16 v[78:81], v[152:155], v[206:209], v[78:81]
	v_mfma_f32_16x16x32_bf16 v[74:77], v[160:163], v[206:209], v[74:77]
	s_barrier
	s_add_i32 s28, 16, 0x14000
	v_add_u32_e32 v146, s28, v92
	s_add_i32 s27, s27, s17
	ds_read_b128 v[214:217], v146
	ds_read_b128 v[218:221], v146 offset:1024
	ds_read_b128 v[222:225], v146 offset:2048
	ds_read_b128 v[226:229], v146 offset:3072
	v_lshl_add_u64 v[146:147], s[12:13], 0, v[0:1]
	s_mov_b32 m0, s27
	v_lshl_add_u64 v[176:177], s[12:13], 0, v[82:83]
	global_load_lds_dwordx4 v[146:147], off
	s_add_i32 m0, s27, 0x2000
	s_nop 0
	global_load_lds_dwordx4 v[176:177], off
	s_barrier
	s_waitcnt lgkmcnt(0)
	s_waitcnt lgkmcnt(0)
	v_mfma_f32_16x16x32_bf16 v[134:137], v[214:217], v[164:167], v[134:137]
	v_mfma_f32_16x16x32_bf16 v[130:133], v[222:225], v[164:167], v[130:133]
	v_mfma_f32_16x16x32_bf16 v[118:121], v[214:217], v[172:175], v[118:121]
	v_mfma_f32_16x16x32_bf16 v[114:117], v[222:225], v[172:175], v[114:117]
	v_mfma_f32_16x16x32_bf16 v[102:105], v[214:217], v[190:193], v[102:105]
	v_mfma_f32_16x16x32_bf16 v[98:101], v[222:225], v[190:193], v[98:101]
	v_mfma_f32_16x16x32_bf16 v[70:73], v[214:217], v[202:205], v[70:73]
	v_mfma_f32_16x16x32_bf16 v[66:69], v[222:225], v[202:205], v[66:69]
	v_mfma_f32_16x16x32_bf16 v[134:137], v[218:221], v[168:171], v[134:137]
	v_mfma_f32_16x16x32_bf16 v[130:133], v[226:229], v[168:171], v[130:133]
	v_mfma_f32_16x16x32_bf16 v[118:121], v[218:221], v[186:189], v[118:121]
	v_mfma_f32_16x16x32_bf16 v[114:117], v[226:229], v[186:189], v[114:117]
	v_mfma_f32_16x16x32_bf16 v[102:105], v[218:221], v[198:201], v[102:105]
	v_mfma_f32_16x16x32_bf16 v[98:101], v[226:229], v[198:201], v[98:101]
	v_mfma_f32_16x16x32_bf16 v[70:73], v[218:221], v[206:209], v[70:73]
	v_mfma_f32_16x16x32_bf16 v[66:69], v[226:229], v[206:209], v[66:69]
	s_mov_b32 m0, s18
	v_lshl_add_u64 v[230:231], s[10:11], 0, v[86:87]
	s_barrier
	ds_read_b128 v[164:167], v93 offset:16384
	ds_read_b128 v[168:171], v93 offset:17408
	ds_read_b128 v[172:175], v93 offset:18432
	ds_read_b128 v[186:189], v93 offset:19456
	ds_read_b128 v[190:193], v93 offset:20480
	ds_read_b128 v[198:201], v93 offset:21504
	ds_read_b128 v[202:205], v93 offset:22528
	ds_read_b128 v[206:209], v93 offset:23552
	global_load_lds_dwordx4 v[230:231], off
	v_lshl_add_u64 v[232:233], s[10:11], 0, v[84:85]
	s_mov_b32 m0, s19
	s_nop 0
	global_load_lds_dwordx4 v[232:233], off
	s_barrier
	s_waitcnt lgkmcnt(0)
	s_waitcnt lgkmcnt(0)
	v_mfma_f32_16x16x32_bf16 v[62:65], v[94:97], v[164:167], v[62:65]
	v_mfma_f32_16x16x32_bf16 v[58:61], v[156:159], v[164:167], v[58:61]
	v_mfma_f32_16x16x32_bf16 v[46:49], v[94:97], v[172:175], v[46:49]
	v_mfma_f32_16x16x32_bf16 v[42:45], v[156:159], v[172:175], v[42:45]
	v_mfma_f32_16x16x32_bf16 v[30:33], v[94:97], v[190:193], v[30:33]
	v_mfma_f32_16x16x32_bf16 v[26:29], v[156:159], v[190:193], v[26:29]
	v_mfma_f32_16x16x32_bf16 v[14:17], v[94:97], v[202:205], v[14:17]
	v_mfma_f32_16x16x32_bf16 v[10:13], v[156:159], v[202:205], v[10:13]
	v_mfma_f32_16x16x32_bf16 v[62:65], v[152:155], v[168:171], v[62:65]
	v_mfma_f32_16x16x32_bf16 v[58:61], v[160:163], v[168:171], v[58:61]
	v_mfma_f32_16x16x32_bf16 v[46:49], v[152:155], v[186:189], v[46:49]
	v_mfma_f32_16x16x32_bf16 v[42:45], v[160:163], v[186:189], v[42:45]
	v_mfma_f32_16x16x32_bf16 v[30:33], v[152:155], v[198:201], v[30:33]
	v_mfma_f32_16x16x32_bf16 v[26:29], v[160:163], v[198:201], v[26:29]
	v_mfma_f32_16x16x32_bf16 v[14:17], v[152:155], v[206:209], v[14:17]
	v_mfma_f32_16x16x32_bf16 v[10:13], v[160:163], v[206:209], v[10:13]
	s_barrier
; #define PG8_STAGE(bufoff, gbase, voff) do { _Pragma("unroll") for (int _i = 0; _i < 2; ++_i) \
;     __builtin_amdgcn_global_load_lds((const unsigned*)((const char*)(gbase) + (voff)[_i]), (LAS unsigned*)(lds + (bufoff) + ldsw + _i * 8192), 16, 0, 0); } while (0)
; #define PG8_LDA(dst, b, h) do { _Pragma("unroll") for (int m = 0; m < 4; ++m) _Pragma("unroll") for (int k = 0; k < 2; ++k) dst[m][k] = *(const LAS bf16x8*)(lds + PG8_SA(b, h) + aoff + m * 2048 + k * 1024); } while (0)
; #define PG8_LDB(dst, b, h) do { _Pragma("unroll") for (int n = 0; n < 2; ++n) _Pragma("unroll") for (int k = 0; k < 2; ++k) dst[n][k] = *(const LAS bf16x8*)(lds + PG8_SB(b, h) + boff + n * 2048 + k * 1024); } while (0)
; #define PG8_MMA(ai, bj, At, Bt) do { __builtin_amdgcn_s_setprio(1); _Pragma("unroll") for (int m = 0; m < 4; ++m) _Pragma("unroll") for (int n = 0; n < 2; ++n) _Pragma("unroll") for (int k = 0; k < 2; ++k) \
;     acc[ai][bj][m][n] = __builtin_amdgcn_mfma_f32_16x16x32_bf16(Bt[n][k], At[m][k], acc[ai][bj][m][n], 0, 0, 0); __builtin_amdgcn_s_setprio(0); } while (0)
; #define PG8_WAIT_V(n) asm volatile("s_waitcnt vmcnt(" #n ")" ::: "memory")
; #define PG8_WAIT_L(n) asm volatile("s_waitcnt lgkmcnt(" #n ")" ::: "memory")
; #define PG8_BAR __builtin_amdgcn_s_barrier()
; #define PG8_SCHED __builtin_amdgcn_sched_barrier(0)
; template <class Epi, class Sched>
; DI void gemm_phase(LAS unsigned char* lds, const Gemm g, const Sched& S, const Epi& E) {
;     ...
;       PG8_STAGE(PG8_SB(0, 1), b2 + hstepB, voffB);
;       PG8_WAIT_V(6); PG8_BAR; PG8_MMA(1, 1, At, B1); PG8_BAR;
;       PG8_LDB(B0, 1, 0); PG8_SCHED; PG8_LDA(At, 1, 0); PG8_STAGE(PG8_SA(0, 1), a2 + hstep, voffA);
;       PG8_WAIT_L(8); PG8_BAR; PG8_WAIT_L(0); PG8_MMA(0, 0, At, B0); PG8_BAR; PG8_SCHED;
;       PG8_LDB(B1, 1, 1); PG8_STAGE(PG8_SB(1, 0), b3, voffB);
	s_add_u32 s12, s12, s2
	s_addc_u32 s13, s13, s3
	s_add_i32 s27, s28, s17
	v_lshl_add_u64 v[234:235], s[12:13], 0, v[0:1]
	s_mov_b32 m0, s27
	v_lshl_add_u64 v[236:237], s[12:13], 0, v[82:83]
	global_load_lds_dwordx4 v[234:235], off
	s_add_i32 m0, s27, 0x2000
	s_nop 0
	global_load_lds_dwordx4 v[236:237], off
	s_waitcnt vmcnt(6)
	s_barrier
	v_mfma_f32_16x16x32_bf16 v[54:57], v[214:217], v[164:167], v[54:57]
	v_mfma_f32_16x16x32_bf16 v[50:53], v[222:225], v[164:167], v[50:53]
	v_mfma_f32_16x16x32_bf16 v[38:41], v[214:217], v[172:175], v[38:41]
	v_mfma_f32_16x16x32_bf16 v[34:37], v[222:225], v[172:175], v[34:37]
	v_mfma_f32_16x16x32_bf16 v[22:25], v[214:217], v[190:193], v[22:25]
	v_mfma_f32_16x16x32_bf16 v[18:21], v[222:225], v[190:193], v[18:21]
	v_mfma_f32_16x16x32_bf16 v[6:9], v[214:217], v[202:205], v[6:9]
	v_mfma_f32_16x16x32_bf16 v[2:5], v[222:225], v[202:205], v[2:5]
	v_mfma_f32_16x16x32_bf16 v[54:57], v[218:221], v[168:171], v[54:57]
	v_mfma_f32_16x16x32_bf16 v[50:53], v[226:229], v[168:171], v[50:53]
	v_mfma_f32_16x16x32_bf16 v[38:41], v[218:221], v[186:189], v[38:41]
	v_mfma_f32_16x16x32_bf16 v[34:37], v[226:229], v[186:189], v[34:37]
	v_mfma_f32_16x16x32_bf16 v[22:25], v[218:221], v[198:201], v[22:25]
	v_mfma_f32_16x16x32_bf16 v[18:21], v[226:229], v[198:201], v[18:21]
	v_mfma_f32_16x16x32_bf16 v[6:9], v[218:221], v[206:209], v[6:9]
	v_mfma_f32_16x16x32_bf16 v[2:5], v[226:229], v[206:209], v[2:5]
	s_add_i32 s12, 16, 0x18000
	v_add_u32_e32 v149, s12, v92
	s_barrier
	ds_read_b128 v[94:97], v149
	ds_read_b128 v[152:155], v149 offset:1024
	ds_read_b128 v[156:159], v149 offset:2048
	ds_read_b128 v[160:163], v149 offset:3072
	s_add_u32 s10, s10, s0
	s_addc_u32 s11, s11, s1
	s_mov_b32 m0, s20
	v_lshl_add_u64 v[214:215], s[10:11], 0, v[86:87]
	ds_read_b128 v[164:167], v93 offset:32768
	ds_read_b128 v[168:171], v93 offset:33792
	ds_read_b128 v[172:175], v93 offset:34816
	ds_read_b128 v[186:189], v93 offset:35840
	ds_read_b128 v[190:193], v93 offset:36864
	ds_read_b128 v[198:201], v93 offset:37888
	ds_read_b128 v[202:205], v93 offset:38912
	ds_read_b128 v[206:209], v93 offset:39936
	global_load_lds_dwordx4 v[214:215], off
	v_lshl_add_u64 v[214:215], s[10:11], 0, v[84:85]
	s_mov_b32 m0, s21
	s_nop 0
	global_load_lds_dwordx4 v[214:215], off
	s_barrier
	s_waitcnt lgkmcnt(0)
	s_waitcnt lgkmcnt(0)
	v_mfma_f32_16x16x32_bf16 v[142:145], v[94:97], v[164:167], v[142:145]
	v_mfma_f32_16x16x32_bf16 v[138:141], v[156:159], v[164:167], v[138:141]
	v_mfma_f32_16x16x32_bf16 v[126:129], v[94:97], v[172:175], v[126:129]
	v_mfma_f32_16x16x32_bf16 v[122:125], v[156:159], v[172:175], v[122:125]
	v_mfma_f32_16x16x32_bf16 v[110:113], v[94:97], v[190:193], v[110:113]
	v_mfma_f32_16x16x32_bf16 v[106:109], v[156:159], v[190:193], v[106:109]
	v_mfma_f32_16x16x32_bf16 v[78:81], v[94:97], v[202:205], v[78:81]
	v_mfma_f32_16x16x32_bf16 v[74:77], v[156:159], v[202:205], v[74:77]
	v_mfma_f32_16x16x32_bf16 v[142:145], v[152:155], v[168:171], v[142:145]
	v_mfma_f32_16x16x32_bf16 v[138:141], v[160:163], v[168:171], v[138:141]
	v_mfma_f32_16x16x32_bf16 v[126:129], v[152:155], v[186:189], v[126:129]
	v_mfma_f32_16x16x32_bf16 v[122:125], v[160:163], v[186:189], v[122:125]
	v_mfma_f32_16x16x32_bf16 v[110:113], v[152:155], v[198:201], v[110:113]
	v_mfma_f32_16x16x32_bf16 v[106:109], v[160:163], v[198:201], v[106:109]
	v_mfma_f32_16x16x32_bf16 v[78:81], v[152:155], v[206:209], v[78:81]
	v_mfma_f32_16x16x32_bf16 v[74:77], v[160:163], v[206:209], v[74:77]
	s_barrier
	s_add_i32 s10, 16, 0x1c000
	s_add_i32 s11, s12, s17
	v_add_u32_e32 v149, s10, v92
	v_lshl_add_u64 v[146:147], v[146:147], 0, s[70:71]
	s_mov_b32 m0, s11
	ds_read_b128 v[214:217], v149
	ds_read_b128 v[218:221], v149 offset:1024
	ds_read_b128 v[222:225], v149 offset:2048
	ds_read_b128 v[226:229], v149 offset:3072
	global_load_lds_dwordx4 v[146:147], off
	v_lshl_add_u64 v[146:147], v[176:177], 0, s[70:71]
	s_add_i32 m0, s11, 0x2000
	s_nop 0
	global_load_lds_dwordx4 v[146:147], off
	s_barrier
; #define PG8_STAGE(bufoff, gbase, voff) do { _Pragma("unroll") for (int _i = 0; _i < 2; ++_i) \
;     __builtin_amdgcn_global_load_lds((const unsigned*)((const char*)(gbase) + (voff)[_i]), (LAS unsigned*)(lds + (bufoff) + ldsw + _i * 8192), 16, 0, 0); } while (0)
; #define PG8_LDA(dst, b, h) do { _Pragma("unroll") for (int m = 0; m < 4; ++m) _Pragma("unroll") for (int k = 0; k < 2; ++k) dst[m][k] = *(const LAS bf16x8*)(lds + PG8_SA(b, h) + aoff + m * 2048 + k * 1024); } while (0)
; #define PG8_LDB(dst, b, h) do { _Pragma("unroll") for (int n = 0; n < 2; ++n) _Pragma("unroll") for (int k = 0; k < 2; ++k) dst[n][k] = *(const LAS bf16x8*)(lds + PG8_SB(b, h) + boff + n * 2048 + k * 1024); } while (0)
; #define PG8_MMA(ai, bj, At, Bt) do { __builtin_amdgcn_s_setprio(1); _Pragma("unroll") for (int m = 0; m < 4; ++m) _Pragma("unroll") for (int n = 0; n < 2; ++n) _Pragma("unroll") for (int k = 0; k < 2; ++k) \
;     acc[ai][bj][m][n] = __builtin_amdgcn_mfma_f32_16x16x32_bf16(Bt[n][k], At[m][k], acc[ai][bj][m][n], 0, 0, 0); __builtin_amdgcn_s_setprio(0); } while (0)
; #define PG8_WAIT_V(n) asm volatile("s_waitcnt vmcnt(" #n ")" ::: "memory")
; #define PG8_WAIT_L(n) asm volatile("s_waitcnt lgkmcnt(" #n ")" ::: "memory")
; #define PG8_BAR __builtin_amdgcn_s_barrier()
; #define PG8_SCHED __builtin_amdgcn_sched_barrier(0)
; template <class Epi, class Sched>
; DI void gemm_phase(LAS unsigned char* lds, const Gemm g, const Sched& S, const Epi& E) {
;     ...
;       PG8_LDB(B1, 1, 1); PG8_STAGE(PG8_SB(1, 0), b3, voffB);
;       PG8_BAR; PG8_WAIT_L(0); PG8_MMA(0, 1, At, B1); PG8_BAR;
;       PG8_LDA(At, 1, 1); PG8_STAGE(PG8_SA(1, 0), a3, voffA);
;       PG8_BAR; PG8_WAIT_L(0); PG8_MMA(1, 0, At, B0); PG8_BAR; PG8_SCHED;
;       PG8_STAGE(PG8_SB(1, 1), b3 + hstepB, voffB);
;       PG8_WAIT_V(6); PG8_BAR; PG8_MMA(1, 1, At, B1); PG8_BAR;
;     }
	s_waitcnt lgkmcnt(0)
	s_waitcnt lgkmcnt(0)
	v_mfma_f32_16x16x32_bf16 v[134:137], v[214:217], v[164:167], v[134:137]
	v_mfma_f32_16x16x32_bf16 v[130:133], v[222:225], v[164:167], v[130:133]
	v_mfma_f32_16x16x32_bf16 v[118:121], v[214:217], v[172:175], v[118:121]
	v_mfma_f32_16x16x32_bf16 v[114:117], v[222:225], v[172:175], v[114:117]
	v_mfma_f32_16x16x32_bf16 v[102:105], v[214:217], v[190:193], v[102:105]
	v_mfma_f32_16x16x32_bf16 v[98:101], v[222:225], v[190:193], v[98:101]
	v_mfma_f32_16x16x32_bf16 v[70:73], v[214:217], v[202:205], v[70:73]
	v_mfma_f32_16x16x32_bf16 v[66:69], v[222:225], v[202:205], v[66:69]
	v_mfma_f32_16x16x32_bf16 v[134:137], v[218:221], v[168:171], v[134:137]
	v_mfma_f32_16x16x32_bf16 v[130:133], v[226:229], v[168:171], v[130:133]
	v_mfma_f32_16x16x32_bf16 v[118:121], v[218:221], v[186:189], v[118:121]
	v_mfma_f32_16x16x32_bf16 v[114:117], v[226:229], v[186:189], v[114:117]
	v_mfma_f32_16x16x32_bf16 v[102:105], v[218:221], v[198:201], v[102:105]
	v_mfma_f32_16x16x32_bf16 v[98:101], v[226:229], v[198:201], v[98:101]
	v_mfma_f32_16x16x32_bf16 v[70:73], v[218:221], v[206:209], v[70:73]
	v_mfma_f32_16x16x32_bf16 v[66:69], v[226:229], v[206:209], v[66:69]
	s_mov_b32 m0, s22
	v_lshl_add_u64 v[146:147], v[230:231], 0, s[70:71]
	s_barrier
	ds_read_b128 v[164:167], v93 offset:49152
	ds_read_b128 v[168:171], v93 offset:50176
	ds_read_b128 v[172:175], v93 offset:51200
	ds_read_b128 v[186:189], v93 offset:52224
	ds_read_b128 v[190:193], v93 offset:53248
	ds_read_b128 v[198:201], v93 offset:54272
	ds_read_b128 v[202:205], v93 offset:55296
	ds_read_b128 v[206:209], v93 offset:56320
	global_load_lds_dwordx4 v[146:147], off
	v_lshl_add_u64 v[146:147], v[232:233], 0, s[70:71]
	s_mov_b32 m0, s23
	s_nop 0
	global_load_lds_dwordx4 v[146:147], off
	s_barrier
	s_waitcnt lgkmcnt(0)
	s_waitcnt lgkmcnt(0)
	v_mfma_f32_16x16x32_bf16 v[62:65], v[94:97], v[164:167], v[62:65]
	v_mfma_f32_16x16x32_bf16 v[58:61], v[156:159], v[164:167], v[58:61]
	v_mfma_f32_16x16x32_bf16 v[46:49], v[94:97], v[172:175], v[46:49]
	v_mfma_f32_16x16x32_bf16 v[42:45], v[156:159], v[172:175], v[42:45]
	v_mfma_f32_16x16x32_bf16 v[30:33], v[94:97], v[190:193], v[30:33]
	v_mfma_f32_16x16x32_bf16 v[26:29], v[156:159], v[190:193], v[26:29]
	v_mfma_f32_16x16x32_bf16 v[14:17], v[94:97], v[202:205], v[14:17]
	v_mfma_f32_16x16x32_bf16 v[10:13], v[156:159], v[202:205], v[10:13]
	v_mfma_f32_16x16x32_bf16 v[62:65], v[152:155], v[168:171], v[62:65]
	v_mfma_f32_16x16x32_bf16 v[58:61], v[160:163], v[168:171], v[58:61]
	v_mfma_f32_16x16x32_bf16 v[46:49], v[152:155], v[186:189], v[46:49]
	v_mfma_f32_16x16x32_bf16 v[42:45], v[160:163], v[186:189], v[42:45]
	v_mfma_f32_16x16x32_bf16 v[30:33], v[152:155], v[198:201], v[30:33]
	v_mfma_f32_16x16x32_bf16 v[26:29], v[160:163], v[198:201], v[26:29]
	v_mfma_f32_16x16x32_bf16 v[14:17], v[152:155], v[206:209], v[14:17]
	v_mfma_f32_16x16x32_bf16 v[10:13], v[160:163], v[206:209], v[10:13]
	s_barrier
	s_add_i32 s10, s10, s17
	v_lshl_add_u64 v[94:95], v[234:235], 0, s[70:71]
	s_mov_b32 m0, s10
	s_nop 0
	global_load_lds_dwordx4 v[94:95], off
	v_lshl_add_u64 v[94:95], v[236:237], 0, s[70:71]
	s_add_i32 m0, s10, 0x2000
	s_nop 0
	global_load_lds_dwordx4 v[94:95], off
	s_waitcnt vmcnt(6)
	s_barrier
	v_mfma_f32_16x16x32_bf16 v[54:57], v[214:217], v[164:167], v[54:57]
	v_mfma_f32_16x16x32_bf16 v[50:53], v[222:225], v[164:167], v[50:53]
	v_mfma_f32_16x16x32_bf16 v[38:41], v[214:217], v[172:175], v[38:41]
	v_mfma_f32_16x16x32_bf16 v[34:37], v[222:225], v[172:175], v[34:37]
	v_mfma_f32_16x16x32_bf16 v[22:25], v[214:217], v[190:193], v[22:25]
	v_mfma_f32_16x16x32_bf16 v[18:21], v[222:225], v[190:193], v[18:21]
	v_mfma_f32_16x16x32_bf16 v[6:9], v[214:217], v[202:205], v[6:9]
	v_mfma_f32_16x16x32_bf16 v[2:5], v[222:225], v[202:205], v[2:5]
	v_mfma_f32_16x16x32_bf16 v[54:57], v[218:221], v[168:171], v[54:57]
	v_mfma_f32_16x16x32_bf16 v[50:53], v[226:229], v[168:171], v[50:53]
	v_mfma_f32_16x16x32_bf16 v[38:41], v[218:221], v[186:189], v[38:41]
	v_mfma_f32_16x16x32_bf16 v[34:37], v[226:229], v[186:189], v[34:37]
	v_mfma_f32_16x16x32_bf16 v[22:25], v[218:221], v[198:201], v[22:25]
	v_mfma_f32_16x16x32_bf16 v[18:21], v[226:229], v[198:201], v[18:21]
	v_mfma_f32_16x16x32_bf16 v[6:9], v[218:221], v[206:209], v[6:9]
	v_mfma_f32_16x16x32_bf16 v[2:5], v[226:229], v[206:209], v[2:5]
	s_add_u32 s8, s8, 0x100
	s_addc_u32 s9, s9, 0
	s_cmp_ge_i32 s26, s24
	s_mov_b32 s10, s26
	s_barrier
	s_cbranch_scc0 .LBB0_831
